# epilogue loads batched: P1 rs1 x8 in one wait, P4 gate loads 4x8, P5/P7 xb loads 2x8, P6 rowss one-row-ahead prefetch
# speedup vs baseline: 1.0136x; 1.0136x over previous
; #define GAS __attribute__((address_space(1)))
; __device__ __forceinline__ unsigned cvt_pk_bf16(float lo, float hi) { f32x2 v = {lo, hi}; bf16x2_t b = __builtin_convertvector(v, bf16x2_t); return __builtin_bit_cast(unsigned, b); }
; __device__ __forceinline__ float sigmoid_f(float x) { return __builtin_amdgcn_rcpf(1.0f + __builtin_amdgcn_exp2f(-x * LOG2E)); }
;     __device__ __forceinline__ void operator()(const f32x4 (&acc)[2][2][4][2], const Unit& u, int wr, int wc, int fr, int fq) const {
;     ...
;         const int c = u.pn - 18, br = c >> 2; GAS bf16_t* G = (br < 2) ? g01 + (size_t)br * MROWS * 1024 : g2;
;         const int row0 = u.pm * BM + wr * 64 + fr; const int col0 = (c & 3) * BM + wc * 32 + 8 * fq;
;         f32x4 bv[2][2];
; #pragma unroll
;         for (int bj = 0; bj < 2; ++bj)
; #pragma unroll
;             for (int n = 0; n < 2; ++n) bv[bj][n] = *(const GAS f32x4*)(bias + br * 1024 + col0 + bj * HALF + 4 * n);
; #pragma unroll
;         for (int ai = 0; ai < 2; ++ai)
; #pragma unroll
;             for (int m = 0; m < 4; ++m) { const int row = row0 + ai * HALF + m * 16; const float rs = q.rs1[row]; GAS bf16_t* rowp = G + (size_t)row * 1024 + col0;
; #pragma unroll
;                 for (int bj = 0; bj < 2; ++bj) { const f32x4 v0 = acc[ai][bj][m][0] * rs + bv[bj][0], v1 = acc[ai][bj][m][1] * rs + bv[bj][1];
;                     u32x4 w; w.x = cvt_pk_bf16(fmaxf(sigmoid_f(v0[0]), 1e-30f), fmaxf(sigmoid_f(v0[1]), 1e-30f)); w.y = cvt_pk_bf16(fmaxf(sigmoid_f(v0[2]), 1e-30f), fmaxf(sigmoid_f(v0[3]), 1e-30f));
;                     w.z = cvt_pk_bf16(fmaxf(sigmoid_f(v1[0]), 1e-30f), fmaxf(sigmoid_f(v1[1]), 1e-30f)); w.w = cvt_pk_bf16(fmaxf(sigmoid_f(v1[2]), 1e-30f), fmaxf(sigmoid_f(v1[3]), 1e-30f));
;                     *(GAS u32x4*)(rowp + bj * HALF) = w; } }
.LBB0_171:
	s_sub_i32 s11, s10, 18
	s_lshr_b32 s13, s11, 2
	s_lshl_b32 s15, s11, 8
	s_lshl_b32 s72, s13, 10
	s_and_b32 s15, s15, 0x300
	s_lshl_b64 s[20:21], s[72:73], 2
	s_add_u32 s20, s48, s20
	s_addc_u32 s21, s49, s21
	s_lshl_b32 s13, s13, 26
	s_add_u32 s13, s31, s13
	v_or_b32_e32 v0, s15, v203
	s_addc_u32 s15, s30, 0
	v_lshlrev_b32_e32 v134, 2, v0
	s_cmp_lt_u32 s11, 8
	v_ashrrev_i32_e32 v163, 31, v162
	global_load_dwordx4 v[138:141], v134, s[20:21] offset:16
	global_load_dwordx4 v[142:145], v134, s[20:21]
	global_load_dwordx4 v[130:133], v134, s[20:21] offset:528
	s_nop 0
	global_load_dwordx4 v[134:137], v134, s[20:21] offset:512
	s_cselect_b32 s21, s15, s47
	s_cselect_b32 s20, s13, s46
	v_lshlrev_b32_e32 v0, 1, v0
	v_lshl_add_u64 v[192:193], v[162:163], 2, s[2:3]
	v_lshl_add_u64 v[194:195], s[20:21], 0, v[0:1]
	global_load_dword v206, v[192:193], off
	global_load_dword v207, v[192:193], off offset:64
	global_load_dword v208, v[192:193], off offset:128
	global_load_dword v209, v[192:193], off offset:192
	global_load_dword v210, v[192:193], off offset:512
	global_load_dword v211, v[192:193], off offset:576
	global_load_dword v212, v[192:193], off offset:640
	global_load_dword v213, v[192:193], off offset:704
	v_lshlrev_b64 v[146:147], 11, v[162:163]
	v_lshl_add_u64 v[164:165], v[194:195], 0, v[146:147]
	s_mov_b32 s11, 0x40000
	s_mov_b64 s[20:21], 0x40000
	s_waitcnt vmcnt(0)
	s_nop 1
	v_mov_b32_e32 v0, v206
	v_pk_fma_f32 v[146:147], v[126:127], v[0:1], v[142:143] op_sel_hi:[1,0,1]
	s_nop 0
	v_mul_f32_e32 v146, 0xbfb8aa3b, v146
	v_mul_f32_e32 v147, 0xbfb8aa3b, v147
	v_exp_f32_e32 v146, v146
	v_exp_f32_e32 v147, v147
	v_pk_fma_f32 v[148:149], v[128:129], v[0:1], v[144:145] op_sel_hi:[1,0,1]
	v_pk_fma_f32 v[198:199], v[122:123], v[0:1], v[138:139] op_sel_hi:[1,0,1]
	v_add_f32_e32 v146, 1.0, v146
	v_add_f32_e32 v147, 1.0, v147
	v_rcp_f32_e32 v146, v146
	v_rcp_f32_e32 v147, v147
	v_pk_fma_f32 v[196:197], v[124:125], v[0:1], v[140:141] op_sel_hi:[1,0,1]
	v_max_f32_e32 v146, 0xda24260, v146
	v_max_f32_e32 v147, 0xda24260, v147
	v_cvt_pk_bf16_f32 v146, v146, v147
	v_mul_f32_e32 v147, 0xbfb8aa3b, v148
	v_mul_f32_e32 v148, 0xbfb8aa3b, v149
	v_exp_f32_e32 v147, v147
	v_exp_f32_e32 v148, v148
	v_mul_f32_e32 v149, 0xbfb8aa3b, v199
	v_exp_f32_e32 v149, v149
	v_add_f32_e32 v147, 1.0, v147
	v_add_f32_e32 v148, 1.0, v148
	v_rcp_f32_e32 v147, v147
	v_rcp_f32_e32 v148, v148
	v_add_f32_e32 v149, 1.0, v149
	v_rcp_f32_e32 v149, v149
	v_max_f32_e32 v147, 0xda24260, v147
	v_max_f32_e32 v148, 0xda24260, v148
	v_cvt_pk_bf16_f32 v147, v147, v148
	v_mul_f32_e32 v148, 0xbfb8aa3b, v198
	v_exp_f32_e32 v148, v148
	v_max_f32_e32 v149, 0xda24260, v149
	v_mul_f32_e32 v163, 0xbfb8aa3b, v197
	v_exp_f32_e32 v163, v163
	v_add_f32_e32 v148, 1.0, v148
	v_rcp_f32_e32 v148, v148
	v_pk_fma_f32 v[198:199], v[120:121], v[0:1], v[136:137] op_sel_hi:[1,0,1]
	v_add_f32_e32 v163, 1.0, v163
	v_rcp_f32_e32 v163, v163
	v_max_f32_e32 v148, 0xda24260, v148
	v_cvt_pk_bf16_f32 v148, v148, v149
	v_mul_f32_e32 v149, 0xbfb8aa3b, v196
	v_exp_f32_e32 v149, v149
	v_max_f32_e32 v163, 0xda24260, v163
	v_pk_fma_f32 v[196:197], v[116:117], v[0:1], v[132:133] op_sel_hi:[1,0,1]
	v_add_f32_e32 v149, 1.0, v149
	v_rcp_f32_e32 v149, v149
	s_nop 0
	v_max_f32_e32 v149, 0xda24260, v149
	v_cvt_pk_bf16_f32 v149, v149, v163
	global_store_dwordx4 v[164:165], v[146:149], off
	s_nop 1
	v_pk_fma_f32 v[146:147], v[118:119], v[0:1], v[134:135] op_sel_hi:[1,0,1]
	v_pk_fma_f32 v[148:149], v[114:115], v[0:1], v[130:131] op_sel_hi:[1,0,1]
	v_mul_f32_e32 v0, 0xbfb8aa3b, v146
	v_mul_f32_e32 v146, 0xbfb8aa3b, v147
	v_exp_f32_e32 v0, v0
	v_exp_f32_e32 v146, v146
	v_mul_f32_e32 v147, 0xbfb8aa3b, v199
	v_exp_f32_e32 v147, v147
	v_add_f32_e32 v0, 1.0, v0
	v_add_f32_e32 v146, 1.0, v146
	v_rcp_f32_e32 v0, v0
	v_rcp_f32_e32 v146, v146
	v_add_f32_e32 v147, 1.0, v147
	v_rcp_f32_e32 v147, v147
	v_max_f32_e32 v0, 0xda24260, v0
	v_max_f32_e32 v146, 0xda24260, v146
	v_cvt_pk_bf16_f32 v146, v0, v146
	v_mul_f32_e32 v0, 0xbfb8aa3b, v198
	v_exp_f32_e32 v0, v0
	v_max_f32_e32 v147, 0xda24260, v147
	v_add_f32_e32 v0, 1.0, v0
	v_rcp_f32_e32 v0, v0
	s_nop 0
	v_max_f32_e32 v0, 0xda24260, v0
	v_cvt_pk_bf16_f32 v147, v0, v147
	v_mul_f32_e32 v0, 0xbfb8aa3b, v148
	v_mul_f32_e32 v148, 0xbfb8aa3b, v149
	v_exp_f32_e32 v0, v0
	v_exp_f32_e32 v148, v148
	v_mul_f32_e32 v149, 0xbfb8aa3b, v197
	v_exp_f32_e32 v149, v149
	v_add_f32_e32 v0, 1.0, v0
	v_add_f32_e32 v148, 1.0, v148
	v_rcp_f32_e32 v0, v0
	v_rcp_f32_e32 v148, v148
	v_add_f32_e32 v149, 1.0, v149
	v_rcp_f32_e32 v149, v149
	v_max_f32_e32 v0, 0xda24260, v0
	v_max_f32_e32 v148, 0xda24260, v148
	v_cvt_pk_bf16_f32 v148, v0, v148
	v_mul_f32_e32 v0, 0xbfb8aa3b, v196
	v_exp_f32_e32 v0, v0
	v_max_f32_e32 v149, 0xda24260, v149
	v_add_f32_e32 v0, 1.0, v0
	v_rcp_f32_e32 v0, v0
	s_nop 0
	v_max_f32_e32 v0, 0xda24260, v0
	v_cvt_pk_bf16_f32 v149, v0, v149
	global_store_dwordx4 v[164:165], v[146:149], off offset:256
	s_nop 1
	v_or_b32_e32 v146, 16, v162
	v_ashrrev_i32_e32 v147, 31, v146
	v_lshl_add_u64 v[148:149], v[146:147], 2, s[2:3]
	v_lshlrev_b64 v[146:147], 11, v[146:147]
	v_lshl_add_u64 v[196:197], v[194:195], 0, v[146:147]
	s_nop 1
	v_mov_b32_e32 v0, v207
	v_pk_fma_f32 v[146:147], v[110:111], v[0:1], v[142:143] op_sel_hi:[1,0,1]
	s_nop 0
	v_mul_f32_e32 v146, 0xbfb8aa3b, v146
	v_mul_f32_e32 v147, 0xbfb8aa3b, v147
	v_exp_f32_e32 v146, v146
	v_exp_f32_e32 v147, v147
	v_pk_fma_f32 v[148:149], v[112:113], v[0:1], v[144:145] op_sel_hi:[1,0,1]
	v_pk_fma_f32 v[200:201], v[106:107], v[0:1], v[138:139] op_sel_hi:[1,0,1]
	v_add_f32_e32 v146, 1.0, v146
	v_add_f32_e32 v147, 1.0, v147
	v_rcp_f32_e32 v146, v146
	v_rcp_f32_e32 v147, v147
; #define GAS __attribute__((address_space(1)))
; __device__ __forceinline__ unsigned cvt_pk_bf16(float lo, float hi) { f32x2 v = {lo, hi}; bf16x2_t b = __builtin_convertvector(v, bf16x2_t); return __builtin_bit_cast(unsigned, b); }
; __device__ __forceinline__ float sigmoid_f(float x) { return __builtin_amdgcn_rcpf(1.0f + __builtin_amdgcn_exp2f(-x * LOG2E)); }
;     __device__ __forceinline__ void operator()(const f32x4 (&acc)[2][2][4][2], const Unit& u, int wr, int wc, int fr, int fq) const {
;     ...
;             for (int m = 0; m < 4; ++m) { const int row = row0 + ai * HALF + m * 16; const float rs = q.rs1[row]; GAS bf16_t* rowp = G + (size_t)row * 1024 + col0;
; #pragma unroll
;                 for (int bj = 0; bj < 2; ++bj) { const f32x4 v0 = acc[ai][bj][m][0] * rs + bv[bj][0], v1 = acc[ai][bj][m][1] * rs + bv[bj][1];
;                     u32x4 w; w.x = cvt_pk_bf16(fmaxf(sigmoid_f(v0[0]), 1e-30f), fmaxf(sigmoid_f(v0[1]), 1e-30f)); w.y = cvt_pk_bf16(fmaxf(sigmoid_f(v0[2]), 1e-30f), fmaxf(sigmoid_f(v0[3]), 1e-30f));
;                     w.z = cvt_pk_bf16(fmaxf(sigmoid_f(v1[0]), 1e-30f), fmaxf(sigmoid_f(v1[1]), 1e-30f)); w.w = cvt_pk_bf16(fmaxf(sigmoid_f(v1[2]), 1e-30f), fmaxf(sigmoid_f(v1[3]), 1e-30f));
;                     *(GAS u32x4*)(rowp + bj * HALF) = w; } }
	v_pk_fma_f32 v[198:199], v[108:109], v[0:1], v[140:141] op_sel_hi:[1,0,1]
	v_max_f32_e32 v146, 0xda24260, v146
	v_max_f32_e32 v147, 0xda24260, v147
	v_cvt_pk_bf16_f32 v146, v146, v147
	v_mul_f32_e32 v147, 0xbfb8aa3b, v148
	v_mul_f32_e32 v148, 0xbfb8aa3b, v149
	v_exp_f32_e32 v147, v147
	v_exp_f32_e32 v148, v148
	v_mul_f32_e32 v149, 0xbfb8aa3b, v201
	v_exp_f32_e32 v149, v149
	v_add_f32_e32 v147, 1.0, v147
	v_add_f32_e32 v148, 1.0, v148
	v_rcp_f32_e32 v147, v147
	v_rcp_f32_e32 v148, v148
	v_add_f32_e32 v149, 1.0, v149
	v_rcp_f32_e32 v149, v149
	v_max_f32_e32 v147, 0xda24260, v147
	v_max_f32_e32 v148, 0xda24260, v148
	v_cvt_pk_bf16_f32 v147, v147, v148
	v_mul_f32_e32 v148, 0xbfb8aa3b, v200
	v_exp_f32_e32 v148, v148
	v_max_f32_e32 v149, 0xda24260, v149
	v_mul_f32_e32 v163, 0xbfb8aa3b, v199
	v_exp_f32_e32 v163, v163
	v_add_f32_e32 v148, 1.0, v148
	v_rcp_f32_e32 v148, v148
	v_pk_fma_f32 v[200:201], v[104:105], v[0:1], v[136:137] op_sel_hi:[1,0,1]
	v_add_f32_e32 v163, 1.0, v163
	v_rcp_f32_e32 v163, v163
	v_max_f32_e32 v148, 0xda24260, v148
	v_cvt_pk_bf16_f32 v148, v148, v149
	v_mul_f32_e32 v149, 0xbfb8aa3b, v198
	v_exp_f32_e32 v149, v149
	v_max_f32_e32 v163, 0xda24260, v163
	v_pk_fma_f32 v[198:199], v[100:101], v[0:1], v[132:133] op_sel_hi:[1,0,1]
	v_add_f32_e32 v149, 1.0, v149
	v_rcp_f32_e32 v149, v149
	s_nop 0
	v_max_f32_e32 v149, 0xda24260, v149
	v_cvt_pk_bf16_f32 v149, v149, v163
	global_store_dwordx4 v[196:197], v[146:149], off
	s_nop 1
	v_pk_fma_f32 v[146:147], v[102:103], v[0:1], v[134:135] op_sel_hi:[1,0,1]
	v_pk_fma_f32 v[148:149], v[98:99], v[0:1], v[130:131] op_sel_hi:[1,0,1]
	v_mul_f32_e32 v0, 0xbfb8aa3b, v146
	v_mul_f32_e32 v146, 0xbfb8aa3b, v147
	v_exp_f32_e32 v0, v0
	v_exp_f32_e32 v146, v146
	v_mul_f32_e32 v147, 0xbfb8aa3b, v201
	v_exp_f32_e32 v147, v147
	v_add_f32_e32 v0, 1.0, v0
	v_add_f32_e32 v146, 1.0, v146
	v_rcp_f32_e32 v0, v0
	v_rcp_f32_e32 v146, v146
	v_add_f32_e32 v147, 1.0, v147
	v_rcp_f32_e32 v147, v147
	v_max_f32_e32 v0, 0xda24260, v0
	v_max_f32_e32 v146, 0xda24260, v146
	v_cvt_pk_bf16_f32 v146, v0, v146
	v_mul_f32_e32 v0, 0xbfb8aa3b, v200
	v_exp_f32_e32 v0, v0
	v_max_f32_e32 v147, 0xda24260, v147
	v_add_f32_e32 v0, 1.0, v0
	v_rcp_f32_e32 v0, v0
	s_nop 0
	v_max_f32_e32 v0, 0xda24260, v0
	v_cvt_pk_bf16_f32 v147, v0, v147
	v_mul_f32_e32 v0, 0xbfb8aa3b, v148
	v_mul_f32_e32 v148, 0xbfb8aa3b, v149
	v_exp_f32_e32 v0, v0
	v_exp_f32_e32 v148, v148
	v_mul_f32_e32 v149, 0xbfb8aa3b, v199
	v_exp_f32_e32 v149, v149
	v_add_f32_e32 v0, 1.0, v0
	v_add_f32_e32 v148, 1.0, v148
	v_rcp_f32_e32 v0, v0
	v_rcp_f32_e32 v148, v148
	v_add_f32_e32 v149, 1.0, v149
	v_rcp_f32_e32 v149, v149
	v_max_f32_e32 v0, 0xda24260, v0
	v_max_f32_e32 v148, 0xda24260, v148
	v_cvt_pk_bf16_f32 v148, v0, v148
	v_mul_f32_e32 v0, 0xbfb8aa3b, v198
	v_exp_f32_e32 v0, v0
	v_max_f32_e32 v149, 0xda24260, v149
	v_add_f32_e32 v0, 1.0, v0
	v_rcp_f32_e32 v0, v0
	s_nop 0
	v_max_f32_e32 v0, 0xda24260, v0
	v_cvt_pk_bf16_f32 v149, v0, v149
	global_store_dwordx4 v[196:197], v[146:149], off offset:256
	s_nop 1
	v_or_b32_e32 v146, 32, v162
	v_ashrrev_i32_e32 v147, 31, v146
	v_lshl_add_u64 v[148:149], v[146:147], 2, s[2:3]
	v_lshlrev_b64 v[146:147], 11, v[146:147]
	v_lshl_add_u64 v[146:147], v[194:195], 0, v[146:147]
	s_nop 1
	v_mov_b32_e32 v0, v208
	v_pk_fma_f32 v[148:149], v[96:97], v[0:1], v[144:145] op_sel_hi:[1,0,1]
	s_nop 0
	v_mul_f32_e32 v148, 0xbfb8aa3b, v148
	v_mul_f32_e32 v149, 0xbfb8aa3b, v149
	v_exp_f32_e32 v148, v148
	v_exp_f32_e32 v149, v149
	v_pk_fma_f32 v[196:197], v[94:95], v[0:1], v[142:143] op_sel_hi:[1,0,1]
	v_pk_fma_f32 v[198:199], v[90:91], v[0:1], v[138:139] op_sel_hi:[1,0,1]
	v_add_f32_e32 v148, 1.0, v148
	v_add_f32_e32 v149, 1.0, v149
	v_rcp_f32_e32 v148, v148
	v_rcp_f32_e32 v149, v149
	v_mul_f32_e32 v163, 0xbfb8aa3b, v196
	v_mul_f32_e32 v196, 0xbfb8aa3b, v197
	v_max_f32_e32 v148, 0xda24260, v148
	v_max_f32_e32 v149, 0xda24260, v149
	v_cvt_pk_bf16_f32 v197, v148, v149
	v_mul_f32_e32 v148, 0xbfb8aa3b, v198
	v_mul_f32_e32 v149, 0xbfb8aa3b, v199
	v_exp_f32_e32 v148, v148
	v_exp_f32_e32 v149, v149
	v_pk_fma_f32 v[200:201], v[92:93], v[0:1], v[140:141] op_sel_hi:[1,0,1]
	v_exp_f32_e32 v163, v163
	v_add_f32_e32 v148, 1.0, v148
	v_add_f32_e32 v149, 1.0, v149
	v_rcp_f32_e32 v148, v148
	v_rcp_f32_e32 v149, v149
	v_exp_f32_e32 v196, v196
	v_add_f32_e32 v163, 1.0, v163
	v_max_f32_e32 v148, 0xda24260, v148
	v_max_f32_e32 v149, 0xda24260, v149
	v_cvt_pk_bf16_f32 v198, v148, v149
	v_mul_f32_e32 v148, 0xbfb8aa3b, v200
	v_mul_f32_e32 v149, 0xbfb8aa3b, v201
	v_exp_f32_e32 v148, v148
	v_exp_f32_e32 v149, v149
	v_add_f32_e32 v196, 1.0, v196
	v_rcp_f32_e32 v163, v163
	v_add_f32_e32 v148, 1.0, v148
	v_add_f32_e32 v149, 1.0, v149
	v_rcp_f32_e32 v196, v196
	v_rcp_f32_e32 v148, v148
	v_rcp_f32_e32 v149, v149
	v_max_f32_e32 v163, 0xda24260, v163
	v_max_f32_e32 v196, 0xda24260, v196
	v_max_f32_e32 v148, 0xda24260, v148
	v_max_f32_e32 v149, 0xda24260, v149
	v_cvt_pk_bf16_f32 v196, v163, v196
	v_cvt_pk_bf16_f32 v199, v148, v149
	global_store_dwordx4 v[146:147], v[196:199], off
	v_pk_fma_f32 v[200:201], v[88:89], v[0:1], v[136:137] op_sel_hi:[1,0,1]
	v_pk_fma_f32 v[148:149], v[84:85], v[0:1], v[132:133] op_sel_hi:[1,0,1]
	v_pk_fma_f32 v[198:199], v[86:87], v[0:1], v[134:135] op_sel_hi:[1,0,1]
	v_pk_fma_f32 v[196:197], v[82:83], v[0:1], v[130:131] op_sel_hi:[1,0,1]
	v_mul_f32_e32 v0, 0xbfb8aa3b, v198
	v_mul_f32_e32 v163, 0xbfb8aa3b, v199
	v_exp_f32_e32 v0, v0
	v_exp_f32_e32 v163, v163
	v_add_f32_e32 v0, 1.0, v0
	v_add_f32_e32 v163, 1.0, v163
	v_rcp_f32_e32 v0, v0
	v_rcp_f32_e32 v163, v163
	v_max_f32_e32 v0, 0xda24260, v0
	v_max_f32_e32 v163, 0xda24260, v163
	v_cvt_pk_bf16_f32 v198, v0, v163
; #define GAS __attribute__((address_space(1)))
; __device__ __forceinline__ unsigned cvt_pk_bf16(float lo, float hi) { f32x2 v = {lo, hi}; bf16x2_t b = __builtin_convertvector(v, bf16x2_t); return __builtin_bit_cast(unsigned, b); }
; __device__ __forceinline__ float sigmoid_f(float x) { return __builtin_amdgcn_rcpf(1.0f + __builtin_amdgcn_exp2f(-x * LOG2E)); }
;     __device__ __forceinline__ void operator()(const f32x4 (&acc)[2][2][4][2], const Unit& u, int wr, int wc, int fr, int fq) const {
;     ...
;             for (int m = 0; m < 4; ++m) { const int row = row0 + ai * HALF + m * 16; const float rs = q.rs1[row]; GAS bf16_t* rowp = G + (size_t)row * 1024 + col0;
; #pragma unroll
;                 for (int bj = 0; bj < 2; ++bj) { const f32x4 v0 = acc[ai][bj][m][0] * rs + bv[bj][0], v1 = acc[ai][bj][m][1] * rs + bv[bj][1];
;                     u32x4 w; w.x = cvt_pk_bf16(fmaxf(sigmoid_f(v0[0]), 1e-30f), fmaxf(sigmoid_f(v0[1]), 1e-30f)); w.y = cvt_pk_bf16(fmaxf(sigmoid_f(v0[2]), 1e-30f), fmaxf(sigmoid_f(v0[3]), 1e-30f));
;                     w.z = cvt_pk_bf16(fmaxf(sigmoid_f(v1[0]), 1e-30f), fmaxf(sigmoid_f(v1[1]), 1e-30f)); w.w = cvt_pk_bf16(fmaxf(sigmoid_f(v1[2]), 1e-30f), fmaxf(sigmoid_f(v1[3]), 1e-30f));
;                     *(GAS u32x4*)(rowp + bj * HALF) = w; } }
	v_mul_f32_e32 v0, 0xbfb8aa3b, v200
	v_mul_f32_e32 v163, 0xbfb8aa3b, v201
	v_exp_f32_e32 v0, v0
	v_exp_f32_e32 v163, v163
	v_add_f32_e32 v0, 1.0, v0
	v_add_f32_e32 v163, 1.0, v163
	v_rcp_f32_e32 v0, v0
	v_rcp_f32_e32 v163, v163
	v_max_f32_e32 v0, 0xda24260, v0
	v_max_f32_e32 v163, 0xda24260, v163
	v_cvt_pk_bf16_f32 v199, v0, v163
	v_mul_f32_e32 v0, 0xbfb8aa3b, v196
	v_mul_f32_e32 v163, 0xbfb8aa3b, v197
	v_exp_f32_e32 v0, v0
	v_exp_f32_e32 v163, v163
	v_add_f32_e32 v0, 1.0, v0
	v_add_f32_e32 v163, 1.0, v163
	v_rcp_f32_e32 v0, v0
	v_rcp_f32_e32 v163, v163
	v_max_f32_e32 v0, 0xda24260, v0
	v_max_f32_e32 v163, 0xda24260, v163
	v_cvt_pk_bf16_f32 v200, v0, v163
	v_mul_f32_e32 v0, 0xbfb8aa3b, v148
	v_mul_f32_e32 v148, 0xbfb8aa3b, v149
	v_exp_f32_e32 v0, v0
	v_exp_f32_e32 v148, v148
	v_add_f32_e32 v0, 1.0, v0
	v_add_f32_e32 v148, 1.0, v148
	v_rcp_f32_e32 v0, v0
	v_rcp_f32_e32 v148, v148
	v_max_f32_e32 v0, 0xda24260, v0
	v_max_f32_e32 v148, 0xda24260, v148
	v_cvt_pk_bf16_f32 v201, v0, v148
	global_store_dwordx4 v[146:147], v[198:201], off offset:256
	v_or_b32_e32 v146, 48, v162
	v_ashrrev_i32_e32 v147, 31, v146
	v_lshl_add_u64 v[148:149], v[146:147], 2, s[2:3]
	v_lshlrev_b64 v[146:147], 11, v[146:147]
	v_lshl_add_u64 v[194:195], v[194:195], 0, v[146:147]
	s_nop 1
	v_mov_b32_e32 v0, v209
	v_pk_fma_f32 v[146:147], v[78:79], v[0:1], v[142:143] op_sel_hi:[1,0,1]
	s_nop 0
	v_mul_f32_e32 v146, 0xbfb8aa3b, v146
	v_mul_f32_e32 v147, 0xbfb8aa3b, v147
	v_exp_f32_e32 v146, v146
	v_exp_f32_e32 v147, v147
	v_pk_fma_f32 v[148:149], v[80:81], v[0:1], v[144:145] op_sel_hi:[1,0,1]
	v_pk_fma_f32 v[198:199], v[74:75], v[0:1], v[138:139] op_sel_hi:[1,0,1]
	v_add_f32_e32 v146, 1.0, v146
	v_add_f32_e32 v147, 1.0, v147
	v_rcp_f32_e32 v146, v146
	v_rcp_f32_e32 v147, v147
	v_pk_fma_f32 v[196:197], v[76:77], v[0:1], v[140:141] op_sel_hi:[1,0,1]
	v_max_f32_e32 v146, 0xda24260, v146
	v_max_f32_e32 v147, 0xda24260, v147
	v_cvt_pk_bf16_f32 v146, v146, v147
	v_mul_f32_e32 v147, 0xbfb8aa3b, v148
	v_mul_f32_e32 v148, 0xbfb8aa3b, v149
	v_exp_f32_e32 v147, v147
	v_exp_f32_e32 v148, v148
	v_mul_f32_e32 v149, 0xbfb8aa3b, v199
	v_exp_f32_e32 v149, v149
	v_add_f32_e32 v147, 1.0, v147
	v_add_f32_e32 v148, 1.0, v148
	v_rcp_f32_e32 v147, v147
	v_rcp_f32_e32 v148, v148
	v_add_f32_e32 v149, 1.0, v149
	v_rcp_f32_e32 v149, v149
	v_max_f32_e32 v147, 0xda24260, v147
	v_max_f32_e32 v148, 0xda24260, v148
	v_cvt_pk_bf16_f32 v147, v147, v148
	v_mul_f32_e32 v148, 0xbfb8aa3b, v198
	v_exp_f32_e32 v148, v148
	v_max_f32_e32 v149, 0xda24260, v149
	v_mul_f32_e32 v163, 0xbfb8aa3b, v197
	v_exp_f32_e32 v163, v163
	v_add_f32_e32 v148, 1.0, v148
	v_rcp_f32_e32 v148, v148
	v_pk_fma_f32 v[198:199], v[66:67], v[0:1], v[130:131] op_sel_hi:[1,0,1]
	v_add_f32_e32 v163, 1.0, v163
	v_rcp_f32_e32 v163, v163
	v_max_f32_e32 v148, 0xda24260, v148
	v_cvt_pk_bf16_f32 v148, v148, v149
	v_mul_f32_e32 v149, 0xbfb8aa3b, v196
	v_exp_f32_e32 v149, v149
	v_max_f32_e32 v163, 0xda24260, v163
	v_pk_fma_f32 v[196:197], v[68:69], v[0:1], v[132:133] op_sel_hi:[1,0,1]
	v_add_f32_e32 v149, 1.0, v149
	v_rcp_f32_e32 v149, v149
	s_nop 0
	v_max_f32_e32 v149, 0xda24260, v149
	v_cvt_pk_bf16_f32 v149, v149, v163
	global_store_dwordx4 v[194:195], v[146:149], off
	s_nop 1
	v_pk_fma_f32 v[146:147], v[70:71], v[0:1], v[134:135] op_sel_hi:[1,0,1]
	v_pk_fma_f32 v[148:149], v[72:73], v[0:1], v[136:137] op_sel_hi:[1,0,1]
	v_mul_f32_e32 v0, 0xbfb8aa3b, v146
	v_mul_f32_e32 v146, 0xbfb8aa3b, v147
	v_exp_f32_e32 v0, v0
	v_exp_f32_e32 v146, v146
	v_mul_f32_e32 v147, 0xbfb8aa3b, v149
	v_exp_f32_e32 v147, v147
	v_add_f32_e32 v0, 1.0, v0
	v_add_f32_e32 v146, 1.0, v146
	v_rcp_f32_e32 v0, v0
	v_rcp_f32_e32 v146, v146
	v_add_f32_e32 v147, 1.0, v147
	v_rcp_f32_e32 v147, v147
	v_max_f32_e32 v0, 0xda24260, v0
	v_max_f32_e32 v146, 0xda24260, v146
	v_cvt_pk_bf16_f32 v146, v0, v146
	v_mul_f32_e32 v0, 0xbfb8aa3b, v148
	v_exp_f32_e32 v0, v0
	v_max_f32_e32 v147, 0xda24260, v147
	v_mul_f32_e32 v148, 0xbfb8aa3b, v199
	v_exp_f32_e32 v148, v148
	v_add_f32_e32 v0, 1.0, v0
	v_rcp_f32_e32 v0, v0
	v_mul_f32_e32 v149, 0xbfb8aa3b, v197
	v_add_f32_e32 v148, 1.0, v148
	v_rcp_f32_e32 v148, v148
	v_max_f32_e32 v0, 0xda24260, v0
	v_cvt_pk_bf16_f32 v147, v0, v147
	v_mul_f32_e32 v0, 0xbfb8aa3b, v198
	v_exp_f32_e32 v0, v0
	v_max_f32_e32 v148, 0xda24260, v148
	v_exp_f32_e32 v149, v149
	v_add_f32_e32 v0, 1.0, v0
	v_rcp_f32_e32 v0, v0
	v_add_f32_e32 v149, 1.0, v149
	v_rcp_f32_e32 v149, v149
	v_max_f32_e32 v0, 0xda24260, v0
	v_cvt_pk_bf16_f32 v148, v0, v148
	v_mul_f32_e32 v0, 0xbfb8aa3b, v196
	v_exp_f32_e32 v0, v0
	v_max_f32_e32 v149, 0xda24260, v149
	v_add_f32_e32 v0, 1.0, v0
	v_rcp_f32_e32 v0, v0
	s_nop 0
	v_max_f32_e32 v0, 0xda24260, v0
	v_cvt_pk_bf16_f32 v149, v0, v149
	global_store_dwordx4 v[194:195], v[146:149], off offset:256
	v_lshl_add_u64 v[194:195], v[164:165], 0, s[20:21]
	s_mov_b64 s[20:21], 0x48000
	s_nop 1
	v_mov_b32_e32 v0, v210
	v_pk_fma_f32 v[146:147], v[62:63], v[0:1], v[142:143] op_sel_hi:[1,0,1]
	s_nop 0
	v_mul_f32_e32 v146, 0xbfb8aa3b, v146
	v_mul_f32_e32 v147, 0xbfb8aa3b, v147
	v_exp_f32_e32 v146, v146
	v_exp_f32_e32 v147, v147
	v_pk_fma_f32 v[148:149], v[64:65], v[0:1], v[144:145] op_sel_hi:[1,0,1]
	v_pk_fma_f32 v[198:199], v[58:59], v[0:1], v[138:139] op_sel_hi:[1,0,1]
	v_add_f32_e32 v146, 1.0, v146
	v_add_f32_e32 v147, 1.0, v147
	v_rcp_f32_e32 v146, v146
	v_rcp_f32_e32 v147, v147
	v_pk_fma_f32 v[196:197], v[60:61], v[0:1], v[140:141] op_sel_hi:[1,0,1]
	v_max_f32_e32 v146, 0xda24260, v146
	v_max_f32_e32 v147, 0xda24260, v147
	v_cvt_pk_bf16_f32 v146, v146, v147
	v_mul_f32_e32 v147, 0xbfb8aa3b, v148
	v_mul_f32_e32 v148, 0xbfb8aa3b, v149
	v_exp_f32_e32 v147, v147
; #define GAS __attribute__((address_space(1)))
; __device__ __forceinline__ unsigned cvt_pk_bf16(float lo, float hi) { f32x2 v = {lo, hi}; bf16x2_t b = __builtin_convertvector(v, bf16x2_t); return __builtin_bit_cast(unsigned, b); }
; __device__ __forceinline__ float sigmoid_f(float x) { return __builtin_amdgcn_rcpf(1.0f + __builtin_amdgcn_exp2f(-x * LOG2E)); }
;     __device__ __forceinline__ void operator()(const f32x4 (&acc)[2][2][4][2], const Unit& u, int wr, int wc, int fr, int fq) const {
;     ...
;             for (int m = 0; m < 4; ++m) { const int row = row0 + ai * HALF + m * 16; const float rs = q.rs1[row]; GAS bf16_t* rowp = G + (size_t)row * 1024 + col0;
; #pragma unroll
;                 for (int bj = 0; bj < 2; ++bj) { const f32x4 v0 = acc[ai][bj][m][0] * rs + bv[bj][0], v1 = acc[ai][bj][m][1] * rs + bv[bj][1];
;                     u32x4 w; w.x = cvt_pk_bf16(fmaxf(sigmoid_f(v0[0]), 1e-30f), fmaxf(sigmoid_f(v0[1]), 1e-30f)); w.y = cvt_pk_bf16(fmaxf(sigmoid_f(v0[2]), 1e-30f), fmaxf(sigmoid_f(v0[3]), 1e-30f));
;                     w.z = cvt_pk_bf16(fmaxf(sigmoid_f(v1[0]), 1e-30f), fmaxf(sigmoid_f(v1[1]), 1e-30f)); w.w = cvt_pk_bf16(fmaxf(sigmoid_f(v1[2]), 1e-30f), fmaxf(sigmoid_f(v1[3]), 1e-30f));
;                     *(GAS u32x4*)(rowp + bj * HALF) = w; } }
	v_exp_f32_e32 v148, v148
	v_mul_f32_e32 v149, 0xbfb8aa3b, v199
	v_exp_f32_e32 v149, v149
	v_add_f32_e32 v147, 1.0, v147
	v_add_f32_e32 v148, 1.0, v148
	v_rcp_f32_e32 v147, v147
	v_rcp_f32_e32 v148, v148
	v_add_f32_e32 v149, 1.0, v149
	v_rcp_f32_e32 v149, v149
	v_max_f32_e32 v147, 0xda24260, v147
	v_max_f32_e32 v148, 0xda24260, v148
	v_cvt_pk_bf16_f32 v147, v147, v148
	v_mul_f32_e32 v148, 0xbfb8aa3b, v198
	v_exp_f32_e32 v148, v148
	v_max_f32_e32 v149, 0xda24260, v149
	v_mul_f32_e32 v163, 0xbfb8aa3b, v197
	v_exp_f32_e32 v163, v163
	v_add_f32_e32 v148, 1.0, v148
	v_rcp_f32_e32 v148, v148
	v_pk_fma_f32 v[198:199], v[50:51], v[0:1], v[130:131] op_sel_hi:[1,0,1]
	v_add_f32_e32 v163, 1.0, v163
	v_rcp_f32_e32 v163, v163
	v_max_f32_e32 v148, 0xda24260, v148
	v_cvt_pk_bf16_f32 v148, v148, v149
	v_mul_f32_e32 v149, 0xbfb8aa3b, v196
	v_exp_f32_e32 v149, v149
	v_max_f32_e32 v163, 0xda24260, v163
	v_add_co_u32_e32 v196, vcc, s11, v164
	v_add_f32_e32 v149, 1.0, v149
	v_rcp_f32_e32 v149, v149
	v_addc_co_u32_e32 v197, vcc, 0, v165, vcc
	s_mov_b32 s11, 0x48000
	v_max_f32_e32 v149, 0xda24260, v149
	v_cvt_pk_bf16_f32 v149, v149, v163
	global_store_dwordx4 v[196:197], v[146:149], off
	v_pk_fma_f32 v[196:197], v[52:53], v[0:1], v[132:133] op_sel_hi:[1,0,1]
	s_nop 0
	v_pk_fma_f32 v[146:147], v[54:55], v[0:1], v[134:135] op_sel_hi:[1,0,1]
	v_pk_fma_f32 v[148:149], v[56:57], v[0:1], v[136:137] op_sel_hi:[1,0,1]
	v_mul_f32_e32 v0, 0xbfb8aa3b, v146
	v_mul_f32_e32 v146, 0xbfb8aa3b, v147
	v_exp_f32_e32 v0, v0
	v_exp_f32_e32 v146, v146
	v_mul_f32_e32 v147, 0xbfb8aa3b, v149
	v_exp_f32_e32 v147, v147
	v_add_f32_e32 v0, 1.0, v0
	v_add_f32_e32 v146, 1.0, v146
	v_rcp_f32_e32 v0, v0
	v_rcp_f32_e32 v146, v146
	v_add_f32_e32 v147, 1.0, v147
	v_rcp_f32_e32 v147, v147
	v_max_f32_e32 v0, 0xda24260, v0
	v_max_f32_e32 v146, 0xda24260, v146
	v_cvt_pk_bf16_f32 v146, v0, v146
	v_mul_f32_e32 v0, 0xbfb8aa3b, v148
	v_exp_f32_e32 v0, v0
	v_max_f32_e32 v147, 0xda24260, v147
	v_mul_f32_e32 v148, 0xbfb8aa3b, v199
	v_exp_f32_e32 v148, v148
	v_add_f32_e32 v0, 1.0, v0
	v_rcp_f32_e32 v0, v0
	v_mul_f32_e32 v149, 0xbfb8aa3b, v197
	v_add_f32_e32 v148, 1.0, v148
	v_rcp_f32_e32 v148, v148
	v_max_f32_e32 v0, 0xda24260, v0
	v_cvt_pk_bf16_f32 v147, v0, v147
	v_mul_f32_e32 v0, 0xbfb8aa3b, v198
	v_exp_f32_e32 v0, v0
	v_max_f32_e32 v148, 0xda24260, v148
	v_exp_f32_e32 v149, v149
	v_add_f32_e32 v0, 1.0, v0
	v_rcp_f32_e32 v0, v0
	v_add_f32_e32 v149, 1.0, v149
	v_rcp_f32_e32 v149, v149
	v_max_f32_e32 v0, 0xda24260, v0
	v_cvt_pk_bf16_f32 v148, v0, v148
	v_mul_f32_e32 v0, 0xbfb8aa3b, v196
	v_exp_f32_e32 v0, v0
	v_max_f32_e32 v149, 0xda24260, v149
	v_add_f32_e32 v0, 1.0, v0
	v_rcp_f32_e32 v0, v0
	s_nop 0
	v_max_f32_e32 v0, 0xda24260, v0
	v_cvt_pk_bf16_f32 v149, v0, v149
	global_store_dwordx4 v[194:195], v[146:149], off offset:256
	s_nop 1
	v_mov_b32_e32 v0, v211
	v_pk_fma_f32 v[194:195], v[46:47], v[0:1], v[142:143] op_sel_hi:[1,0,1]
	v_pk_fma_f32 v[148:149], v[48:49], v[0:1], v[144:145] op_sel_hi:[1,0,1]
	v_pk_fma_f32 v[196:197], v[42:43], v[0:1], v[138:139] op_sel_hi:[1,0,1]
	v_mul_f32_e32 v148, 0xbfb8aa3b, v148
	v_mul_f32_e32 v149, 0xbfb8aa3b, v149
	v_exp_f32_e32 v148, v148
	v_exp_f32_e32 v149, v149
	v_mul_f32_e32 v163, 0xbfb8aa3b, v194
	v_mul_f32_e32 v194, 0xbfb8aa3b, v195
	v_add_f32_e32 v148, 1.0, v148
	v_add_f32_e32 v149, 1.0, v149
	v_rcp_f32_e32 v148, v148
	v_rcp_f32_e32 v149, v149
	v_pk_fma_f32 v[198:199], v[44:45], v[0:1], v[140:141] op_sel_hi:[1,0,1]
	v_exp_f32_e32 v163, v163
	v_max_f32_e32 v148, 0xda24260, v148
	v_max_f32_e32 v149, 0xda24260, v149
	v_cvt_pk_bf16_f32 v195, v148, v149
	v_mul_f32_e32 v148, 0xbfb8aa3b, v196
	v_mul_f32_e32 v149, 0xbfb8aa3b, v197
	v_exp_f32_e32 v148, v148
	v_exp_f32_e32 v149, v149
	v_exp_f32_e32 v194, v194
	v_add_f32_e32 v163, 1.0, v163
	v_add_f32_e32 v148, 1.0, v148
	v_add_f32_e32 v149, 1.0, v149
	v_rcp_f32_e32 v148, v148
	v_rcp_f32_e32 v149, v149
	v_add_f32_e32 v194, 1.0, v194
	v_rcp_f32_e32 v163, v163
	v_max_f32_e32 v148, 0xda24260, v148
	v_max_f32_e32 v149, 0xda24260, v149
	v_cvt_pk_bf16_f32 v196, v148, v149
	v_mul_f32_e32 v148, 0xbfb8aa3b, v198
	v_mul_f32_e32 v149, 0xbfb8aa3b, v199
	v_exp_f32_e32 v148, v148
	v_exp_f32_e32 v149, v149
	v_rcp_f32_e32 v194, v194
	v_max_f32_e32 v163, 0xda24260, v163
	v_add_f32_e32 v148, 1.0, v148
	v_add_f32_e32 v149, 1.0, v149
	v_rcp_f32_e32 v148, v148
	v_rcp_f32_e32 v149, v149
	v_max_f32_e32 v194, 0xda24260, v194
	v_cvt_pk_bf16_f32 v194, v163, v194
	v_max_f32_e32 v148, 0xda24260, v148
	v_max_f32_e32 v149, 0xda24260, v149
	v_cvt_pk_bf16_f32 v197, v148, v149
	v_add_co_u32_e32 v148, vcc, s11, v164
	v_pk_fma_f32 v[198:199], v[36:37], v[0:1], v[132:133] op_sel_hi:[1,0,1]
	s_nop 0
	v_addc_co_u32_e32 v149, vcc, 0, v165, vcc
	global_store_dwordx4 v[148:149], v[194:197], off
	v_pk_fma_f32 v[148:149], v[40:41], v[0:1], v[136:137] op_sel_hi:[1,0,1]
	v_lshl_add_u64 v[146:147], v[164:165], 0, s[20:21]
	v_pk_fma_f32 v[194:195], v[38:39], v[0:1], v[134:135] op_sel_hi:[1,0,1]
	v_pk_fma_f32 v[196:197], v[34:35], v[0:1], v[130:131] op_sel_hi:[1,0,1]
	v_mul_f32_e32 v0, 0xbfb8aa3b, v194
	v_mul_f32_e32 v163, 0xbfb8aa3b, v195
	v_exp_f32_e32 v0, v0
	v_exp_f32_e32 v163, v163
	s_mov_b32 s11, 0x50000
	s_mov_b64 s[20:21], 0x50000
	v_add_f32_e32 v0, 1.0, v0
	v_add_f32_e32 v163, 1.0, v163
	v_rcp_f32_e32 v0, v0
	v_rcp_f32_e32 v163, v163
	v_max_f32_e32 v0, 0xda24260, v0
	v_max_f32_e32 v163, 0xda24260, v163
	v_cvt_pk_bf16_f32 v194, v0, v163
	v_mul_f32_e32 v0, 0xbfb8aa3b, v148
	v_mul_f32_e32 v148, 0xbfb8aa3b, v149
	v_exp_f32_e32 v0, v0
	v_exp_f32_e32 v148, v148
	v_add_f32_e32 v0, 1.0, v0
	v_add_f32_e32 v148, 1.0, v148
	v_rcp_f32_e32 v0, v0
	v_rcp_f32_e32 v148, v148
; #define GAS __attribute__((address_space(1)))
; __device__ __forceinline__ unsigned cvt_pk_bf16(float lo, float hi) { f32x2 v = {lo, hi}; bf16x2_t b = __builtin_convertvector(v, bf16x2_t); return __builtin_bit_cast(unsigned, b); }
; __device__ __forceinline__ float sigmoid_f(float x) { return __builtin_amdgcn_rcpf(1.0f + __builtin_amdgcn_exp2f(-x * LOG2E)); }
;     __device__ __forceinline__ void operator()(const f32x4 (&acc)[2][2][4][2], const Unit& u, int wr, int wc, int fr, int fq) const {
;     ...
;             for (int m = 0; m < 4; ++m) { const int row = row0 + ai * HALF + m * 16; const float rs = q.rs1[row]; GAS bf16_t* rowp = G + (size_t)row * 1024 + col0;
; #pragma unroll
;                 for (int bj = 0; bj < 2; ++bj) { const f32x4 v0 = acc[ai][bj][m][0] * rs + bv[bj][0], v1 = acc[ai][bj][m][1] * rs + bv[bj][1];
;                     u32x4 w; w.x = cvt_pk_bf16(fmaxf(sigmoid_f(v0[0]), 1e-30f), fmaxf(sigmoid_f(v0[1]), 1e-30f)); w.y = cvt_pk_bf16(fmaxf(sigmoid_f(v0[2]), 1e-30f), fmaxf(sigmoid_f(v0[3]), 1e-30f));
;                     w.z = cvt_pk_bf16(fmaxf(sigmoid_f(v1[0]), 1e-30f), fmaxf(sigmoid_f(v1[1]), 1e-30f)); w.w = cvt_pk_bf16(fmaxf(sigmoid_f(v1[2]), 1e-30f), fmaxf(sigmoid_f(v1[3]), 1e-30f));
;                     *(GAS u32x4*)(rowp + bj * HALF) = w; } }
	v_max_f32_e32 v0, 0xda24260, v0
	v_max_f32_e32 v148, 0xda24260, v148
	v_cvt_pk_bf16_f32 v195, v0, v148
	v_mul_f32_e32 v0, 0xbfb8aa3b, v196
	v_mul_f32_e32 v148, 0xbfb8aa3b, v197
	v_exp_f32_e32 v0, v0
	v_exp_f32_e32 v148, v148
	v_add_f32_e32 v0, 1.0, v0
	v_add_f32_e32 v148, 1.0, v148
	v_rcp_f32_e32 v0, v0
	v_rcp_f32_e32 v148, v148
	v_max_f32_e32 v0, 0xda24260, v0
	v_max_f32_e32 v148, 0xda24260, v148
	v_cvt_pk_bf16_f32 v196, v0, v148
	v_mul_f32_e32 v0, 0xbfb8aa3b, v198
	v_mul_f32_e32 v148, 0xbfb8aa3b, v199
	v_exp_f32_e32 v0, v0
	v_exp_f32_e32 v148, v148
	v_add_f32_e32 v0, 1.0, v0
	v_add_f32_e32 v148, 1.0, v148
	v_rcp_f32_e32 v0, v0
	v_rcp_f32_e32 v148, v148
	v_max_f32_e32 v0, 0xda24260, v0
	v_max_f32_e32 v148, 0xda24260, v148
	v_cvt_pk_bf16_f32 v197, v0, v148
	global_store_dwordx4 v[146:147], v[194:197], off offset:256
	v_lshl_add_u64 v[146:147], v[164:165], 0, s[20:21]
	s_mov_b64 s[20:21], 0x58000
	s_nop 1
	v_mov_b32_e32 v0, v212
	v_pk_fma_f32 v[148:149], v[32:33], v[0:1], v[144:145] op_sel_hi:[1,0,1]
	s_nop 0
	v_mul_f32_e32 v148, 0xbfb8aa3b, v148
	v_mul_f32_e32 v149, 0xbfb8aa3b, v149
	v_exp_f32_e32 v148, v148
	v_exp_f32_e32 v149, v149
	v_pk_fma_f32 v[194:195], v[30:31], v[0:1], v[142:143] op_sel_hi:[1,0,1]
	v_pk_fma_f32 v[196:197], v[26:27], v[0:1], v[138:139] op_sel_hi:[1,0,1]
	v_add_f32_e32 v148, 1.0, v148
	v_add_f32_e32 v149, 1.0, v149
	v_rcp_f32_e32 v148, v148
	v_rcp_f32_e32 v149, v149
	v_mul_f32_e32 v163, 0xbfb8aa3b, v194
	v_mul_f32_e32 v194, 0xbfb8aa3b, v195
	v_max_f32_e32 v148, 0xda24260, v148
	v_max_f32_e32 v149, 0xda24260, v149
	v_cvt_pk_bf16_f32 v195, v148, v149
	v_mul_f32_e32 v148, 0xbfb8aa3b, v196
	v_mul_f32_e32 v149, 0xbfb8aa3b, v197
	v_exp_f32_e32 v148, v148
	v_exp_f32_e32 v149, v149
	v_pk_fma_f32 v[198:199], v[28:29], v[0:1], v[140:141] op_sel_hi:[1,0,1]
	v_exp_f32_e32 v163, v163
	v_add_f32_e32 v148, 1.0, v148
	v_add_f32_e32 v149, 1.0, v149
	v_rcp_f32_e32 v148, v148
	v_rcp_f32_e32 v149, v149
	v_exp_f32_e32 v194, v194
	v_add_f32_e32 v163, 1.0, v163
	v_max_f32_e32 v148, 0xda24260, v148
	v_max_f32_e32 v149, 0xda24260, v149
	v_cvt_pk_bf16_f32 v196, v148, v149
	v_mul_f32_e32 v148, 0xbfb8aa3b, v198
	v_mul_f32_e32 v149, 0xbfb8aa3b, v199
	v_exp_f32_e32 v148, v148
	v_exp_f32_e32 v149, v149
	v_add_f32_e32 v194, 1.0, v194
	v_rcp_f32_e32 v163, v163
	v_add_f32_e32 v148, 1.0, v148
	v_add_f32_e32 v149, 1.0, v149
	v_rcp_f32_e32 v148, v148
	v_rcp_f32_e32 v149, v149
	v_rcp_f32_e32 v194, v194
	v_max_f32_e32 v163, 0xda24260, v163
	v_max_f32_e32 v148, 0xda24260, v148
	v_max_f32_e32 v149, 0xda24260, v149
	v_max_f32_e32 v194, 0xda24260, v194
	v_cvt_pk_bf16_f32 v197, v148, v149
	v_add_co_u32_e32 v148, vcc, s11, v164
	v_cvt_pk_bf16_f32 v194, v163, v194
	s_nop 0
	v_addc_co_u32_e32 v149, vcc, 0, v165, vcc
	global_store_dwordx4 v[148:149], v[194:197], off
	v_pk_fma_f32 v[148:149], v[24:25], v[0:1], v[136:137] op_sel_hi:[1,0,1]
	v_pk_fma_f32 v[198:199], v[20:21], v[0:1], v[132:133] op_sel_hi:[1,0,1]
	v_pk_fma_f32 v[194:195], v[22:23], v[0:1], v[134:135] op_sel_hi:[1,0,1]
	v_pk_fma_f32 v[196:197], v[18:19], v[0:1], v[130:131] op_sel_hi:[1,0,1]
	v_mul_f32_e32 v0, 0xbfb8aa3b, v194
	v_mul_f32_e32 v163, 0xbfb8aa3b, v195
	v_exp_f32_e32 v0, v0
	v_exp_f32_e32 v163, v163
	s_mov_b32 s11, 0x58000
	v_add_f32_e32 v0, 1.0, v0
	v_add_f32_e32 v163, 1.0, v163
	v_rcp_f32_e32 v0, v0
	v_rcp_f32_e32 v163, v163
	v_max_f32_e32 v0, 0xda24260, v0
	v_max_f32_e32 v163, 0xda24260, v163
	v_cvt_pk_bf16_f32 v194, v0, v163
	v_mul_f32_e32 v0, 0xbfb8aa3b, v148
	v_mul_f32_e32 v148, 0xbfb8aa3b, v149
	v_exp_f32_e32 v0, v0
	v_exp_f32_e32 v148, v148
	v_add_f32_e32 v0, 1.0, v0
	v_add_f32_e32 v148, 1.0, v148
	v_rcp_f32_e32 v0, v0
	v_rcp_f32_e32 v148, v148
	v_max_f32_e32 v0, 0xda24260, v0
	v_max_f32_e32 v148, 0xda24260, v148
	v_cvt_pk_bf16_f32 v195, v0, v148
	v_mul_f32_e32 v0, 0xbfb8aa3b, v196
	v_mul_f32_e32 v148, 0xbfb8aa3b, v197
	v_exp_f32_e32 v0, v0
	v_exp_f32_e32 v148, v148
	v_add_f32_e32 v0, 1.0, v0
	v_add_f32_e32 v148, 1.0, v148
	v_rcp_f32_e32 v0, v0
	v_rcp_f32_e32 v148, v148
	v_max_f32_e32 v0, 0xda24260, v0
	v_max_f32_e32 v148, 0xda24260, v148
; #define GAS __attribute__((address_space(1)))
; __device__ __forceinline__ unsigned cvt_pk_bf16(float lo, float hi) { f32x2 v = {lo, hi}; bf16x2_t b = __builtin_convertvector(v, bf16x2_t); return __builtin_bit_cast(unsigned, b); }
; __device__ __forceinline__ float sigmoid_f(float x) { return __builtin_amdgcn_rcpf(1.0f + __builtin_amdgcn_exp2f(-x * LOG2E)); }
;     __device__ __forceinline__ void operator()(const f32x4 (&acc)[2][2][4][2], const Unit& u, int wr, int wc, int fr, int fq) const {
;     ...
;             for (int m = 0; m < 4; ++m) { const int row = row0 + ai * HALF + m * 16; const float rs = q.rs1[row]; GAS bf16_t* rowp = G + (size_t)row * 1024 + col0;
; #pragma unroll
;                 for (int bj = 0; bj < 2; ++bj) { const f32x4 v0 = acc[ai][bj][m][0] * rs + bv[bj][0], v1 = acc[ai][bj][m][1] * rs + bv[bj][1];
;                     u32x4 w; w.x = cvt_pk_bf16(fmaxf(sigmoid_f(v0[0]), 1e-30f), fmaxf(sigmoid_f(v0[1]), 1e-30f)); w.y = cvt_pk_bf16(fmaxf(sigmoid_f(v0[2]), 1e-30f), fmaxf(sigmoid_f(v0[3]), 1e-30f));
;                     w.z = cvt_pk_bf16(fmaxf(sigmoid_f(v1[0]), 1e-30f), fmaxf(sigmoid_f(v1[1]), 1e-30f)); w.w = cvt_pk_bf16(fmaxf(sigmoid_f(v1[2]), 1e-30f), fmaxf(sigmoid_f(v1[3]), 1e-30f));
;                     *(GAS u32x4*)(rowp + bj * HALF) = w; } }
	v_cvt_pk_bf16_f32 v196, v0, v148
	v_mul_f32_e32 v0, 0xbfb8aa3b, v198
	v_mul_f32_e32 v148, 0xbfb8aa3b, v199
	v_exp_f32_e32 v0, v0
	v_exp_f32_e32 v148, v148
	v_add_f32_e32 v0, 1.0, v0
	v_add_f32_e32 v148, 1.0, v148
	v_rcp_f32_e32 v0, v0
	v_rcp_f32_e32 v148, v148
	v_max_f32_e32 v0, 0xda24260, v0
	v_max_f32_e32 v148, 0xda24260, v148
	v_cvt_pk_bf16_f32 v197, v0, v148
	global_store_dwordx4 v[146:147], v[194:197], off offset:256
	v_lshl_add_u64 v[146:147], v[164:165], 0, s[20:21]
	s_nop 1
	v_mov_b32_e32 v0, v213
	v_pk_fma_f32 v[142:143], v[14:15], v[0:1], v[142:143] op_sel_hi:[1,0,1]
	v_pk_fma_f32 v[148:149], v[12:13], v[0:1], v[140:141] op_sel_hi:[1,0,1]
	v_pk_fma_f32 v[140:141], v[10:11], v[0:1], v[138:139] op_sel_hi:[1,0,1]
	v_mul_f32_e32 v138, 0xbfb8aa3b, v142
	v_mul_f32_e32 v139, 0xbfb8aa3b, v143
	v_exp_f32_e32 v138, v138
	v_exp_f32_e32 v139, v139
	v_pk_fma_f32 v[144:145], v[16:17], v[0:1], v[144:145] op_sel_hi:[1,0,1]
	v_mul_f32_e32 v140, 0xbfb8aa3b, v140
	v_add_f32_e32 v138, 1.0, v138
	v_add_f32_e32 v139, 1.0, v139
	v_rcp_f32_e32 v138, v138
	v_rcp_f32_e32 v139, v139
	v_mul_f32_e32 v142, 0xbfb8aa3b, v145
	v_mul_f32_e32 v141, 0xbfb8aa3b, v141
	v_max_f32_e32 v138, 0xda24260, v138
	v_max_f32_e32 v139, 0xda24260, v139
	v_cvt_pk_bf16_f32 v138, v138, v139
	v_mul_f32_e32 v139, 0xbfb8aa3b, v144
	v_exp_f32_e32 v139, v139
	v_exp_f32_e32 v142, v142
	v_exp_f32_e32 v140, v140
	v_exp_f32_e32 v141, v141
	v_add_f32_e32 v139, 1.0, v139
	v_add_f32_e32 v142, 1.0, v142
	v_add_f32_e32 v140, 1.0, v140
	v_add_f32_e32 v141, 1.0, v141
	v_rcp_f32_e32 v139, v139
	v_rcp_f32_e32 v142, v142
	v_rcp_f32_e32 v140, v140
	v_rcp_f32_e32 v141, v141
	v_max_f32_e32 v139, 0xda24260, v139
	v_max_f32_e32 v142, 0xda24260, v142
	v_max_f32_e32 v140, 0xda24260, v140
	v_max_f32_e32 v141, 0xda24260, v141
	v_cvt_pk_bf16_f32 v139, v139, v142
	v_cvt_pk_bf16_f32 v140, v140, v141
	v_mul_f32_e32 v141, 0xbfb8aa3b, v148
	v_mul_f32_e32 v142, 0xbfb8aa3b, v149
	v_exp_f32_e32 v141, v141
	v_exp_f32_e32 v142, v142
	v_pk_fma_f32 v[134:135], v[6:7], v[0:1], v[134:135] op_sel_hi:[1,0,1]
	v_pk_fma_f32 v[136:137], v[8:9], v[0:1], v[136:137] op_sel_hi:[1,0,1]
	v_add_f32_e32 v141, 1.0, v141
	v_add_f32_e32 v142, 1.0, v142
	v_rcp_f32_e32 v141, v141
	v_rcp_f32_e32 v142, v142
	v_max_f32_e32 v141, 0xda24260, v141
	v_max_f32_e32 v142, 0xda24260, v142
	v_cvt_pk_bf16_f32 v141, v141, v142
	v_add_co_u32_e32 v142, vcc, s11, v164
	s_nop 1
	v_addc_co_u32_e32 v143, vcc, 0, v165, vcc
	global_store_dwordx4 v[142:143], v[138:141], off
	s_nop 1
	v_pk_fma_f32 v[138:139], v[4:5], v[0:1], v[132:133] op_sel_hi:[1,0,1]
	v_pk_fma_f32 v[132:133], v[2:3], v[0:1], v[130:131] op_sel_hi:[1,0,1]
	v_mul_f32_e32 v0, 0xbfb8aa3b, v134
	v_mul_f32_e32 v130, 0xbfb8aa3b, v135
	v_exp_f32_e32 v0, v0
	v_exp_f32_e32 v130, v130
	v_mul_f32_e32 v131, 0xbfb8aa3b, v137
	v_exp_f32_e32 v131, v131
	v_add_f32_e32 v0, 1.0, v0
	v_add_f32_e32 v130, 1.0, v130
	v_rcp_f32_e32 v0, v0
	v_rcp_f32_e32 v130, v130
	v_add_f32_e32 v131, 1.0, v131
	v_rcp_f32_e32 v131, v131
	v_max_f32_e32 v0, 0xda24260, v0
	v_max_f32_e32 v130, 0xda24260, v130
	v_cvt_pk_bf16_f32 v130, v0, v130
	v_mul_f32_e32 v0, 0xbfb8aa3b, v136
	v_exp_f32_e32 v0, v0
	v_max_f32_e32 v131, 0xda24260, v131
	v_add_f32_e32 v0, 1.0, v0
	v_rcp_f32_e32 v0, v0
	s_nop 0
	v_max_f32_e32 v0, 0xda24260, v0
	v_cvt_pk_bf16_f32 v131, v0, v131
	v_mul_f32_e32 v0, 0xbfb8aa3b, v132
	v_mul_f32_e32 v132, 0xbfb8aa3b, v133
	v_exp_f32_e32 v0, v0
	v_exp_f32_e32 v132, v132
	v_mul_f32_e32 v133, 0xbfb8aa3b, v139
	v_exp_f32_e32 v133, v133
	v_add_f32_e32 v0, 1.0, v0
	v_add_f32_e32 v132, 1.0, v132
	v_rcp_f32_e32 v0, v0
	v_rcp_f32_e32 v132, v132
	v_add_f32_e32 v133, 1.0, v133
	v_rcp_f32_e32 v133, v133
	v_max_f32_e32 v0, 0xda24260, v0
	v_max_f32_e32 v132, 0xda24260, v132
	v_cvt_pk_bf16_f32 v132, v0, v132
	v_mul_f32_e32 v0, 0xbfb8aa3b, v138
	v_exp_f32_e32 v0, v0
	v_max_f32_e32 v133, 0xda24260, v133
	v_add_f32_e32 v0, 1.0, v0
	v_rcp_f32_e32 v0, v0
	s_nop 0
	v_max_f32_e32 v0, 0xda24260, v0
	v_cvt_pk_bf16_f32 v133, v0, v133
	global_store_dwordx4 v[146:147], v[130:133], off offset:256
	s_cbranch_execnz .LBB0_250

; #define GAS __attribute__((address_space(1)))
; __device__ __forceinline__ unsigned cvt_pk_bf16(float lo, float hi) { f32x2 v = {lo, hi}; bf16x2_t b = __builtin_convertvector(v, bf16x2_t); return __builtin_bit_cast(unsigned, b); }
;     __device__ __forceinline__ void operator()(const f32x4 (&acc)[2][2][4][2], const Unit& u, int wr, int wc, int fr, int fq) const {
;     ...
;             for (int m = 0; m < 4; ++m) { const int row = row0 + ai * HALF + m * 16; const float rs = rs1[row]; GAS bf16_t* rowp = base + (size_t)row * 512 + col0;
; #pragma unroll
;                 for (int bj = 0; bj < 2; ++bj) { const f32x4 v0 = acc[ai][bj][m][0] * rs, v1 = acc[ai][bj][m][1] * rs;
;                     u32x4 w; w.x = cvt_pk_bf16(v0[0], v0[1]); w.y = cvt_pk_bf16(v0[2], v0[3]); w.z = cvt_pk_bf16(v1[0], v1[1]); w.w = cvt_pk_bf16(v1[2], v1[3]);
;                     *(GAS u32x4*)(rowp + bj * HALF) = w;
;                     if (sidx >= 0) { float q = ((v0[0] * v0[0] + v0[1] * v0[1]) + (v0[2] * v0[2] + v0[3] * v0[3])) + ((v1[0] * v1[0] + v1[1] * v1[1]) + (v1[2] * v1[2] + v1[3] * v1[3]));
;                         q += __shfl_xor(q, 16); q += __shfl_xor(q, 32);
;                         if (fq == 0) ss[((size_t)sidx * MROWS + row) * 16 + (colt >> 5) + 4 * bj + wc] = q; } } }
.LBB0_186:
	v_ashrrev_i32_e32 v163, 31, v162
	v_lshl_add_u64 v[130:131], v[162:163], 2, s[2:3]
	global_load_dword v206, v[130:131], off
	global_load_dword v207, v[130:131], off offset:64
	global_load_dword v208, v[130:131], off offset:128
	global_load_dword v209, v[130:131], off offset:192
	global_load_dword v210, v[130:131], off offset:512
	global_load_dword v211, v[130:131], off offset:576
	global_load_dword v212, v[130:131], off offset:640
	global_load_dword v213, v[130:131], off offset:704
	s_lshl_b32 s10, s10, 8
	s_ashr_i32 s21, s20, 31
	s_and_b32 s13, s10, 0x100
	s_lshl_b64 s[10:11], s[20:21], 25
	s_add_u32 s10, s42, s10
	v_or_b32_e32 v0, s13, v203
	s_addc_u32 s11, s43, s11
	v_lshlrev_b32_e32 v0, 1, v0
	s_cmp_gt_i32 s72, -1
	v_lshlrev_b64 v[138:139], 10, v[162:163]
	v_lshl_add_u64 v[132:133], s[10:11], 0, v[0:1]
	s_cselect_b64 s[22:23], -1, 0
	s_lshr_b32 s13, s13, 5
	s_lshl_b64 s[20:21], s[72:73], 21
	v_lshlrev_b64 v[134:135], 6, v[162:163]
	v_lshl_add_u64 v[138:139], v[132:133], 0, v[138:139]
	s_cmp_lt_i32 s72, 0
	s_waitcnt vmcnt(0)
	s_nop 1
	v_mov_b32_e32 v136, v206
	v_pk_mul_f32 v[128:129], v[128:129], v[136:137] op_sel_hi:[1,0]
	v_pk_mul_f32 v[126:127], v[126:127], v[136:137] op_sel_hi:[1,0]
	v_pk_mul_f32 v[124:125], v[124:125], v[136:137] op_sel_hi:[1,0]
	v_pk_mul_f32 v[122:123], v[122:123], v[136:137] op_sel_hi:[1,0]
	v_cvt_pk_bf16_f32 v140, v126, v127
	v_cvt_pk_bf16_f32 v141, v128, v129
	v_cvt_pk_bf16_f32 v142, v122, v123
	v_cvt_pk_bf16_f32 v143, v124, v125
	global_store_dwordx4 v[138:139], v[140:143], off
	s_cbranch_scc1 .LBB0_190
	v_mul_f32_e32 v0, v127, v127
	v_mul_f32_e32 v123, v123, v123
	v_fmac_f32_e32 v0, v126, v126
	v_mul_f32_e32 v126, v129, v129
	v_fmac_f32_e32 v123, v122, v122
	v_mul_f32_e32 v122, v125, v125
	v_fmac_f32_e32 v126, v128, v128
	v_fmac_f32_e32 v122, v124, v124
	v_add_f32_e32 v0, v0, v126
	v_add_f32_e32 v122, v123, v122
	v_and_b32_e32 v123, 64, v240
	v_add_f32_e32 v0, v0, v122
	v_xor_b32_e32 v122, 16, v240
	v_add_u32_e32 v123, 64, v123
	v_cmp_lt_i32_e32 vcc, v122, v123
	s_nop 1
	v_cndmask_b32_e32 v122, v240, v122, vcc
	v_lshlrev_b32_e32 v122, 2, v122
	ds_bpermute_b32 v122, v122, v0
	s_waitcnt lgkmcnt(0)
	v_add_f32_e32 v0, v0, v122
	v_xor_b32_e32 v122, 32, v240
	v_cmp_lt_i32_e32 vcc, v122, v123
	s_nop 1
	v_cndmask_b32_e32 v122, v240, v122, vcc
	v_lshlrev_b32_e32 v122, 2, v122
	ds_bpermute_b32 v122, v122, v0
	s_and_saveexec_b64 s[10:11], s[6:7]
	s_cbranch_execz .LBB0_189
	s_add_u32 s24, s44, s20
	s_addc_u32 s25, s45, s21
	v_lshl_add_u64 v[124:125], s[24:25], 0, v[134:135]
	s_lshl_b32 s72, s13, 2
	v_lshl_add_u64 v[124:125], v[124:125], 0, s[72:73]
	s_lshl_b32 s72, s50, 2
	v_lshl_add_u64 v[124:125], v[124:125], 0, s[72:73]
	s_waitcnt lgkmcnt(0)
	v_add_f32_e32 v0, v0, v122
	global_store_dword v[124:125], v0, off

; #define GAS __attribute__((address_space(1)))
; __device__ __forceinline__ unsigned cvt_pk_bf16(float lo, float hi) { f32x2 v = {lo, hi}; bf16x2_t b = __builtin_convertvector(v, bf16x2_t); return __builtin_bit_cast(unsigned, b); }
;     __device__ __forceinline__ void operator()(const f32x4 (&acc)[2][2][4][2], const Unit& u, int wr, int wc, int fr, int fq) const {
;     ...
;             for (int m = 0; m < 4; ++m) { const int row = row0 + ai * HALF + m * 16; const float rs = rs1[row]; GAS bf16_t* rowp = base + (size_t)row * 512 + col0;
; #pragma unroll
;                 for (int bj = 0; bj < 2; ++bj) { const f32x4 v0 = acc[ai][bj][m][0] * rs, v1 = acc[ai][bj][m][1] * rs;
;                     u32x4 w; w.x = cvt_pk_bf16(v0[0], v0[1]); w.y = cvt_pk_bf16(v0[2], v0[3]); w.z = cvt_pk_bf16(v1[0], v1[1]); w.w = cvt_pk_bf16(v1[2], v1[3]);
;                     *(GAS u32x4*)(rowp + bj * HALF) = w;
;                     if (sidx >= 0) { float q = ((v0[0] * v0[0] + v0[1] * v0[1]) + (v0[2] * v0[2] + v0[3] * v0[3])) + ((v1[0] * v1[0] + v1[1] * v1[1]) + (v1[2] * v1[2] + v1[3] * v1[3]));
;                         q += __shfl_xor(q, 16); q += __shfl_xor(q, 32);
;                         if (fq == 0) ss[((size_t)sidx * MROWS + row) * 16 + (colt >> 5) + 4 * bj + wc] = q; } } }
.LBB0_194:
	s_waitcnt lgkmcnt(0)
	v_or_b32_e32 v114, 16, v162
	v_ashrrev_i32_e32 v115, 31, v114
	v_lshl_add_u64 v[116:117], v[114:115], 2, s[2:3]
	v_lshlrev_b64 v[116:117], 10, v[114:115]
	v_lshlrev_b64 v[114:115], 6, v[114:115]
	v_lshl_add_u64 v[116:117], v[132:133], 0, v[116:117]
	s_and_b64 vcc, exec, s[10:11]
	s_nop 1
	v_mov_b32_e32 v118, v207
	v_pk_mul_f32 v[112:113], v[112:113], v[118:119] op_sel_hi:[1,0]
	v_pk_mul_f32 v[110:111], v[110:111], v[118:119] op_sel_hi:[1,0]
	v_pk_mul_f32 v[108:109], v[108:109], v[118:119] op_sel_hi:[1,0]
	v_pk_mul_f32 v[106:107], v[106:107], v[118:119] op_sel_hi:[1,0]
	v_cvt_pk_bf16_f32 v120, v110, v111
	v_cvt_pk_bf16_f32 v121, v112, v113
	v_cvt_pk_bf16_f32 v122, v106, v107
	v_cvt_pk_bf16_f32 v123, v108, v109
	global_store_dwordx4 v[116:117], v[120:123], off
	s_cbranch_vccnz .LBB0_198
	v_mul_f32_e32 v0, v111, v111
	v_mul_f32_e32 v107, v107, v107
	v_fmac_f32_e32 v0, v110, v110
	v_mul_f32_e32 v110, v113, v113
	v_fmac_f32_e32 v107, v106, v106
	v_mul_f32_e32 v106, v109, v109
	v_fmac_f32_e32 v110, v112, v112
	v_fmac_f32_e32 v106, v108, v108
	v_add_f32_e32 v0, v0, v110
	v_add_f32_e32 v106, v107, v106
	v_and_b32_e32 v107, 64, v240
	v_add_f32_e32 v0, v0, v106
	v_xor_b32_e32 v106, 16, v240
	v_add_u32_e32 v107, 64, v107
	v_cmp_lt_i32_e32 vcc, v106, v107
	s_nop 1
	v_cndmask_b32_e32 v106, v240, v106, vcc
	v_lshlrev_b32_e32 v106, 2, v106
	ds_bpermute_b32 v106, v106, v0
	s_waitcnt lgkmcnt(0)
	v_add_f32_e32 v0, v0, v106
	v_xor_b32_e32 v106, 32, v240
	v_cmp_lt_i32_e32 vcc, v106, v107
	s_nop 1
	v_cndmask_b32_e32 v106, v240, v106, vcc
	v_lshlrev_b32_e32 v106, 2, v106
	ds_bpermute_b32 v106, v106, v0
	s_and_saveexec_b64 s[22:23], s[6:7]
	s_cbranch_execz .LBB0_197
	s_add_u32 s24, s44, s20
	s_addc_u32 s25, s45, s21
	v_lshl_add_u64 v[108:109], s[24:25], 0, v[114:115]
	s_lshl_b32 s72, s13, 2
	v_lshl_add_u64 v[108:109], v[108:109], 0, s[72:73]
	s_lshl_b32 s72, s50, 2
	v_lshl_add_u64 v[108:109], v[108:109], 0, s[72:73]
	s_waitcnt lgkmcnt(0)
	v_add_f32_e32 v0, v0, v106
	global_store_dword v[108:109], v0, off

; #define GAS __attribute__((address_space(1)))
; __device__ __forceinline__ unsigned cvt_pk_bf16(float lo, float hi) { f32x2 v = {lo, hi}; bf16x2_t b = __builtin_convertvector(v, bf16x2_t); return __builtin_bit_cast(unsigned, b); }
;     __device__ __forceinline__ void operator()(const f32x4 (&acc)[2][2][4][2], const Unit& u, int wr, int wc, int fr, int fq) const {
;     ...
;             for (int m = 0; m < 4; ++m) { const int row = row0 + ai * HALF + m * 16; const float rs = rs1[row]; GAS bf16_t* rowp = base + (size_t)row * 512 + col0;
; #pragma unroll
;                 for (int bj = 0; bj < 2; ++bj) { const f32x4 v0 = acc[ai][bj][m][0] * rs, v1 = acc[ai][bj][m][1] * rs;
;                     u32x4 w; w.x = cvt_pk_bf16(v0[0], v0[1]); w.y = cvt_pk_bf16(v0[2], v0[3]); w.z = cvt_pk_bf16(v1[0], v1[1]); w.w = cvt_pk_bf16(v1[2], v1[3]);
;                     *(GAS u32x4*)(rowp + bj * HALF) = w;
;                     if (sidx >= 0) { float q = ((v0[0] * v0[0] + v0[1] * v0[1]) + (v0[2] * v0[2] + v0[3] * v0[3])) + ((v1[0] * v1[0] + v1[1] * v1[1]) + (v1[2] * v1[2] + v1[3] * v1[3]));
;                         q += __shfl_xor(q, 16); q += __shfl_xor(q, 32);
;                         if (fq == 0) ss[((size_t)sidx * MROWS + row) * 16 + (colt >> 5) + 4 * bj + wc] = q; } } }
.LBB0_202:
	s_waitcnt lgkmcnt(0)
	v_or_b32_e32 v98, 32, v162
	v_ashrrev_i32_e32 v99, 31, v98
	v_lshl_add_u64 v[100:101], v[98:99], 2, s[2:3]
	v_lshlrev_b64 v[100:101], 10, v[98:99]
	v_lshlrev_b64 v[98:99], 6, v[98:99]
	v_lshl_add_u64 v[100:101], v[132:133], 0, v[100:101]
	s_and_b64 vcc, exec, s[10:11]
	s_nop 1
	v_mov_b32_e32 v102, v208
	v_pk_mul_f32 v[96:97], v[96:97], v[102:103] op_sel_hi:[1,0]
	v_pk_mul_f32 v[94:95], v[94:95], v[102:103] op_sel_hi:[1,0]
	v_pk_mul_f32 v[92:93], v[92:93], v[102:103] op_sel_hi:[1,0]
	v_pk_mul_f32 v[90:91], v[90:91], v[102:103] op_sel_hi:[1,0]
	v_cvt_pk_bf16_f32 v104, v94, v95
	v_cvt_pk_bf16_f32 v105, v96, v97
	v_cvt_pk_bf16_f32 v106, v90, v91
	v_cvt_pk_bf16_f32 v107, v92, v93
	global_store_dwordx4 v[100:101], v[104:107], off
	s_cbranch_vccnz .LBB0_206
	v_mul_f32_e32 v0, v95, v95
	v_mul_f32_e32 v91, v91, v91
	v_fmac_f32_e32 v0, v94, v94
	v_mul_f32_e32 v94, v97, v97
	v_fmac_f32_e32 v91, v90, v90
	v_mul_f32_e32 v90, v93, v93
	v_fmac_f32_e32 v94, v96, v96
	v_fmac_f32_e32 v90, v92, v92
	v_add_f32_e32 v0, v0, v94
	v_add_f32_e32 v90, v91, v90
	v_and_b32_e32 v91, 64, v240
	v_add_f32_e32 v0, v0, v90
	v_xor_b32_e32 v90, 16, v240
	v_add_u32_e32 v91, 64, v91
	v_cmp_lt_i32_e32 vcc, v90, v91
	s_nop 1
	v_cndmask_b32_e32 v90, v240, v90, vcc
	v_lshlrev_b32_e32 v90, 2, v90
	ds_bpermute_b32 v90, v90, v0
	s_waitcnt lgkmcnt(0)
	v_add_f32_e32 v0, v0, v90
	v_xor_b32_e32 v90, 32, v240
	v_cmp_lt_i32_e32 vcc, v90, v91
	s_nop 1
	v_cndmask_b32_e32 v90, v240, v90, vcc
	v_lshlrev_b32_e32 v90, 2, v90
	ds_bpermute_b32 v90, v90, v0
	s_and_saveexec_b64 s[22:23], s[6:7]
	s_cbranch_execz .LBB0_205
	s_add_u32 s24, s44, s20
	s_addc_u32 s25, s45, s21
	v_lshl_add_u64 v[92:93], s[24:25], 0, v[98:99]
	s_lshl_b32 s72, s13, 2
	v_lshl_add_u64 v[92:93], v[92:93], 0, s[72:73]
	s_lshl_b32 s72, s50, 2
	v_lshl_add_u64 v[92:93], v[92:93], 0, s[72:73]
	s_waitcnt lgkmcnt(0)
	v_add_f32_e32 v0, v0, v90
	global_store_dword v[92:93], v0, off

; #define GAS __attribute__((address_space(1)))
; __device__ __forceinline__ unsigned cvt_pk_bf16(float lo, float hi) { f32x2 v = {lo, hi}; bf16x2_t b = __builtin_convertvector(v, bf16x2_t); return __builtin_bit_cast(unsigned, b); }
;     __device__ __forceinline__ void operator()(const f32x4 (&acc)[2][2][4][2], const Unit& u, int wr, int wc, int fr, int fq) const {
;     ...
;             for (int m = 0; m < 4; ++m) { const int row = row0 + ai * HALF + m * 16; const float rs = rs1[row]; GAS bf16_t* rowp = base + (size_t)row * 512 + col0;
; #pragma unroll
;                 for (int bj = 0; bj < 2; ++bj) { const f32x4 v0 = acc[ai][bj][m][0] * rs, v1 = acc[ai][bj][m][1] * rs;
;                     u32x4 w; w.x = cvt_pk_bf16(v0[0], v0[1]); w.y = cvt_pk_bf16(v0[2], v0[3]); w.z = cvt_pk_bf16(v1[0], v1[1]); w.w = cvt_pk_bf16(v1[2], v1[3]);
;                     *(GAS u32x4*)(rowp + bj * HALF) = w;
;                     if (sidx >= 0) { float q = ((v0[0] * v0[0] + v0[1] * v0[1]) + (v0[2] * v0[2] + v0[3] * v0[3])) + ((v1[0] * v1[0] + v1[1] * v1[1]) + (v1[2] * v1[2] + v1[3] * v1[3]));
;                         q += __shfl_xor(q, 16); q += __shfl_xor(q, 32);
;                         if (fq == 0) ss[((size_t)sidx * MROWS + row) * 16 + (colt >> 5) + 4 * bj + wc] = q; } } }
.LBB0_210:
	s_waitcnt lgkmcnt(0)
	v_or_b32_e32 v82, 48, v162
	v_ashrrev_i32_e32 v83, 31, v82
	v_lshl_add_u64 v[84:85], v[82:83], 2, s[2:3]
	v_lshlrev_b64 v[84:85], 10, v[82:83]
	v_lshlrev_b64 v[82:83], 6, v[82:83]
	v_lshl_add_u64 v[84:85], v[132:133], 0, v[84:85]
	s_and_b64 vcc, exec, s[10:11]
	s_nop 1
	v_mov_b32_e32 v86, v209
	v_pk_mul_f32 v[80:81], v[80:81], v[86:87] op_sel_hi:[1,0]
	v_pk_mul_f32 v[78:79], v[78:79], v[86:87] op_sel_hi:[1,0]
	v_pk_mul_f32 v[76:77], v[76:77], v[86:87] op_sel_hi:[1,0]
	v_pk_mul_f32 v[74:75], v[74:75], v[86:87] op_sel_hi:[1,0]
	v_cvt_pk_bf16_f32 v88, v78, v79
	v_cvt_pk_bf16_f32 v89, v80, v81
	v_cvt_pk_bf16_f32 v90, v74, v75
	v_cvt_pk_bf16_f32 v91, v76, v77
	global_store_dwordx4 v[84:85], v[88:91], off
	s_cbranch_vccnz .LBB0_214
	v_mul_f32_e32 v0, v79, v79
	v_mul_f32_e32 v75, v75, v75
	v_fmac_f32_e32 v0, v78, v78
	v_mul_f32_e32 v78, v81, v81
	v_fmac_f32_e32 v75, v74, v74
	v_mul_f32_e32 v74, v77, v77
	v_fmac_f32_e32 v78, v80, v80
	v_fmac_f32_e32 v74, v76, v76
	v_add_f32_e32 v0, v0, v78
	v_add_f32_e32 v74, v75, v74
	v_and_b32_e32 v75, 64, v240
	v_add_f32_e32 v0, v0, v74
	v_xor_b32_e32 v74, 16, v240
	v_add_u32_e32 v75, 64, v75
	v_cmp_lt_i32_e32 vcc, v74, v75
	s_nop 1
	v_cndmask_b32_e32 v74, v240, v74, vcc
	v_lshlrev_b32_e32 v74, 2, v74
	ds_bpermute_b32 v74, v74, v0
	s_waitcnt lgkmcnt(0)
	v_add_f32_e32 v0, v0, v74
	v_xor_b32_e32 v74, 32, v240
	v_cmp_lt_i32_e32 vcc, v74, v75
	s_nop 1
	v_cndmask_b32_e32 v74, v240, v74, vcc
	v_lshlrev_b32_e32 v74, 2, v74
	ds_bpermute_b32 v74, v74, v0
	s_and_saveexec_b64 s[22:23], s[6:7]
	s_cbranch_execz .LBB0_213
	s_add_u32 s24, s44, s20
	s_addc_u32 s25, s45, s21
	v_lshl_add_u64 v[76:77], s[24:25], 0, v[82:83]
	s_lshl_b32 s72, s13, 2
	v_lshl_add_u64 v[76:77], v[76:77], 0, s[72:73]
	s_lshl_b32 s72, s50, 2
	v_lshl_add_u64 v[76:77], v[76:77], 0, s[72:73]
	s_waitcnt lgkmcnt(0)
	v_add_f32_e32 v0, v0, v74
	global_store_dword v[76:77], v0, off

; #define GAS __attribute__((address_space(1)))
; __device__ __forceinline__ unsigned cvt_pk_bf16(float lo, float hi) { f32x2 v = {lo, hi}; bf16x2_t b = __builtin_convertvector(v, bf16x2_t); return __builtin_bit_cast(unsigned, b); }
;     __device__ __forceinline__ void operator()(const f32x4 (&acc)[2][2][4][2], const Unit& u, int wr, int wc, int fr, int fq) const {
;     ...
;             for (int m = 0; m < 4; ++m) { const int row = row0 + ai * HALF + m * 16; const float rs = rs1[row]; GAS bf16_t* rowp = base + (size_t)row * 512 + col0;
; #pragma unroll
;                 for (int bj = 0; bj < 2; ++bj) { const f32x4 v0 = acc[ai][bj][m][0] * rs, v1 = acc[ai][bj][m][1] * rs;
;                     u32x4 w; w.x = cvt_pk_bf16(v0[0], v0[1]); w.y = cvt_pk_bf16(v0[2], v0[3]); w.z = cvt_pk_bf16(v1[0], v1[1]); w.w = cvt_pk_bf16(v1[2], v1[3]);
;                     *(GAS u32x4*)(rowp + bj * HALF) = w;
;                     if (sidx >= 0) { float q = ((v0[0] * v0[0] + v0[1] * v0[1]) + (v0[2] * v0[2] + v0[3] * v0[3])) + ((v1[0] * v1[0] + v1[1] * v1[1]) + (v1[2] * v1[2] + v1[3] * v1[3]));
;                         q += __shfl_xor(q, 16); q += __shfl_xor(q, 32);
;                         if (fq == 0) ss[((size_t)sidx * MROWS + row) * 16 + (colt >> 5) + 4 * bj + wc] = q; } } }
.LBB0_218:
	s_waitcnt lgkmcnt(0)
	v_add_u32_e32 v66, 0x80, v162
	v_ashrrev_i32_e32 v67, 31, v66
	v_lshlrev_b64 v[68:69], 10, v[66:67]
	v_lshlrev_b64 v[66:67], 6, v[66:67]
	v_lshl_add_u64 v[68:69], v[132:133], 0, v[68:69]
	s_and_b64 vcc, exec, s[10:11]
	s_nop 1
	v_mov_b32_e32 v70, v210
	v_pk_mul_f32 v[64:65], v[64:65], v[70:71] op_sel_hi:[1,0]
	v_pk_mul_f32 v[62:63], v[62:63], v[70:71] op_sel_hi:[1,0]
	v_pk_mul_f32 v[60:61], v[60:61], v[70:71] op_sel_hi:[1,0]
	v_pk_mul_f32 v[58:59], v[58:59], v[70:71] op_sel_hi:[1,0]
	v_cvt_pk_bf16_f32 v72, v62, v63
	v_cvt_pk_bf16_f32 v73, v64, v65
	v_cvt_pk_bf16_f32 v74, v58, v59
	v_cvt_pk_bf16_f32 v75, v60, v61
	global_store_dwordx4 v[68:69], v[72:75], off
	s_cbranch_vccnz .LBB0_222
	v_mul_f32_e32 v0, v63, v63
	v_mul_f32_e32 v59, v59, v59
	v_fmac_f32_e32 v0, v62, v62
	v_mul_f32_e32 v62, v65, v65
	v_fmac_f32_e32 v59, v58, v58
	v_mul_f32_e32 v58, v61, v61
	v_fmac_f32_e32 v62, v64, v64
	v_fmac_f32_e32 v58, v60, v60
	v_add_f32_e32 v0, v0, v62
	v_add_f32_e32 v58, v59, v58
	v_and_b32_e32 v59, 64, v240
	v_add_f32_e32 v0, v0, v58
	v_xor_b32_e32 v58, 16, v240
	v_add_u32_e32 v59, 64, v59
	v_cmp_lt_i32_e32 vcc, v58, v59
	s_nop 1
	v_cndmask_b32_e32 v58, v240, v58, vcc
	v_lshlrev_b32_e32 v58, 2, v58
	ds_bpermute_b32 v58, v58, v0
	s_waitcnt lgkmcnt(0)
	v_add_f32_e32 v0, v0, v58
	v_xor_b32_e32 v58, 32, v240
	v_cmp_lt_i32_e32 vcc, v58, v59
	s_nop 1
	v_cndmask_b32_e32 v58, v240, v58, vcc
	v_lshlrev_b32_e32 v58, 2, v58
	ds_bpermute_b32 v58, v58, v0
	s_and_saveexec_b64 s[22:23], s[6:7]
	s_cbranch_execz .LBB0_221
	s_add_u32 s24, s44, s20
	s_addc_u32 s25, s45, s21
	v_lshl_add_u64 v[60:61], s[24:25], 0, v[66:67]
	s_lshl_b32 s72, s13, 2
	v_lshl_add_u64 v[60:61], v[60:61], 0, s[72:73]
	s_lshl_b32 s72, s50, 2
	v_lshl_add_u64 v[60:61], v[60:61], 0, s[72:73]
	s_waitcnt lgkmcnt(0)
	v_add_f32_e32 v0, v0, v58
	global_store_dword v[60:61], v0, off

; #define GAS __attribute__((address_space(1)))
; __device__ __forceinline__ unsigned cvt_pk_bf16(float lo, float hi) { f32x2 v = {lo, hi}; bf16x2_t b = __builtin_convertvector(v, bf16x2_t); return __builtin_bit_cast(unsigned, b); }
;     __device__ __forceinline__ void operator()(const f32x4 (&acc)[2][2][4][2], const Unit& u, int wr, int wc, int fr, int fq) const {
;     ...
;             for (int m = 0; m < 4; ++m) { const int row = row0 + ai * HALF + m * 16; const float rs = rs1[row]; GAS bf16_t* rowp = base + (size_t)row * 512 + col0;
; #pragma unroll
;                 for (int bj = 0; bj < 2; ++bj) { const f32x4 v0 = acc[ai][bj][m][0] * rs, v1 = acc[ai][bj][m][1] * rs;
;                     u32x4 w; w.x = cvt_pk_bf16(v0[0], v0[1]); w.y = cvt_pk_bf16(v0[2], v0[3]); w.z = cvt_pk_bf16(v1[0], v1[1]); w.w = cvt_pk_bf16(v1[2], v1[3]);
;                     *(GAS u32x4*)(rowp + bj * HALF) = w;
;                     if (sidx >= 0) { float q = ((v0[0] * v0[0] + v0[1] * v0[1]) + (v0[2] * v0[2] + v0[3] * v0[3])) + ((v1[0] * v1[0] + v1[1] * v1[1]) + (v1[2] * v1[2] + v1[3] * v1[3]));
;                         q += __shfl_xor(q, 16); q += __shfl_xor(q, 32);
;                         if (fq == 0) ss[((size_t)sidx * MROWS + row) * 16 + (colt >> 5) + 4 * bj + wc] = q; } } }
.LBB0_226:
	s_waitcnt lgkmcnt(0)
	v_add_u32_e32 v50, 0x90, v162
	v_ashrrev_i32_e32 v51, 31, v50
	v_lshlrev_b64 v[52:53], 10, v[50:51]
	v_lshlrev_b64 v[50:51], 6, v[50:51]
	v_lshl_add_u64 v[52:53], v[132:133], 0, v[52:53]
	s_and_b64 vcc, exec, s[10:11]
	s_nop 1
	v_mov_b32_e32 v54, v211
	v_pk_mul_f32 v[48:49], v[48:49], v[54:55] op_sel_hi:[1,0]
	v_pk_mul_f32 v[46:47], v[46:47], v[54:55] op_sel_hi:[1,0]
	v_pk_mul_f32 v[44:45], v[44:45], v[54:55] op_sel_hi:[1,0]
	v_pk_mul_f32 v[42:43], v[42:43], v[54:55] op_sel_hi:[1,0]
	v_cvt_pk_bf16_f32 v56, v46, v47
	v_cvt_pk_bf16_f32 v57, v48, v49
	v_cvt_pk_bf16_f32 v58, v42, v43
	v_cvt_pk_bf16_f32 v59, v44, v45
	global_store_dwordx4 v[52:53], v[56:59], off
	s_cbranch_vccnz .LBB0_230
	v_mul_f32_e32 v0, v47, v47
	v_mul_f32_e32 v43, v43, v43
	v_fmac_f32_e32 v0, v46, v46
	v_mul_f32_e32 v46, v49, v49
	v_fmac_f32_e32 v43, v42, v42
	v_mul_f32_e32 v42, v45, v45
	v_fmac_f32_e32 v46, v48, v48
	v_fmac_f32_e32 v42, v44, v44
	v_add_f32_e32 v0, v0, v46
	v_add_f32_e32 v42, v43, v42
	v_and_b32_e32 v43, 64, v240
	v_add_f32_e32 v0, v0, v42
	v_xor_b32_e32 v42, 16, v240
	v_add_u32_e32 v43, 64, v43
	v_cmp_lt_i32_e32 vcc, v42, v43
	s_nop 1
	v_cndmask_b32_e32 v42, v240, v42, vcc
	v_lshlrev_b32_e32 v42, 2, v42
	ds_bpermute_b32 v42, v42, v0
	s_waitcnt lgkmcnt(0)
	v_add_f32_e32 v0, v0, v42
	v_xor_b32_e32 v42, 32, v240
	v_cmp_lt_i32_e32 vcc, v42, v43
	s_nop 1
	v_cndmask_b32_e32 v42, v240, v42, vcc
	v_lshlrev_b32_e32 v42, 2, v42
	ds_bpermute_b32 v42, v42, v0
	s_and_saveexec_b64 s[22:23], s[6:7]
	s_cbranch_execz .LBB0_229
	s_add_u32 s24, s44, s20
	s_addc_u32 s25, s45, s21
	v_lshl_add_u64 v[44:45], s[24:25], 0, v[50:51]
	s_lshl_b32 s72, s13, 2
	v_lshl_add_u64 v[44:45], v[44:45], 0, s[72:73]
	s_lshl_b32 s72, s50, 2
	v_lshl_add_u64 v[44:45], v[44:45], 0, s[72:73]
	s_waitcnt lgkmcnt(0)
	v_add_f32_e32 v0, v0, v42
	global_store_dword v[44:45], v0, off

; #define GAS __attribute__((address_space(1)))
; __device__ __forceinline__ unsigned cvt_pk_bf16(float lo, float hi) { f32x2 v = {lo, hi}; bf16x2_t b = __builtin_convertvector(v, bf16x2_t); return __builtin_bit_cast(unsigned, b); }
;     __device__ __forceinline__ void operator()(const f32x4 (&acc)[2][2][4][2], const Unit& u, int wr, int wc, int fr, int fq) const {
;     ...
;             for (int m = 0; m < 4; ++m) { const int row = row0 + ai * HALF + m * 16; const float rs = rs1[row]; GAS bf16_t* rowp = base + (size_t)row * 512 + col0;
; #pragma unroll
;                 for (int bj = 0; bj < 2; ++bj) { const f32x4 v0 = acc[ai][bj][m][0] * rs, v1 = acc[ai][bj][m][1] * rs;
;                     u32x4 w; w.x = cvt_pk_bf16(v0[0], v0[1]); w.y = cvt_pk_bf16(v0[2], v0[3]); w.z = cvt_pk_bf16(v1[0], v1[1]); w.w = cvt_pk_bf16(v1[2], v1[3]);
;                     *(GAS u32x4*)(rowp + bj * HALF) = w;
;                     if (sidx >= 0) { float q = ((v0[0] * v0[0] + v0[1] * v0[1]) + (v0[2] * v0[2] + v0[3] * v0[3])) + ((v1[0] * v1[0] + v1[1] * v1[1]) + (v1[2] * v1[2] + v1[3] * v1[3]));
;                         q += __shfl_xor(q, 16); q += __shfl_xor(q, 32);
;                         if (fq == 0) ss[((size_t)sidx * MROWS + row) * 16 + (colt >> 5) + 4 * bj + wc] = q; } } }
.LBB0_234:
	s_waitcnt lgkmcnt(0)
	v_add_u32_e32 v34, 0xa0, v162
	v_ashrrev_i32_e32 v35, 31, v34
	v_lshlrev_b64 v[36:37], 10, v[34:35]
	v_lshlrev_b64 v[34:35], 6, v[34:35]
	v_lshl_add_u64 v[36:37], v[132:133], 0, v[36:37]
	s_and_b64 vcc, exec, s[10:11]
	s_nop 1
	v_mov_b32_e32 v38, v212
	v_pk_mul_f32 v[32:33], v[32:33], v[38:39] op_sel_hi:[1,0]
	v_pk_mul_f32 v[30:31], v[30:31], v[38:39] op_sel_hi:[1,0]
	v_pk_mul_f32 v[28:29], v[28:29], v[38:39] op_sel_hi:[1,0]
	v_pk_mul_f32 v[26:27], v[26:27], v[38:39] op_sel_hi:[1,0]
	v_cvt_pk_bf16_f32 v40, v30, v31
	v_cvt_pk_bf16_f32 v41, v32, v33
	v_cvt_pk_bf16_f32 v42, v26, v27
	v_cvt_pk_bf16_f32 v43, v28, v29
	global_store_dwordx4 v[36:37], v[40:43], off
	s_cbranch_vccnz .LBB0_238
	v_mul_f32_e32 v0, v31, v31
	v_mul_f32_e32 v27, v27, v27
	v_fmac_f32_e32 v0, v30, v30
	v_mul_f32_e32 v30, v33, v33
	v_fmac_f32_e32 v27, v26, v26
	v_mul_f32_e32 v26, v29, v29
	v_fmac_f32_e32 v30, v32, v32
	v_fmac_f32_e32 v26, v28, v28
	v_add_f32_e32 v0, v0, v30
	v_add_f32_e32 v26, v27, v26
	v_and_b32_e32 v27, 64, v240
	v_add_f32_e32 v0, v0, v26
	v_xor_b32_e32 v26, 16, v240
	v_add_u32_e32 v27, 64, v27
	v_cmp_lt_i32_e32 vcc, v26, v27
	s_nop 1
	v_cndmask_b32_e32 v26, v240, v26, vcc
	v_lshlrev_b32_e32 v26, 2, v26
	ds_bpermute_b32 v26, v26, v0
	s_waitcnt lgkmcnt(0)
	v_add_f32_e32 v0, v0, v26
	v_xor_b32_e32 v26, 32, v240
	v_cmp_lt_i32_e32 vcc, v26, v27
	s_nop 1
	v_cndmask_b32_e32 v26, v240, v26, vcc
	v_lshlrev_b32_e32 v26, 2, v26
	ds_bpermute_b32 v26, v26, v0
	s_and_saveexec_b64 s[22:23], s[6:7]
	s_cbranch_execz .LBB0_237
	s_add_u32 s24, s44, s20
	s_addc_u32 s25, s45, s21
	v_lshl_add_u64 v[28:29], s[24:25], 0, v[34:35]
	s_lshl_b32 s72, s13, 2
	v_lshl_add_u64 v[28:29], v[28:29], 0, s[72:73]
	s_lshl_b32 s72, s50, 2
	v_lshl_add_u64 v[28:29], v[28:29], 0, s[72:73]
	s_waitcnt lgkmcnt(0)
	v_add_f32_e32 v0, v0, v26
	global_store_dword v[28:29], v0, off

; #define GAS __attribute__((address_space(1)))
; __device__ __forceinline__ unsigned cvt_pk_bf16(float lo, float hi) { f32x2 v = {lo, hi}; bf16x2_t b = __builtin_convertvector(v, bf16x2_t); return __builtin_bit_cast(unsigned, b); }
;     __device__ __forceinline__ void operator()(const f32x4 (&acc)[2][2][4][2], const Unit& u, int wr, int wc, int fr, int fq) const {
;     ...
;             for (int m = 0; m < 4; ++m) { const int row = row0 + ai * HALF + m * 16; const float rs = rs1[row]; GAS bf16_t* rowp = base + (size_t)row * 512 + col0;
; #pragma unroll
;                 for (int bj = 0; bj < 2; ++bj) { const f32x4 v0 = acc[ai][bj][m][0] * rs, v1 = acc[ai][bj][m][1] * rs;
;                     u32x4 w; w.x = cvt_pk_bf16(v0[0], v0[1]); w.y = cvt_pk_bf16(v0[2], v0[3]); w.z = cvt_pk_bf16(v1[0], v1[1]); w.w = cvt_pk_bf16(v1[2], v1[3]);
;                     *(GAS u32x4*)(rowp + bj * HALF) = w;
;                     if (sidx >= 0) { float q = ((v0[0] * v0[0] + v0[1] * v0[1]) + (v0[2] * v0[2] + v0[3] * v0[3])) + ((v1[0] * v1[0] + v1[1] * v1[1]) + (v1[2] * v1[2] + v1[3] * v1[3]));
;                         q += __shfl_xor(q, 16); q += __shfl_xor(q, 32);
;                         if (fq == 0) ss[((size_t)sidx * MROWS + row) * 16 + (colt >> 5) + 4 * bj + wc] = q; } } }
.LBB0_242:
	s_waitcnt lgkmcnt(0)
	v_add_u32_e32 v18, 0xb0, v162
	v_ashrrev_i32_e32 v19, 31, v18
	v_lshlrev_b64 v[20:21], 10, v[18:19]
	v_lshlrev_b64 v[18:19], 6, v[18:19]
	v_lshl_add_u64 v[20:21], v[132:133], 0, v[20:21]
	s_and_b64 vcc, exec, s[10:11]
	s_nop 1
	v_mov_b32_e32 v22, v213
	v_pk_mul_f32 v[16:17], v[16:17], v[22:23] op_sel_hi:[1,0]
	v_pk_mul_f32 v[14:15], v[14:15], v[22:23] op_sel_hi:[1,0]
	v_pk_mul_f32 v[12:13], v[12:13], v[22:23] op_sel_hi:[1,0]
	v_pk_mul_f32 v[10:11], v[10:11], v[22:23] op_sel_hi:[1,0]
	v_cvt_pk_bf16_f32 v24, v14, v15
	v_cvt_pk_bf16_f32 v25, v16, v17
	v_cvt_pk_bf16_f32 v26, v10, v11
	v_cvt_pk_bf16_f32 v27, v12, v13
	global_store_dwordx4 v[20:21], v[24:27], off
	s_cbranch_vccnz .LBB0_246
	v_mul_f32_e32 v0, v15, v15
	v_mul_f32_e32 v11, v11, v11
	v_fmac_f32_e32 v0, v14, v14
	v_mul_f32_e32 v14, v17, v17
	v_fmac_f32_e32 v11, v10, v10
	v_mul_f32_e32 v10, v13, v13
	v_fmac_f32_e32 v14, v16, v16
	v_fmac_f32_e32 v10, v12, v12
	v_add_f32_e32 v0, v0, v14
	v_add_f32_e32 v10, v11, v10
	v_and_b32_e32 v11, 64, v240
	v_add_f32_e32 v0, v0, v10
	v_xor_b32_e32 v10, 16, v240
	v_add_u32_e32 v11, 64, v11
	v_cmp_lt_i32_e32 vcc, v10, v11
	s_nop 1
	v_cndmask_b32_e32 v10, v240, v10, vcc
	v_lshlrev_b32_e32 v10, 2, v10
	ds_bpermute_b32 v10, v10, v0
	s_waitcnt lgkmcnt(0)
	v_add_f32_e32 v0, v0, v10
	v_xor_b32_e32 v10, 32, v240
	v_cmp_lt_i32_e32 vcc, v10, v11
	s_nop 1
	v_cndmask_b32_e32 v10, v240, v10, vcc
	v_lshlrev_b32_e32 v10, 2, v10
	ds_bpermute_b32 v10, v10, v0
	s_and_saveexec_b64 s[22:23], s[6:7]
	s_cbranch_execz .LBB0_245
	s_add_u32 s24, s44, s20
	s_addc_u32 s25, s45, s21
	v_lshl_add_u64 v[12:13], s[24:25], 0, v[18:19]
	s_lshl_b32 s72, s13, 2
	v_lshl_add_u64 v[12:13], v[12:13], 0, s[72:73]
	s_lshl_b32 s72, s50, 2
	v_lshl_add_u64 v[12:13], v[12:13], 0, s[72:73]
	s_waitcnt lgkmcnt(0)
	v_add_f32_e32 v0, v0, v10
	global_store_dword v[12:13], v0, off

; #define GAS __attribute__((address_space(1)))
; __device__ __forceinline__ unsigned cvt_pk_bf16(float lo, float hi) { f32x2 v = {lo, hi}; bf16x2_t b = __builtin_convertvector(v, bf16x2_t); return __builtin_bit_cast(unsigned, b); }
; __device__ __forceinline__ float bf_lo(unsigned u) { return __uint_as_float(u << 16); }
; __device__ __forceinline__ float bf_hi(unsigned u) { return __uint_as_float(u & 0xffff0000u); }
;     __device__ __forceinline__ void operator()(f32x4 (&acc)[2][2][4][2], const Unit& u, int wr, int wc, int fr, int fq) const {
;         const int br = u.pm >> 7, pm = u.pm & 127, pn = u.pn & 3;
;         const int row0 = pm * BM + wr * 64 + fr; const int col0 = pn * BM + wc * 32 + 8 * fq;
; #pragma unroll
;         for (int ai = 0; ai < 2; ++ai)
; #pragma unroll
;             for (int m = 0; m < 4; ++m) { const int row = row0 + ai * HALF + m * 16; const GAS bf16_t* gp = ((br < 2) ? g01 + (size_t)br * MROWS * 1024 : g2) + (size_t)row * 1024 + col0; const GAS bf16_t* gn = ((br == 0) ? g01 + (size_t)MROWS * 1024 : g2) + (size_t)row * 1024 + col0; GAS bf16_t* mp = Mg + (size_t)row * 1024 + col0;
; #pragma unroll
;                 for (int bj = 0; bj < 2; ++bj) { const u32x4 g = *(const GAS u32x4*)(gp + bj * HALF);
;                     f32x4 s0 = {bf_lo(g.x), bf_hi(g.x), bf_lo(g.y), bf_hi(g.y)}, s1 = {bf_lo(g.z), bf_hi(g.z), bf_lo(g.w), bf_hi(g.w)};
;                     if (br < 2) { const u32x4 h = *(const GAS u32x4*)(gn + bj * HALF);
;                         const f32x4 d0 = {bf_lo(h.x), bf_hi(h.x), bf_lo(h.y), bf_hi(h.y)}, d1 = {bf_lo(h.z), bf_hi(h.z), bf_lo(h.w), bf_hi(h.w)};
; #pragma unroll
;                         for (int e = 0; e < 4; ++e) { s0[e] *= __builtin_amdgcn_rcpf(fmaxf(d0[e], 1e-30f)); s1[e] *= __builtin_amdgcn_rcpf(fmaxf(d1[e], 1e-30f)); }
;                         acc[ai][bj][m][0] *= s0; acc[ai][bj][m][1] *= s1;
;                     } else { const f32x4 v0 = acc[ai][bj][m][0] * s0, v1 = acc[ai][bj][m][1] * s1;
;                         u32x4 w; w.x = cvt_pk_bf16(v0[0], v0[1]); w.y = cvt_pk_bf16(v0[2], v0[3]); w.z = cvt_pk_bf16(v1[0], v1[1]); w.w = cvt_pk_bf16(v1[2], v1[3]);
;                         *(GAS u32x4*)(mp + bj * HALF) = w; } } }
.LBB0_517:
	s_lshl_b32 s7, s8, 8
	s_and_b32 s7, s7, 0x7f00
	v_add_u32_e32 v2, s7, v158
	s_lshl_b32 s7, s24, 8
	s_ashr_i32 s6, s8, 7
	s_and_b32 s7, s7, 0x300
	s_cmp_gt_i32 s6, 1
	v_or_b32_e32 v0, s7, v160
	s_cselect_b64 s[24:25], -1, 0
	s_ashr_i32 s7, s6, 31
	s_lshl_b64 s[20:21], s[6:7], 26
	s_add_u32 s7, s29, s20
	s_addc_u32 s11, s28, s21
	s_cmp_lt_i32 s6, 2
	v_ashrrev_i32_e32 v3, 31, v2
	s_cselect_b32 s22, s7, s39
	s_cselect_b32 s23, s11, s40
	v_lshlrev_b64 v[148:149], 11, v[2:3]
	v_lshl_add_u64 v[144:145], s[22:23], 0, v[148:149]
	v_lshlrev_b32_e32 v0, 1, v0
	v_lshl_add_u64 v[146:147], v[144:145], 0, v[0:1]
	v_lshl_add_u64 v[144:145], s[2:3], 0, v[148:149]
	s_cmpk_lt_u32 s8, 0x80
	s_mov_b64 s[6:7], -1
	v_lshl_add_u64 v[144:145], v[144:145], 0, v[0:1]
	s_cselect_b32 s21, s44, s40
	s_cselect_b32 s20, s43, s39
	s_and_b64 vcc, exec, s[24:25]
	v_lshlrev_b32_e32 v198, 11, v2
	v_add_u32_e32 v198, v198, v0
	global_load_dwordx4 v[200:203], v198, s[22:23]
	global_load_dwordx4 v[204:207], v198, s[20:21]
	global_load_dwordx4 v[208:211], v198, s[22:23] offset:256
	global_load_dwordx4 v[212:215], v198, s[20:21] offset:256
	v_add_u32_e32 v199, 0x8000, v198
	global_load_dwordx4 v[216:219], v199, s[22:23]
	global_load_dwordx4 v[220:223], v199, s[20:21]
	global_load_dwordx4 v[224:227], v199, s[22:23] offset:256
	global_load_dwordx4 v[228:231], v199, s[20:21] offset:256
	s_waitcnt vmcnt(0)
	s_nop 1
	v_mov_b32_e32 v162, v200
	v_mov_b32_e32 v163, v201
	v_mov_b32_e32 v164, v202
	v_mov_b32_e32 v165, v203
	v_lshlrev_b32_e32 v156, 16, v162
	v_and_b32_e32 v157, 0xffff0000, v162
	v_lshlrev_b32_e32 v152, 16, v163
	v_and_b32_e32 v153, 0xffff0000, v163
	v_lshlrev_b32_e32 v154, 16, v164
	v_and_b32_e32 v155, 0xffff0000, v164
	v_lshlrev_b32_e32 v150, 16, v165
	v_and_b32_e32 v151, 0xffff0000, v165
	s_cbranch_vccz .LBB0_519
	v_pk_mul_f32 v[164:165], v[130:131], v[152:153]
	v_pk_mul_f32 v[162:163], v[128:129], v[156:157]
	v_pk_mul_f32 v[192:193], v[126:127], v[150:151]
	v_pk_mul_f32 v[194:195], v[124:125], v[154:155]
	v_cvt_pk_bf16_f32 v162, v162, v163
	v_cvt_pk_bf16_f32 v163, v164, v165
	v_cvt_pk_bf16_f32 v164, v194, v195
	v_cvt_pk_bf16_f32 v165, v192, v193
	global_store_dwordx4 v[144:145], v[162:165], off
	s_mov_b64 s[6:7], 0
.LBB0_519:
	v_lshl_add_u64 v[148:149], s[20:21], 0, v[148:149]
	s_andn2_b64 vcc, exec, s[6:7]
	v_lshl_add_u64 v[148:149], v[148:149], 0, v[0:1]
	s_cbranch_vccnz .LBB0_521
	s_nop 1
	v_mov_b32_e32 v162, v204
	v_mov_b32_e32 v163, v205
	v_mov_b32_e32 v164, v206
	v_mov_b32_e32 v165, v207
	v_lshlrev_b32_e32 v193, 16, v163
	v_and_b32_e32 v194, 0xffff0000, v163
	v_lshlrev_b32_e32 v163, 16, v164
	v_max_f32_e32 v163, v163, v163
	v_lshlrev_b32_e32 v182, 16, v162
	v_and_b32_e32 v192, 0xffff0000, v162
	v_max_f32_e32 v163, 0xda24260, v163
	v_and_b32_e32 v195, 0xffff0000, v164
	v_max_f32_e32 v162, v182, v182
	v_rcp_f32_e32 v164, v163
	v_max_f32_e32 v163, v192, v192
	v_max_f32_e32 v162, 0xda24260, v162
	v_max_f32_e32 v163, 0xda24260, v163
	v_rcp_f32_e32 v162, v162
	v_rcp_f32_e32 v163, v163
	v_lshlrev_b32_e32 v196, 16, v165
	v_and_b32_e32 v197, 0xffff0000, v165
	v_pk_mul_f32 v[156:157], v[162:163], v[156:157]
	v_max_f32_e32 v162, v195, v195
	v_max_f32_e32 v162, 0xda24260, v162
	v_rcp_f32_e32 v165, v162
	v_max_f32_e32 v163, v196, v196
	v_max_f32_e32 v163, 0xda24260, v163
	v_max_f32_e32 v162, v193, v193
	v_pk_mul_f32 v[154:155], v[164:165], v[154:155]
	v_rcp_f32_e32 v164, v163
	v_max_f32_e32 v163, v194, v194
	v_max_f32_e32 v162, 0xda24260, v162
	v_max_f32_e32 v163, 0xda24260, v163
	v_rcp_f32_e32 v162, v162
	v_rcp_f32_e32 v163, v163
	v_pk_mul_f32 v[128:129], v[128:129], v[156:157]
	v_pk_mul_f32 v[124:125], v[124:125], v[154:155]
	v_pk_mul_f32 v[152:153], v[162:163], v[152:153]
	v_max_f32_e32 v162, v197, v197
	v_max_f32_e32 v162, 0xda24260, v162
	v_rcp_f32_e32 v165, v162
	v_pk_mul_f32 v[130:131], v[130:131], v[152:153]
	v_pk_mul_f32 v[150:151], v[164:165], v[150:151]
	s_nop 0
	v_pk_mul_f32 v[126:127], v[126:127], v[150:151]
.LBB0_521:
	v_cndmask_b32_e64 v146, 0, 1, s[24:25]
	v_cmp_ne_u32_e64 s[6:7], 1, v146
	s_andn2_b64 vcc, exec, s[24:25]
	s_mov_b64 s[24:25], -1
	s_nop 1
	v_mov_b32_e32 v162, v208
	v_mov_b32_e32 v163, v209
	v_mov_b32_e32 v164, v210
	v_mov_b32_e32 v165, v211
	v_lshlrev_b32_e32 v154, 16, v162
	v_and_b32_e32 v155, 0xffff0000, v162
	v_lshlrev_b32_e32 v150, 16, v163
	v_and_b32_e32 v151, 0xffff0000, v163
	v_lshlrev_b32_e32 v152, 16, v164
	v_and_b32_e32 v153, 0xffff0000, v164
	v_lshlrev_b32_e32 v146, 16, v165
	v_and_b32_e32 v147, 0xffff0000, v165
	s_cbranch_vccnz .LBB0_523
	v_pk_mul_f32 v[156:157], v[98:99], v[150:151]
	v_pk_mul_f32 v[162:163], v[96:97], v[154:155]
	v_pk_mul_f32 v[192:193], v[94:95], v[146:147]
	v_pk_mul_f32 v[164:165], v[92:93], v[152:153]
	v_cvt_pk_bf16_f32 v162, v162, v163
	v_cvt_pk_bf16_f32 v163, v156, v157
	v_cvt_pk_bf16_f32 v164, v164, v165
	v_cvt_pk_bf16_f32 v165, v192, v193
	s_mov_b64 s[24:25], 0
	global_store_dwordx4 v[144:145], v[162:165], off offset:256
; #define GAS __attribute__((address_space(1)))
; __device__ __forceinline__ float bf_lo(unsigned u) { return __uint_as_float(u << 16); }
; __device__ __forceinline__ float bf_hi(unsigned u) { return __uint_as_float(u & 0xffff0000u); }
;     __device__ __forceinline__ void operator()(f32x4 (&acc)[2][2][4][2], const Unit& u, int wr, int wc, int fr, int fq) const {
;     ...
;             for (int m = 0; m < 4; ++m) { const int row = row0 + ai * HALF + m * 16; const GAS bf16_t* gp = ((br < 2) ? g01 + (size_t)br * MROWS * 1024 : g2) + (size_t)row * 1024 + col0; const GAS bf16_t* gn = ((br == 0) ? g01 + (size_t)MROWS * 1024 : g2) + (size_t)row * 1024 + col0; GAS bf16_t* mp = Mg + (size_t)row * 1024 + col0;
; #pragma unroll
;                 for (int bj = 0; bj < 2; ++bj) { const u32x4 g = *(const GAS u32x4*)(gp + bj * HALF);
;                     f32x4 s0 = {bf_lo(g.x), bf_hi(g.x), bf_lo(g.y), bf_hi(g.y)}, s1 = {bf_lo(g.z), bf_hi(g.z), bf_lo(g.w), bf_hi(g.w)};
;                     if (br < 2) { const u32x4 h = *(const GAS u32x4*)(gn + bj * HALF);
;                         const f32x4 d0 = {bf_lo(h.x), bf_hi(h.x), bf_lo(h.y), bf_hi(h.y)}, d1 = {bf_lo(h.z), bf_hi(h.z), bf_lo(h.w), bf_hi(h.w)};
; #pragma unroll
;                         for (int e = 0; e < 4; ++e) { s0[e] *= __builtin_amdgcn_rcpf(fmaxf(d0[e], 1e-30f)); s1[e] *= __builtin_amdgcn_rcpf(fmaxf(d1[e], 1e-30f)); }
;                         acc[ai][bj][m][0] *= s0; acc[ai][bj][m][1] *= s1;
.LBB0_523:
	s_andn2_b64 vcc, exec, s[24:25]
	s_cbranch_vccnz .LBB0_525
	s_nop 1
	v_mov_b32_e32 v162, v212
	v_mov_b32_e32 v163, v213
	v_mov_b32_e32 v164, v214
	v_mov_b32_e32 v165, v215
	v_lshlrev_b32_e32 v148, 16, v164
	v_and_b32_e32 v149, 0xffff0000, v164
	v_max_f32_e32 v148, v148, v148
	v_max_f32_e32 v149, v149, v149
	v_lshlrev_b32_e32 v144, 16, v162
	v_and_b32_e32 v145, 0xffff0000, v162
	v_max_f32_e32 v148, 0xda24260, v148
	v_max_f32_e32 v149, 0xda24260, v149
	v_max_f32_e32 v144, v144, v144
	v_rcp_f32_e32 v148, v148
	v_max_f32_e32 v145, v145, v145
	v_rcp_f32_e32 v149, v149
	v_max_f32_e32 v144, 0xda24260, v144
	v_max_f32_e32 v145, 0xda24260, v145
	v_rcp_f32_e32 v144, v144
	v_rcp_f32_e32 v145, v145
	v_lshlrev_b32_e32 v162, 16, v165
	v_pk_mul_f32 v[148:149], v[148:149], v[152:153]
	v_max_f32_e32 v153, v162, v162
	v_lshlrev_b32_e32 v156, 16, v163
	v_and_b32_e32 v157, 0xffff0000, v163
	v_max_f32_e32 v153, 0xda24260, v153
	v_pk_mul_f32 v[144:145], v[144:145], v[154:155]
	v_max_f32_e32 v152, v156, v156
	v_rcp_f32_e32 v154, v153
	v_max_f32_e32 v153, v157, v157
	v_max_f32_e32 v152, 0xda24260, v152
	v_max_f32_e32 v153, 0xda24260, v153
	v_rcp_f32_e32 v152, v152
	v_rcp_f32_e32 v153, v153
	v_and_b32_e32 v163, 0xffff0000, v165
	v_pk_mul_f32 v[96:97], v[96:97], v[144:145]
	v_pk_mul_f32 v[92:93], v[92:93], v[148:149]
	v_pk_mul_f32 v[150:151], v[152:153], v[150:151]
	v_max_f32_e32 v152, v163, v163
	v_max_f32_e32 v152, 0xda24260, v152
	v_rcp_f32_e32 v155, v152
	v_pk_mul_f32 v[98:99], v[98:99], v[150:151]
	v_pk_mul_f32 v[146:147], v[154:155], v[146:147]
	s_nop 0
	v_pk_mul_f32 v[94:95], v[94:95], v[146:147]
.LBB0_525:
	v_or_b32_e32 v144, 16, v2
	v_ashrrev_i32_e32 v145, 31, v144
	v_lshlrev_b64 v[148:149], 11, v[144:145]
	v_lshl_add_u64 v[144:145], s[22:23], 0, v[148:149]
	v_lshl_add_u64 v[146:147], v[144:145], 0, v[0:1]
	v_lshl_add_u64 v[144:145], s[2:3], 0, v[148:149]
	s_and_b64 vcc, exec, s[6:7]
	v_lshl_add_u64 v[144:145], v[144:145], 0, v[0:1]
	s_mov_b64 s[24:25], -1
	s_nop 1
	v_mov_b32_e32 v162, v216
	v_mov_b32_e32 v163, v217
	v_mov_b32_e32 v164, v218
	v_mov_b32_e32 v165, v219
	v_lshlrev_b32_e32 v156, 16, v162
	v_and_b32_e32 v157, 0xffff0000, v162
	v_lshlrev_b32_e32 v152, 16, v163
	v_and_b32_e32 v153, 0xffff0000, v163
	v_lshlrev_b32_e32 v154, 16, v164
	v_and_b32_e32 v155, 0xffff0000, v164
	v_lshlrev_b32_e32 v150, 16, v165
	v_and_b32_e32 v151, 0xffff0000, v165
	s_cbranch_vccnz .LBB0_527
	v_pk_mul_f32 v[164:165], v[122:123], v[152:153]
	v_pk_mul_f32 v[162:163], v[120:121], v[156:157]
	v_pk_mul_f32 v[192:193], v[118:119], v[150:151]
	v_pk_mul_f32 v[194:195], v[116:117], v[154:155]
	v_cvt_pk_bf16_f32 v162, v162, v163
	v_cvt_pk_bf16_f32 v163, v164, v165
	v_cvt_pk_bf16_f32 v164, v194, v195
	v_cvt_pk_bf16_f32 v165, v192, v193
	s_mov_b64 s[24:25], 0
	global_store_dwordx4 v[144:145], v[162:165], off
.LBB0_527:
	v_lshl_add_u64 v[148:149], s[20:21], 0, v[148:149]
	s_andn2_b64 vcc, exec, s[24:25]
	v_lshl_add_u64 v[148:149], v[148:149], 0, v[0:1]
	s_cbranch_vccnz .LBB0_529
	s_nop 1
	v_mov_b32_e32 v162, v220
	v_mov_b32_e32 v163, v221
	v_mov_b32_e32 v164, v222
	v_mov_b32_e32 v165, v223
	v_lshlrev_b32_e32 v193, 16, v163
	v_and_b32_e32 v194, 0xffff0000, v163
	v_lshlrev_b32_e32 v163, 16, v164
	v_max_f32_e32 v163, v163, v163
	v_lshlrev_b32_e32 v182, 16, v162
	v_and_b32_e32 v192, 0xffff0000, v162
	v_max_f32_e32 v163, 0xda24260, v163
	v_and_b32_e32 v195, 0xffff0000, v164
	v_max_f32_e32 v162, v182, v182
	v_rcp_f32_e32 v164, v163
	v_max_f32_e32 v163, v192, v192
	v_max_f32_e32 v162, 0xda24260, v162
	v_max_f32_e32 v163, 0xda24260, v163
	v_rcp_f32_e32 v162, v162
	v_rcp_f32_e32 v163, v163
	v_lshlrev_b32_e32 v196, 16, v165
	v_and_b32_e32 v197, 0xffff0000, v165
	v_pk_mul_f32 v[156:157], v[162:163], v[156:157]
	v_max_f32_e32 v162, v195, v195
	v_max_f32_e32 v162, 0xda24260, v162
	v_rcp_f32_e32 v165, v162
	v_max_f32_e32 v163, v196, v196
	v_max_f32_e32 v163, 0xda24260, v163
	v_max_f32_e32 v162, v193, v193
	v_pk_mul_f32 v[154:155], v[164:165], v[154:155]
	v_rcp_f32_e32 v164, v163
	v_max_f32_e32 v163, v194, v194
	v_max_f32_e32 v162, 0xda24260, v162
	v_max_f32_e32 v163, 0xda24260, v163
	v_rcp_f32_e32 v162, v162
	v_rcp_f32_e32 v163, v163
	v_pk_mul_f32 v[120:121], v[120:121], v[156:157]
	v_pk_mul_f32 v[116:117], v[116:117], v[154:155]
	v_pk_mul_f32 v[152:153], v[162:163], v[152:153]
	v_max_f32_e32 v162, v197, v197
	v_max_f32_e32 v162, 0xda24260, v162
	v_rcp_f32_e32 v165, v162
	v_pk_mul_f32 v[122:123], v[122:123], v[152:153]
	v_pk_mul_f32 v[150:151], v[164:165], v[150:151]
	s_nop 0
	v_pk_mul_f32 v[118:119], v[118:119], v[150:151]
.LBB0_529:
	s_and_b64 vcc, exec, s[6:7]
	s_mov_b64 s[24:25], -1
	s_nop 1
	v_mov_b32_e32 v162, v224
	v_mov_b32_e32 v163, v225
	v_mov_b32_e32 v164, v226
	v_mov_b32_e32 v165, v227
	v_lshlrev_b32_e32 v154, 16, v162
	v_and_b32_e32 v155, 0xffff0000, v162
	v_lshlrev_b32_e32 v150, 16, v163
	v_and_b32_e32 v151, 0xffff0000, v163
	v_lshlrev_b32_e32 v152, 16, v164
	v_and_b32_e32 v153, 0xffff0000, v164
	v_lshlrev_b32_e32 v146, 16, v165
	v_and_b32_e32 v147, 0xffff0000, v165
	s_cbranch_vccnz .LBB0_531
	v_pk_mul_f32 v[156:157], v[90:91], v[150:151]
	v_pk_mul_f32 v[162:163], v[88:89], v[154:155]
	v_pk_mul_f32 v[192:193], v[86:87], v[146:147]
	v_pk_mul_f32 v[164:165], v[84:85], v[152:153]
	v_cvt_pk_bf16_f32 v162, v162, v163
	v_cvt_pk_bf16_f32 v163, v156, v157
	v_cvt_pk_bf16_f32 v164, v164, v165
	v_cvt_pk_bf16_f32 v165, v192, v193
	s_mov_b64 s[24:25], 0
	global_store_dwordx4 v[144:145], v[162:165], off offset:256
; #define GAS __attribute__((address_space(1)))
; __device__ __forceinline__ float bf_lo(unsigned u) { return __uint_as_float(u << 16); }
; __device__ __forceinline__ float bf_hi(unsigned u) { return __uint_as_float(u & 0xffff0000u); }
;     __device__ __forceinline__ void operator()(f32x4 (&acc)[2][2][4][2], const Unit& u, int wr, int wc, int fr, int fq) const {
;     ...
;             for (int m = 0; m < 4; ++m) { const int row = row0 + ai * HALF + m * 16; const GAS bf16_t* gp = ((br < 2) ? g01 + (size_t)br * MROWS * 1024 : g2) + (size_t)row * 1024 + col0; const GAS bf16_t* gn = ((br == 0) ? g01 + (size_t)MROWS * 1024 : g2) + (size_t)row * 1024 + col0; GAS bf16_t* mp = Mg + (size_t)row * 1024 + col0;
; #pragma unroll
;                 for (int bj = 0; bj < 2; ++bj) { const u32x4 g = *(const GAS u32x4*)(gp + bj * HALF);
;                     f32x4 s0 = {bf_lo(g.x), bf_hi(g.x), bf_lo(g.y), bf_hi(g.y)}, s1 = {bf_lo(g.z), bf_hi(g.z), bf_lo(g.w), bf_hi(g.w)};
;                     if (br < 2) { const u32x4 h = *(const GAS u32x4*)(gn + bj * HALF);
;                         const f32x4 d0 = {bf_lo(h.x), bf_hi(h.x), bf_lo(h.y), bf_hi(h.y)}, d1 = {bf_lo(h.z), bf_hi(h.z), bf_lo(h.w), bf_hi(h.w)};
; #pragma unroll
;                         for (int e = 0; e < 4; ++e) { s0[e] *= __builtin_amdgcn_rcpf(fmaxf(d0[e], 1e-30f)); s1[e] *= __builtin_amdgcn_rcpf(fmaxf(d1[e], 1e-30f)); }
;                         acc[ai][bj][m][0] *= s0; acc[ai][bj][m][1] *= s1;
.LBB0_531:
	s_andn2_b64 vcc, exec, s[24:25]
	s_cbranch_vccnz .LBB0_533
	s_nop 1
	v_mov_b32_e32 v162, v228
	v_mov_b32_e32 v163, v229
	v_mov_b32_e32 v164, v230
	v_mov_b32_e32 v165, v231
	v_lshlrev_b32_e32 v148, 16, v164
	v_and_b32_e32 v149, 0xffff0000, v164
	v_max_f32_e32 v148, v148, v148
	v_max_f32_e32 v149, v149, v149
	v_lshlrev_b32_e32 v144, 16, v162
	v_and_b32_e32 v145, 0xffff0000, v162
	v_max_f32_e32 v148, 0xda24260, v148
	v_max_f32_e32 v149, 0xda24260, v149
	v_max_f32_e32 v144, v144, v144
	v_rcp_f32_e32 v148, v148
	v_max_f32_e32 v145, v145, v145
	v_rcp_f32_e32 v149, v149
	v_max_f32_e32 v144, 0xda24260, v144
	v_max_f32_e32 v145, 0xda24260, v145
	v_rcp_f32_e32 v144, v144
	v_rcp_f32_e32 v145, v145
	v_lshlrev_b32_e32 v162, 16, v165
	v_pk_mul_f32 v[148:149], v[148:149], v[152:153]
	v_max_f32_e32 v153, v162, v162
	v_lshlrev_b32_e32 v156, 16, v163
	v_and_b32_e32 v157, 0xffff0000, v163
	v_max_f32_e32 v153, 0xda24260, v153
	v_pk_mul_f32 v[144:145], v[144:145], v[154:155]
	v_max_f32_e32 v152, v156, v156
	v_rcp_f32_e32 v154, v153
	v_max_f32_e32 v153, v157, v157
	v_max_f32_e32 v152, 0xda24260, v152
	v_max_f32_e32 v153, 0xda24260, v153
	v_rcp_f32_e32 v152, v152
	v_rcp_f32_e32 v153, v153
	v_and_b32_e32 v163, 0xffff0000, v165
	v_pk_mul_f32 v[88:89], v[88:89], v[144:145]
	v_pk_mul_f32 v[84:85], v[84:85], v[148:149]
	v_pk_mul_f32 v[150:151], v[152:153], v[150:151]
	v_max_f32_e32 v152, v163, v163
	v_max_f32_e32 v152, 0xda24260, v152
	v_rcp_f32_e32 v155, v152
	v_pk_mul_f32 v[90:91], v[90:91], v[150:151]
	v_pk_mul_f32 v[146:147], v[154:155], v[146:147]
	s_nop 0
	v_pk_mul_f32 v[86:87], v[86:87], v[146:147]
.LBB0_533:
	v_or_b32_e32 v144, 32, v2
	v_ashrrev_i32_e32 v145, 31, v144
	v_lshlrev_b64 v[148:149], 11, v[144:145]
	v_lshl_add_u64 v[144:145], s[22:23], 0, v[148:149]
	v_lshl_add_u64 v[146:147], v[144:145], 0, v[0:1]
	v_lshl_add_u64 v[144:145], s[2:3], 0, v[148:149]
	s_and_b64 vcc, exec, s[6:7]
	v_lshl_add_u64 v[144:145], v[144:145], 0, v[0:1]
	s_mov_b64 s[24:25], -1
	v_add_u32_e32 v199, 0x10000, v198
	global_load_dwordx4 v[200:203], v199, s[22:23]
	global_load_dwordx4 v[204:207], v199, s[20:21]
	global_load_dwordx4 v[208:211], v199, s[22:23] offset:256
	global_load_dwordx4 v[212:215], v199, s[20:21] offset:256
	v_add_u32_e32 v199, 0x18000, v198
	global_load_dwordx4 v[216:219], v199, s[22:23]
	global_load_dwordx4 v[220:223], v199, s[20:21]
	global_load_dwordx4 v[224:227], v199, s[22:23] offset:256
	global_load_dwordx4 v[228:231], v199, s[20:21] offset:256
	s_waitcnt vmcnt(0)
	s_nop 1
	v_mov_b32_e32 v162, v200
	v_mov_b32_e32 v163, v201
	v_mov_b32_e32 v164, v202
	v_mov_b32_e32 v165, v203
	v_lshlrev_b32_e32 v156, 16, v162
	v_and_b32_e32 v157, 0xffff0000, v162
	v_lshlrev_b32_e32 v152, 16, v163
	v_and_b32_e32 v153, 0xffff0000, v163
	v_lshlrev_b32_e32 v154, 16, v164
	v_and_b32_e32 v155, 0xffff0000, v164
	v_lshlrev_b32_e32 v150, 16, v165
	v_and_b32_e32 v151, 0xffff0000, v165
	s_cbranch_vccnz .LBB0_535
	v_pk_mul_f32 v[164:165], v[114:115], v[152:153]
	v_pk_mul_f32 v[162:163], v[112:113], v[156:157]
	v_pk_mul_f32 v[192:193], v[110:111], v[150:151]
	v_pk_mul_f32 v[194:195], v[108:109], v[154:155]
	v_cvt_pk_bf16_f32 v162, v162, v163
	v_cvt_pk_bf16_f32 v163, v164, v165
	v_cvt_pk_bf16_f32 v164, v194, v195
	v_cvt_pk_bf16_f32 v165, v192, v193
	s_mov_b64 s[24:25], 0
	global_store_dwordx4 v[144:145], v[162:165], off
.LBB0_535:
	v_lshl_add_u64 v[148:149], s[20:21], 0, v[148:149]
	s_andn2_b64 vcc, exec, s[24:25]
	v_lshl_add_u64 v[148:149], v[148:149], 0, v[0:1]
	s_cbranch_vccnz .LBB0_537
	s_nop 1
	v_mov_b32_e32 v162, v204
	v_mov_b32_e32 v163, v205
	v_mov_b32_e32 v164, v206
	v_mov_b32_e32 v165, v207
	v_lshlrev_b32_e32 v193, 16, v163
	v_and_b32_e32 v194, 0xffff0000, v163
	v_lshlrev_b32_e32 v163, 16, v164
	v_max_f32_e32 v163, v163, v163
	v_lshlrev_b32_e32 v182, 16, v162
	v_and_b32_e32 v192, 0xffff0000, v162
	v_max_f32_e32 v163, 0xda24260, v163
	v_and_b32_e32 v195, 0xffff0000, v164
	v_max_f32_e32 v162, v182, v182
	v_rcp_f32_e32 v164, v163
	v_max_f32_e32 v163, v192, v192
	v_max_f32_e32 v162, 0xda24260, v162
	v_max_f32_e32 v163, 0xda24260, v163
	v_rcp_f32_e32 v162, v162
	v_rcp_f32_e32 v163, v163
	v_lshlrev_b32_e32 v196, 16, v165
	v_and_b32_e32 v197, 0xffff0000, v165
	v_pk_mul_f32 v[156:157], v[162:163], v[156:157]
	v_max_f32_e32 v162, v195, v195
	v_max_f32_e32 v162, 0xda24260, v162
	v_rcp_f32_e32 v165, v162
	v_max_f32_e32 v163, v196, v196
	v_max_f32_e32 v163, 0xda24260, v163
	v_max_f32_e32 v162, v193, v193
	v_pk_mul_f32 v[154:155], v[164:165], v[154:155]
	v_rcp_f32_e32 v164, v163
	v_max_f32_e32 v163, v194, v194
	v_max_f32_e32 v162, 0xda24260, v162
	v_max_f32_e32 v163, 0xda24260, v163
	v_rcp_f32_e32 v162, v162
	v_rcp_f32_e32 v163, v163
	v_pk_mul_f32 v[112:113], v[112:113], v[156:157]
	v_pk_mul_f32 v[108:109], v[108:109], v[154:155]
	v_pk_mul_f32 v[152:153], v[162:163], v[152:153]
	v_max_f32_e32 v162, v197, v197
	v_max_f32_e32 v162, 0xda24260, v162
	v_rcp_f32_e32 v165, v162
	v_pk_mul_f32 v[114:115], v[114:115], v[152:153]
	v_pk_mul_f32 v[150:151], v[164:165], v[150:151]
	s_nop 0
	v_pk_mul_f32 v[110:111], v[110:111], v[150:151]
.LBB0_537:
	s_and_b64 vcc, exec, s[6:7]
	s_mov_b64 s[24:25], -1
	s_nop 1
	v_mov_b32_e32 v162, v208
	v_mov_b32_e32 v163, v209
	v_mov_b32_e32 v164, v210
	v_mov_b32_e32 v165, v211
	v_lshlrev_b32_e32 v154, 16, v162
	v_and_b32_e32 v155, 0xffff0000, v162
	v_lshlrev_b32_e32 v150, 16, v163
	v_and_b32_e32 v151, 0xffff0000, v163
	v_lshlrev_b32_e32 v152, 16, v164
	v_and_b32_e32 v153, 0xffff0000, v164
	v_lshlrev_b32_e32 v146, 16, v165
	v_and_b32_e32 v147, 0xffff0000, v165
	s_cbranch_vccnz .LBB0_539
	v_pk_mul_f32 v[156:157], v[82:83], v[150:151]
	v_pk_mul_f32 v[162:163], v[80:81], v[154:155]
	v_pk_mul_f32 v[192:193], v[78:79], v[146:147]
	v_pk_mul_f32 v[164:165], v[76:77], v[152:153]
	v_cvt_pk_bf16_f32 v162, v162, v163
	v_cvt_pk_bf16_f32 v163, v156, v157
	v_cvt_pk_bf16_f32 v164, v164, v165
	v_cvt_pk_bf16_f32 v165, v192, v193
	s_mov_b64 s[24:25], 0
	global_store_dwordx4 v[144:145], v[162:165], off offset:256
; #define GAS __attribute__((address_space(1)))
; __device__ __forceinline__ float bf_lo(unsigned u) { return __uint_as_float(u << 16); }
; __device__ __forceinline__ float bf_hi(unsigned u) { return __uint_as_float(u & 0xffff0000u); }
;     __device__ __forceinline__ void operator()(f32x4 (&acc)[2][2][4][2], const Unit& u, int wr, int wc, int fr, int fq) const {
;     ...
;             for (int m = 0; m < 4; ++m) { const int row = row0 + ai * HALF + m * 16; const GAS bf16_t* gp = ((br < 2) ? g01 + (size_t)br * MROWS * 1024 : g2) + (size_t)row * 1024 + col0; const GAS bf16_t* gn = ((br == 0) ? g01 + (size_t)MROWS * 1024 : g2) + (size_t)row * 1024 + col0; GAS bf16_t* mp = Mg + (size_t)row * 1024 + col0;
; #pragma unroll
;                 for (int bj = 0; bj < 2; ++bj) { const u32x4 g = *(const GAS u32x4*)(gp + bj * HALF);
;                     f32x4 s0 = {bf_lo(g.x), bf_hi(g.x), bf_lo(g.y), bf_hi(g.y)}, s1 = {bf_lo(g.z), bf_hi(g.z), bf_lo(g.w), bf_hi(g.w)};
;                     if (br < 2) { const u32x4 h = *(const GAS u32x4*)(gn + bj * HALF);
;                         const f32x4 d0 = {bf_lo(h.x), bf_hi(h.x), bf_lo(h.y), bf_hi(h.y)}, d1 = {bf_lo(h.z), bf_hi(h.z), bf_lo(h.w), bf_hi(h.w)};
; #pragma unroll
;                         for (int e = 0; e < 4; ++e) { s0[e] *= __builtin_amdgcn_rcpf(fmaxf(d0[e], 1e-30f)); s1[e] *= __builtin_amdgcn_rcpf(fmaxf(d1[e], 1e-30f)); }
;                         acc[ai][bj][m][0] *= s0; acc[ai][bj][m][1] *= s1;
.LBB0_539:
	s_andn2_b64 vcc, exec, s[24:25]
	s_cbranch_vccnz .LBB0_541
	s_nop 1
	v_mov_b32_e32 v162, v212
	v_mov_b32_e32 v163, v213
	v_mov_b32_e32 v164, v214
	v_mov_b32_e32 v165, v215
	v_lshlrev_b32_e32 v148, 16, v164
	v_and_b32_e32 v149, 0xffff0000, v164
	v_max_f32_e32 v148, v148, v148
	v_max_f32_e32 v149, v149, v149
	v_lshlrev_b32_e32 v144, 16, v162
	v_and_b32_e32 v145, 0xffff0000, v162
	v_max_f32_e32 v148, 0xda24260, v148
	v_max_f32_e32 v149, 0xda24260, v149
	v_max_f32_e32 v144, v144, v144
	v_rcp_f32_e32 v148, v148
	v_max_f32_e32 v145, v145, v145
	v_rcp_f32_e32 v149, v149
	v_max_f32_e32 v144, 0xda24260, v144
	v_max_f32_e32 v145, 0xda24260, v145
	v_rcp_f32_e32 v144, v144
	v_rcp_f32_e32 v145, v145
	v_lshlrev_b32_e32 v162, 16, v165
	v_pk_mul_f32 v[148:149], v[148:149], v[152:153]
	v_max_f32_e32 v153, v162, v162
	v_lshlrev_b32_e32 v156, 16, v163
	v_and_b32_e32 v157, 0xffff0000, v163
	v_max_f32_e32 v153, 0xda24260, v153
	v_pk_mul_f32 v[144:145], v[144:145], v[154:155]
	v_max_f32_e32 v152, v156, v156
	v_rcp_f32_e32 v154, v153
	v_max_f32_e32 v153, v157, v157
	v_max_f32_e32 v152, 0xda24260, v152
	v_max_f32_e32 v153, 0xda24260, v153
	v_rcp_f32_e32 v152, v152
	v_rcp_f32_e32 v153, v153
	v_and_b32_e32 v163, 0xffff0000, v165
	v_pk_mul_f32 v[80:81], v[80:81], v[144:145]
	v_pk_mul_f32 v[76:77], v[76:77], v[148:149]
	v_pk_mul_f32 v[150:151], v[152:153], v[150:151]
	v_max_f32_e32 v152, v163, v163
	v_max_f32_e32 v152, 0xda24260, v152
	v_rcp_f32_e32 v155, v152
	v_pk_mul_f32 v[82:83], v[82:83], v[150:151]
	v_pk_mul_f32 v[146:147], v[154:155], v[146:147]
	s_nop 0
	v_pk_mul_f32 v[78:79], v[78:79], v[146:147]
.LBB0_541:
	v_or_b32_e32 v144, 48, v2
	v_ashrrev_i32_e32 v145, 31, v144
	v_lshlrev_b64 v[148:149], 11, v[144:145]
	v_lshl_add_u64 v[144:145], s[22:23], 0, v[148:149]
	v_lshl_add_u64 v[146:147], v[144:145], 0, v[0:1]
	v_lshl_add_u64 v[144:145], s[2:3], 0, v[148:149]
	s_and_b64 vcc, exec, s[6:7]
	v_lshl_add_u64 v[144:145], v[144:145], 0, v[0:1]
	s_mov_b64 s[24:25], -1
	s_nop 1
	v_mov_b32_e32 v162, v216
	v_mov_b32_e32 v163, v217
	v_mov_b32_e32 v164, v218
	v_mov_b32_e32 v165, v219
	v_lshlrev_b32_e32 v156, 16, v162
	v_and_b32_e32 v157, 0xffff0000, v162
	v_lshlrev_b32_e32 v152, 16, v163
	v_and_b32_e32 v153, 0xffff0000, v163
	v_lshlrev_b32_e32 v154, 16, v164
	v_and_b32_e32 v155, 0xffff0000, v164
	v_lshlrev_b32_e32 v150, 16, v165
	v_and_b32_e32 v151, 0xffff0000, v165
	s_cbranch_vccnz .LBB0_543
	v_pk_mul_f32 v[164:165], v[106:107], v[152:153]
	v_pk_mul_f32 v[162:163], v[104:105], v[156:157]
	v_pk_mul_f32 v[192:193], v[102:103], v[150:151]
	v_pk_mul_f32 v[194:195], v[100:101], v[154:155]
	v_cvt_pk_bf16_f32 v162, v162, v163
	v_cvt_pk_bf16_f32 v163, v164, v165
	v_cvt_pk_bf16_f32 v164, v194, v195
	v_cvt_pk_bf16_f32 v165, v192, v193
	s_mov_b64 s[24:25], 0
	global_store_dwordx4 v[144:145], v[162:165], off
.LBB0_543:
	v_lshl_add_u64 v[148:149], s[20:21], 0, v[148:149]
	s_andn2_b64 vcc, exec, s[24:25]
	v_lshl_add_u64 v[148:149], v[148:149], 0, v[0:1]
	s_cbranch_vccnz .LBB0_545
	s_nop 1
	v_mov_b32_e32 v162, v220
	v_mov_b32_e32 v163, v221
	v_mov_b32_e32 v164, v222
	v_mov_b32_e32 v165, v223
	v_lshlrev_b32_e32 v193, 16, v163
	v_and_b32_e32 v194, 0xffff0000, v163
	v_lshlrev_b32_e32 v163, 16, v164
	v_max_f32_e32 v163, v163, v163
	v_lshlrev_b32_e32 v182, 16, v162
	v_and_b32_e32 v192, 0xffff0000, v162
	v_max_f32_e32 v163, 0xda24260, v163
	v_and_b32_e32 v195, 0xffff0000, v164
	v_max_f32_e32 v162, v182, v182
	v_rcp_f32_e32 v164, v163
	v_max_f32_e32 v163, v192, v192
	v_max_f32_e32 v162, 0xda24260, v162
	v_max_f32_e32 v163, 0xda24260, v163
	v_rcp_f32_e32 v162, v162
	v_rcp_f32_e32 v163, v163
	v_lshlrev_b32_e32 v196, 16, v165
	v_and_b32_e32 v197, 0xffff0000, v165
	v_pk_mul_f32 v[156:157], v[162:163], v[156:157]
	v_max_f32_e32 v162, v195, v195
	v_max_f32_e32 v162, 0xda24260, v162
	v_rcp_f32_e32 v165, v162
	v_max_f32_e32 v163, v196, v196
	v_max_f32_e32 v163, 0xda24260, v163
	v_max_f32_e32 v162, v193, v193
	v_pk_mul_f32 v[154:155], v[164:165], v[154:155]
	v_rcp_f32_e32 v164, v163
	v_max_f32_e32 v163, v194, v194
	v_max_f32_e32 v162, 0xda24260, v162
	v_max_f32_e32 v163, 0xda24260, v163
	v_rcp_f32_e32 v162, v162
	v_rcp_f32_e32 v163, v163
	v_pk_mul_f32 v[104:105], v[104:105], v[156:157]
	v_pk_mul_f32 v[100:101], v[100:101], v[154:155]
	v_pk_mul_f32 v[152:153], v[162:163], v[152:153]
	v_max_f32_e32 v162, v197, v197
	v_max_f32_e32 v162, 0xda24260, v162
	v_rcp_f32_e32 v165, v162
	v_pk_mul_f32 v[106:107], v[106:107], v[152:153]
	v_pk_mul_f32 v[150:151], v[164:165], v[150:151]
	s_nop 0
	v_pk_mul_f32 v[102:103], v[102:103], v[150:151]
.LBB0_545:
	s_and_b64 vcc, exec, s[6:7]
	s_mov_b64 s[24:25], -1
	s_nop 1
	v_mov_b32_e32 v162, v224
	v_mov_b32_e32 v163, v225
	v_mov_b32_e32 v164, v226
	v_mov_b32_e32 v165, v227
	v_lshlrev_b32_e32 v154, 16, v162
	v_and_b32_e32 v155, 0xffff0000, v162
	v_lshlrev_b32_e32 v150, 16, v163
	v_and_b32_e32 v151, 0xffff0000, v163
	v_lshlrev_b32_e32 v152, 16, v164
	v_and_b32_e32 v153, 0xffff0000, v164
	v_lshlrev_b32_e32 v146, 16, v165
	v_and_b32_e32 v147, 0xffff0000, v165
	s_cbranch_vccnz .LBB0_547
	v_pk_mul_f32 v[156:157], v[74:75], v[150:151]
	v_pk_mul_f32 v[162:163], v[72:73], v[154:155]
	v_pk_mul_f32 v[192:193], v[70:71], v[146:147]
	v_pk_mul_f32 v[164:165], v[68:69], v[152:153]
	v_cvt_pk_bf16_f32 v162, v162, v163
	v_cvt_pk_bf16_f32 v163, v156, v157
	v_cvt_pk_bf16_f32 v164, v164, v165
	v_cvt_pk_bf16_f32 v165, v192, v193
	s_mov_b64 s[24:25], 0
	global_store_dwordx4 v[144:145], v[162:165], off offset:256
; #define GAS __attribute__((address_space(1)))
; __device__ __forceinline__ float bf_lo(unsigned u) { return __uint_as_float(u << 16); }
; __device__ __forceinline__ float bf_hi(unsigned u) { return __uint_as_float(u & 0xffff0000u); }
;     __device__ __forceinline__ void operator()(f32x4 (&acc)[2][2][4][2], const Unit& u, int wr, int wc, int fr, int fq) const {
;     ...
;             for (int m = 0; m < 4; ++m) { const int row = row0 + ai * HALF + m * 16; const GAS bf16_t* gp = ((br < 2) ? g01 + (size_t)br * MROWS * 1024 : g2) + (size_t)row * 1024 + col0; const GAS bf16_t* gn = ((br == 0) ? g01 + (size_t)MROWS * 1024 : g2) + (size_t)row * 1024 + col0; GAS bf16_t* mp = Mg + (size_t)row * 1024 + col0;
; #pragma unroll
;                 for (int bj = 0; bj < 2; ++bj) { const u32x4 g = *(const GAS u32x4*)(gp + bj * HALF);
;                     f32x4 s0 = {bf_lo(g.x), bf_hi(g.x), bf_lo(g.y), bf_hi(g.y)}, s1 = {bf_lo(g.z), bf_hi(g.z), bf_lo(g.w), bf_hi(g.w)};
;                     if (br < 2) { const u32x4 h = *(const GAS u32x4*)(gn + bj * HALF);
;                         const f32x4 d0 = {bf_lo(h.x), bf_hi(h.x), bf_lo(h.y), bf_hi(h.y)}, d1 = {bf_lo(h.z), bf_hi(h.z), bf_lo(h.w), bf_hi(h.w)};
; #pragma unroll
;                         for (int e = 0; e < 4; ++e) { s0[e] *= __builtin_amdgcn_rcpf(fmaxf(d0[e], 1e-30f)); s1[e] *= __builtin_amdgcn_rcpf(fmaxf(d1[e], 1e-30f)); }
;                         acc[ai][bj][m][0] *= s0; acc[ai][bj][m][1] *= s1;
.LBB0_547:
	s_andn2_b64 vcc, exec, s[24:25]
	s_cbranch_vccnz .LBB0_549
	s_nop 1
	v_mov_b32_e32 v162, v228
	v_mov_b32_e32 v163, v229
	v_mov_b32_e32 v164, v230
	v_mov_b32_e32 v165, v231
	v_lshlrev_b32_e32 v148, 16, v164
	v_and_b32_e32 v149, 0xffff0000, v164
	v_max_f32_e32 v148, v148, v148
	v_max_f32_e32 v149, v149, v149
	v_lshlrev_b32_e32 v144, 16, v162
	v_and_b32_e32 v145, 0xffff0000, v162
	v_max_f32_e32 v148, 0xda24260, v148
	v_max_f32_e32 v149, 0xda24260, v149
	v_max_f32_e32 v144, v144, v144
	v_rcp_f32_e32 v148, v148
	v_max_f32_e32 v145, v145, v145
	v_rcp_f32_e32 v149, v149
	v_max_f32_e32 v144, 0xda24260, v144
	v_max_f32_e32 v145, 0xda24260, v145
	v_rcp_f32_e32 v144, v144
	v_rcp_f32_e32 v145, v145
	v_lshlrev_b32_e32 v162, 16, v165
	v_pk_mul_f32 v[148:149], v[148:149], v[152:153]
	v_max_f32_e32 v153, v162, v162
	v_lshlrev_b32_e32 v156, 16, v163
	v_and_b32_e32 v157, 0xffff0000, v163
	v_max_f32_e32 v153, 0xda24260, v153
	v_pk_mul_f32 v[144:145], v[144:145], v[154:155]
	v_max_f32_e32 v152, v156, v156
	v_rcp_f32_e32 v154, v153
	v_max_f32_e32 v153, v157, v157
	v_max_f32_e32 v152, 0xda24260, v152
	v_max_f32_e32 v153, 0xda24260, v153
	v_rcp_f32_e32 v152, v152
	v_rcp_f32_e32 v153, v153
	v_and_b32_e32 v163, 0xffff0000, v165
	v_pk_mul_f32 v[72:73], v[72:73], v[144:145]
	v_pk_mul_f32 v[68:69], v[68:69], v[148:149]
	v_pk_mul_f32 v[150:151], v[152:153], v[150:151]
	v_max_f32_e32 v152, v163, v163
	v_max_f32_e32 v152, 0xda24260, v152
	v_rcp_f32_e32 v155, v152
	v_pk_mul_f32 v[74:75], v[74:75], v[150:151]
	v_pk_mul_f32 v[146:147], v[154:155], v[146:147]
	s_nop 0
	v_pk_mul_f32 v[70:71], v[70:71], v[146:147]
.LBB0_549:
	v_lshlrev_b64 v[144:145], 11, v[2:3]
	s_mov_b64 s[24:25], 0x40000
	v_lshl_add_u64 v[148:149], v[144:145], 0, s[24:25]
	v_lshl_add_u64 v[144:145], s[22:23], 0, v[148:149]
	v_lshl_add_u64 v[146:147], v[144:145], 0, v[0:1]
	v_lshl_add_u64 v[144:145], s[2:3], 0, v[148:149]
	s_and_b64 vcc, exec, s[6:7]
	v_lshl_add_u64 v[144:145], v[144:145], 0, v[0:1]
	s_mov_b64 s[24:25], -1
	v_add_u32_e32 v199, 0x40000, v198
	global_load_dwordx4 v[200:203], v199, s[22:23]
	global_load_dwordx4 v[204:207], v199, s[20:21]
	global_load_dwordx4 v[208:211], v199, s[22:23] offset:256
	global_load_dwordx4 v[212:215], v199, s[20:21] offset:256
	v_add_u32_e32 v199, 0x48000, v198
	global_load_dwordx4 v[216:219], v199, s[22:23]
	global_load_dwordx4 v[220:223], v199, s[20:21]
	global_load_dwordx4 v[224:227], v199, s[22:23] offset:256
	global_load_dwordx4 v[228:231], v199, s[20:21] offset:256
	s_waitcnt vmcnt(0)
	s_nop 1
	v_mov_b32_e32 v162, v200
	v_mov_b32_e32 v163, v201
	v_mov_b32_e32 v164, v202
	v_mov_b32_e32 v165, v203
	v_lshlrev_b32_e32 v156, 16, v162
	v_and_b32_e32 v157, 0xffff0000, v162
	v_lshlrev_b32_e32 v152, 16, v163
	v_and_b32_e32 v153, 0xffff0000, v163
	v_lshlrev_b32_e32 v154, 16, v164
	v_and_b32_e32 v155, 0xffff0000, v164
	v_lshlrev_b32_e32 v150, 16, v165
	v_and_b32_e32 v151, 0xffff0000, v165
	s_cbranch_vccnz .LBB0_551
	v_pk_mul_f32 v[164:165], v[66:67], v[152:153]
	v_pk_mul_f32 v[162:163], v[64:65], v[156:157]
	v_pk_mul_f32 v[192:193], v[62:63], v[150:151]
	v_pk_mul_f32 v[194:195], v[60:61], v[154:155]
	v_cvt_pk_bf16_f32 v162, v162, v163
	v_cvt_pk_bf16_f32 v163, v164, v165
	v_cvt_pk_bf16_f32 v164, v194, v195
	v_cvt_pk_bf16_f32 v165, v192, v193
	s_mov_b64 s[24:25], 0
	global_store_dwordx4 v[144:145], v[162:165], off
.LBB0_551:
	v_lshl_add_u64 v[148:149], s[20:21], 0, v[148:149]
	s_andn2_b64 vcc, exec, s[24:25]
	v_lshl_add_u64 v[148:149], v[148:149], 0, v[0:1]
	s_cbranch_vccnz .LBB0_553
	s_nop 1
	v_mov_b32_e32 v162, v204
	v_mov_b32_e32 v163, v205
	v_mov_b32_e32 v164, v206
	v_mov_b32_e32 v165, v207
	v_lshlrev_b32_e32 v193, 16, v163
	v_and_b32_e32 v194, 0xffff0000, v163
	v_lshlrev_b32_e32 v163, 16, v164
	v_max_f32_e32 v163, v163, v163
	v_lshlrev_b32_e32 v182, 16, v162
	v_and_b32_e32 v192, 0xffff0000, v162
	v_max_f32_e32 v163, 0xda24260, v163
	v_and_b32_e32 v195, 0xffff0000, v164
	v_max_f32_e32 v162, v182, v182
	v_rcp_f32_e32 v164, v163
	v_max_f32_e32 v163, v192, v192
	v_max_f32_e32 v162, 0xda24260, v162
	v_max_f32_e32 v163, 0xda24260, v163
	v_rcp_f32_e32 v162, v162
	v_rcp_f32_e32 v163, v163
	v_lshlrev_b32_e32 v196, 16, v165
	v_and_b32_e32 v197, 0xffff0000, v165
	v_pk_mul_f32 v[156:157], v[162:163], v[156:157]
	v_max_f32_e32 v162, v195, v195
	v_max_f32_e32 v162, 0xda24260, v162
	v_rcp_f32_e32 v165, v162
	v_max_f32_e32 v163, v196, v196
	v_max_f32_e32 v163, 0xda24260, v163
	v_max_f32_e32 v162, v193, v193
	v_pk_mul_f32 v[154:155], v[164:165], v[154:155]
	v_rcp_f32_e32 v164, v163
	v_max_f32_e32 v163, v194, v194
	v_max_f32_e32 v162, 0xda24260, v162
	v_max_f32_e32 v163, 0xda24260, v163
	v_rcp_f32_e32 v162, v162
	v_rcp_f32_e32 v163, v163
	v_pk_mul_f32 v[64:65], v[64:65], v[156:157]
	v_pk_mul_f32 v[60:61], v[60:61], v[154:155]
	v_pk_mul_f32 v[152:153], v[162:163], v[152:153]
	v_max_f32_e32 v162, v197, v197
	v_max_f32_e32 v162, 0xda24260, v162
	v_rcp_f32_e32 v165, v162
	v_pk_mul_f32 v[66:67], v[66:67], v[152:153]
	v_pk_mul_f32 v[150:151], v[164:165], v[150:151]
	s_nop 0
	v_pk_mul_f32 v[62:63], v[62:63], v[150:151]
.LBB0_553:
	s_and_b64 vcc, exec, s[6:7]
	s_mov_b64 s[24:25], -1
	s_nop 1
	v_mov_b32_e32 v162, v208
	v_mov_b32_e32 v163, v209
	v_mov_b32_e32 v164, v210
	v_mov_b32_e32 v165, v211
	v_lshlrev_b32_e32 v154, 16, v162
	v_and_b32_e32 v155, 0xffff0000, v162
	v_lshlrev_b32_e32 v150, 16, v163
	v_and_b32_e32 v151, 0xffff0000, v163
	v_lshlrev_b32_e32 v152, 16, v164
	v_and_b32_e32 v153, 0xffff0000, v164
	v_lshlrev_b32_e32 v146, 16, v165
	v_and_b32_e32 v147, 0xffff0000, v165
	s_cbranch_vccnz .LBB0_555
	v_pk_mul_f32 v[156:157], v[34:35], v[150:151]
	v_pk_mul_f32 v[162:163], v[32:33], v[154:155]
	v_pk_mul_f32 v[192:193], v[30:31], v[146:147]
	v_pk_mul_f32 v[164:165], v[28:29], v[152:153]
	v_cvt_pk_bf16_f32 v162, v162, v163
	v_cvt_pk_bf16_f32 v163, v156, v157
	v_cvt_pk_bf16_f32 v164, v164, v165
	v_cvt_pk_bf16_f32 v165, v192, v193
	s_mov_b64 s[24:25], 0
	global_store_dwordx4 v[144:145], v[162:165], off offset:256
; #define GAS __attribute__((address_space(1)))
; __device__ __forceinline__ float bf_lo(unsigned u) { return __uint_as_float(u << 16); }
; __device__ __forceinline__ float bf_hi(unsigned u) { return __uint_as_float(u & 0xffff0000u); }
;     __device__ __forceinline__ void operator()(f32x4 (&acc)[2][2][4][2], const Unit& u, int wr, int wc, int fr, int fq) const {
;     ...
;             for (int m = 0; m < 4; ++m) { const int row = row0 + ai * HALF + m * 16; const GAS bf16_t* gp = ((br < 2) ? g01 + (size_t)br * MROWS * 1024 : g2) + (size_t)row * 1024 + col0; const GAS bf16_t* gn = ((br == 0) ? g01 + (size_t)MROWS * 1024 : g2) + (size_t)row * 1024 + col0; GAS bf16_t* mp = Mg + (size_t)row * 1024 + col0;
; #pragma unroll
;                 for (int bj = 0; bj < 2; ++bj) { const u32x4 g = *(const GAS u32x4*)(gp + bj * HALF);
;                     f32x4 s0 = {bf_lo(g.x), bf_hi(g.x), bf_lo(g.y), bf_hi(g.y)}, s1 = {bf_lo(g.z), bf_hi(g.z), bf_lo(g.w), bf_hi(g.w)};
;                     if (br < 2) { const u32x4 h = *(const GAS u32x4*)(gn + bj * HALF);
;                         const f32x4 d0 = {bf_lo(h.x), bf_hi(h.x), bf_lo(h.y), bf_hi(h.y)}, d1 = {bf_lo(h.z), bf_hi(h.z), bf_lo(h.w), bf_hi(h.w)};
; #pragma unroll
;                         for (int e = 0; e < 4; ++e) { s0[e] *= __builtin_amdgcn_rcpf(fmaxf(d0[e], 1e-30f)); s1[e] *= __builtin_amdgcn_rcpf(fmaxf(d1[e], 1e-30f)); }
;                         acc[ai][bj][m][0] *= s0; acc[ai][bj][m][1] *= s1;
.LBB0_555:
	s_andn2_b64 vcc, exec, s[24:25]
	s_cbranch_vccnz .LBB0_557
	s_nop 1
	v_mov_b32_e32 v162, v212
	v_mov_b32_e32 v163, v213
	v_mov_b32_e32 v164, v214
	v_mov_b32_e32 v165, v215
	v_lshlrev_b32_e32 v148, 16, v164
	v_and_b32_e32 v149, 0xffff0000, v164
	v_max_f32_e32 v148, v148, v148
	v_max_f32_e32 v149, v149, v149
	v_lshlrev_b32_e32 v144, 16, v162
	v_and_b32_e32 v145, 0xffff0000, v162
	v_max_f32_e32 v148, 0xda24260, v148
	v_max_f32_e32 v149, 0xda24260, v149
	v_max_f32_e32 v144, v144, v144
	v_rcp_f32_e32 v148, v148
	v_max_f32_e32 v145, v145, v145
	v_rcp_f32_e32 v149, v149
	v_max_f32_e32 v144, 0xda24260, v144
	v_max_f32_e32 v145, 0xda24260, v145
	v_rcp_f32_e32 v144, v144
	v_rcp_f32_e32 v145, v145
	v_lshlrev_b32_e32 v162, 16, v165
	v_pk_mul_f32 v[148:149], v[148:149], v[152:153]
	v_max_f32_e32 v153, v162, v162
	v_lshlrev_b32_e32 v156, 16, v163
	v_and_b32_e32 v157, 0xffff0000, v163
	v_max_f32_e32 v153, 0xda24260, v153
	v_pk_mul_f32 v[144:145], v[144:145], v[154:155]
	v_max_f32_e32 v152, v156, v156
	v_rcp_f32_e32 v154, v153
	v_max_f32_e32 v153, v157, v157
	v_max_f32_e32 v152, 0xda24260, v152
	v_max_f32_e32 v153, 0xda24260, v153
	v_rcp_f32_e32 v152, v152
	v_rcp_f32_e32 v153, v153
	v_and_b32_e32 v163, 0xffff0000, v165
	v_pk_mul_f32 v[32:33], v[32:33], v[144:145]
	v_pk_mul_f32 v[28:29], v[28:29], v[148:149]
	v_pk_mul_f32 v[150:151], v[152:153], v[150:151]
	v_max_f32_e32 v152, v163, v163
	v_max_f32_e32 v152, 0xda24260, v152
	v_rcp_f32_e32 v155, v152
	v_pk_mul_f32 v[34:35], v[34:35], v[150:151]
	v_pk_mul_f32 v[146:147], v[154:155], v[146:147]
	s_nop 0
	v_pk_mul_f32 v[30:31], v[30:31], v[146:147]
.LBB0_557:
	v_lshlrev_b64 v[144:145], 11, v[2:3]
	s_mov_b64 s[24:25], 0x48000
	v_lshl_add_u64 v[148:149], v[144:145], 0, s[24:25]
	v_lshl_add_u64 v[144:145], s[22:23], 0, v[148:149]
	v_lshl_add_u64 v[146:147], v[144:145], 0, v[0:1]
	v_lshl_add_u64 v[144:145], s[2:3], 0, v[148:149]
	s_and_b64 vcc, exec, s[6:7]
	v_lshl_add_u64 v[144:145], v[144:145], 0, v[0:1]
	s_mov_b64 s[24:25], -1
	s_nop 1
	v_mov_b32_e32 v162, v216
	v_mov_b32_e32 v163, v217
	v_mov_b32_e32 v164, v218
	v_mov_b32_e32 v165, v219
	v_lshlrev_b32_e32 v156, 16, v162
	v_and_b32_e32 v157, 0xffff0000, v162
	v_lshlrev_b32_e32 v152, 16, v163
	v_and_b32_e32 v153, 0xffff0000, v163
	v_lshlrev_b32_e32 v154, 16, v164
	v_and_b32_e32 v155, 0xffff0000, v164
	v_lshlrev_b32_e32 v150, 16, v165
	v_and_b32_e32 v151, 0xffff0000, v165
	s_cbranch_vccnz .LBB0_559
	v_pk_mul_f32 v[164:165], v[58:59], v[152:153]
	v_pk_mul_f32 v[162:163], v[56:57], v[156:157]
	v_pk_mul_f32 v[192:193], v[54:55], v[150:151]
	v_pk_mul_f32 v[194:195], v[52:53], v[154:155]
	v_cvt_pk_bf16_f32 v162, v162, v163
	v_cvt_pk_bf16_f32 v163, v164, v165
	v_cvt_pk_bf16_f32 v164, v194, v195
	v_cvt_pk_bf16_f32 v165, v192, v193
	s_mov_b64 s[24:25], 0
	global_store_dwordx4 v[144:145], v[162:165], off
.LBB0_559:
	v_lshl_add_u64 v[148:149], s[20:21], 0, v[148:149]
	s_andn2_b64 vcc, exec, s[24:25]
	v_lshl_add_u64 v[148:149], v[148:149], 0, v[0:1]
	s_cbranch_vccnz .LBB0_561
	s_nop 1
	v_mov_b32_e32 v162, v220
	v_mov_b32_e32 v163, v221
	v_mov_b32_e32 v164, v222
	v_mov_b32_e32 v165, v223
	v_lshlrev_b32_e32 v193, 16, v163
	v_and_b32_e32 v194, 0xffff0000, v163
	v_lshlrev_b32_e32 v163, 16, v164
	v_max_f32_e32 v163, v163, v163
	v_lshlrev_b32_e32 v182, 16, v162
	v_and_b32_e32 v192, 0xffff0000, v162
	v_max_f32_e32 v163, 0xda24260, v163
	v_and_b32_e32 v195, 0xffff0000, v164
	v_max_f32_e32 v162, v182, v182
	v_rcp_f32_e32 v164, v163
	v_max_f32_e32 v163, v192, v192
	v_max_f32_e32 v162, 0xda24260, v162
	v_max_f32_e32 v163, 0xda24260, v163
	v_rcp_f32_e32 v162, v162
	v_rcp_f32_e32 v163, v163
	v_lshlrev_b32_e32 v196, 16, v165
	v_and_b32_e32 v197, 0xffff0000, v165
	v_pk_mul_f32 v[156:157], v[162:163], v[156:157]
	v_max_f32_e32 v162, v195, v195
	v_max_f32_e32 v162, 0xda24260, v162
	v_rcp_f32_e32 v165, v162
	v_max_f32_e32 v163, v196, v196
	v_max_f32_e32 v163, 0xda24260, v163
	v_max_f32_e32 v162, v193, v193
	v_pk_mul_f32 v[154:155], v[164:165], v[154:155]
	v_rcp_f32_e32 v164, v163
	v_max_f32_e32 v163, v194, v194
	v_max_f32_e32 v162, 0xda24260, v162
	v_max_f32_e32 v163, 0xda24260, v163
	v_rcp_f32_e32 v162, v162
	v_rcp_f32_e32 v163, v163
	v_pk_mul_f32 v[56:57], v[56:57], v[156:157]
	v_pk_mul_f32 v[52:53], v[52:53], v[154:155]
	v_pk_mul_f32 v[152:153], v[162:163], v[152:153]
	v_max_f32_e32 v162, v197, v197
	v_max_f32_e32 v162, 0xda24260, v162
	v_rcp_f32_e32 v165, v162
	v_pk_mul_f32 v[58:59], v[58:59], v[152:153]
	v_pk_mul_f32 v[150:151], v[164:165], v[150:151]
	s_nop 0
	v_pk_mul_f32 v[54:55], v[54:55], v[150:151]
.LBB0_561:
	s_and_b64 vcc, exec, s[6:7]
	s_mov_b64 s[24:25], -1
	s_nop 1
	v_mov_b32_e32 v162, v224
	v_mov_b32_e32 v163, v225
	v_mov_b32_e32 v164, v226
	v_mov_b32_e32 v165, v227
	v_lshlrev_b32_e32 v154, 16, v162
	v_and_b32_e32 v155, 0xffff0000, v162
	v_lshlrev_b32_e32 v150, 16, v163
	v_and_b32_e32 v151, 0xffff0000, v163
	v_lshlrev_b32_e32 v152, 16, v164
	v_and_b32_e32 v153, 0xffff0000, v164
	v_lshlrev_b32_e32 v146, 16, v165
	v_and_b32_e32 v147, 0xffff0000, v165
	s_cbranch_vccnz .LBB0_563
	v_pk_mul_f32 v[156:157], v[26:27], v[150:151]
	v_pk_mul_f32 v[162:163], v[24:25], v[154:155]
	v_pk_mul_f32 v[192:193], v[22:23], v[146:147]
	v_pk_mul_f32 v[164:165], v[20:21], v[152:153]
	v_cvt_pk_bf16_f32 v162, v162, v163
	v_cvt_pk_bf16_f32 v163, v156, v157
	v_cvt_pk_bf16_f32 v164, v164, v165
	v_cvt_pk_bf16_f32 v165, v192, v193
	s_mov_b64 s[24:25], 0
	global_store_dwordx4 v[144:145], v[162:165], off offset:256
; #define GAS __attribute__((address_space(1)))
; __device__ __forceinline__ float bf_lo(unsigned u) { return __uint_as_float(u << 16); }
; __device__ __forceinline__ float bf_hi(unsigned u) { return __uint_as_float(u & 0xffff0000u); }
;     __device__ __forceinline__ void operator()(f32x4 (&acc)[2][2][4][2], const Unit& u, int wr, int wc, int fr, int fq) const {
;     ...
;             for (int m = 0; m < 4; ++m) { const int row = row0 + ai * HALF + m * 16; const GAS bf16_t* gp = ((br < 2) ? g01 + (size_t)br * MROWS * 1024 : g2) + (size_t)row * 1024 + col0; const GAS bf16_t* gn = ((br == 0) ? g01 + (size_t)MROWS * 1024 : g2) + (size_t)row * 1024 + col0; GAS bf16_t* mp = Mg + (size_t)row * 1024 + col0;
; #pragma unroll
;                 for (int bj = 0; bj < 2; ++bj) { const u32x4 g = *(const GAS u32x4*)(gp + bj * HALF);
;                     f32x4 s0 = {bf_lo(g.x), bf_hi(g.x), bf_lo(g.y), bf_hi(g.y)}, s1 = {bf_lo(g.z), bf_hi(g.z), bf_lo(g.w), bf_hi(g.w)};
;                     if (br < 2) { const u32x4 h = *(const GAS u32x4*)(gn + bj * HALF);
;                         const f32x4 d0 = {bf_lo(h.x), bf_hi(h.x), bf_lo(h.y), bf_hi(h.y)}, d1 = {bf_lo(h.z), bf_hi(h.z), bf_lo(h.w), bf_hi(h.w)};
; #pragma unroll
;                         for (int e = 0; e < 4; ++e) { s0[e] *= __builtin_amdgcn_rcpf(fmaxf(d0[e], 1e-30f)); s1[e] *= __builtin_amdgcn_rcpf(fmaxf(d1[e], 1e-30f)); }
;                         acc[ai][bj][m][0] *= s0; acc[ai][bj][m][1] *= s1;
.LBB0_563:
	s_andn2_b64 vcc, exec, s[24:25]
	s_cbranch_vccnz .LBB0_565
	s_nop 1
	v_mov_b32_e32 v162, v228
	v_mov_b32_e32 v163, v229
	v_mov_b32_e32 v164, v230
	v_mov_b32_e32 v165, v231
	v_lshlrev_b32_e32 v148, 16, v164
	v_and_b32_e32 v149, 0xffff0000, v164
	v_max_f32_e32 v148, v148, v148
	v_max_f32_e32 v149, v149, v149
	v_lshlrev_b32_e32 v144, 16, v162
	v_and_b32_e32 v145, 0xffff0000, v162
	v_max_f32_e32 v148, 0xda24260, v148
	v_max_f32_e32 v149, 0xda24260, v149
	v_max_f32_e32 v144, v144, v144
	v_rcp_f32_e32 v148, v148
	v_max_f32_e32 v145, v145, v145
	v_rcp_f32_e32 v149, v149
	v_max_f32_e32 v144, 0xda24260, v144
	v_max_f32_e32 v145, 0xda24260, v145
	v_rcp_f32_e32 v144, v144
	v_rcp_f32_e32 v145, v145
	v_lshlrev_b32_e32 v162, 16, v165
	v_pk_mul_f32 v[148:149], v[148:149], v[152:153]
	v_max_f32_e32 v153, v162, v162
	v_lshlrev_b32_e32 v156, 16, v163
	v_and_b32_e32 v157, 0xffff0000, v163
	v_max_f32_e32 v153, 0xda24260, v153
	v_pk_mul_f32 v[144:145], v[144:145], v[154:155]
	v_max_f32_e32 v152, v156, v156
	v_rcp_f32_e32 v154, v153
	v_max_f32_e32 v153, v157, v157
	v_max_f32_e32 v152, 0xda24260, v152
	v_max_f32_e32 v153, 0xda24260, v153
	v_rcp_f32_e32 v152, v152
	v_rcp_f32_e32 v153, v153
	v_and_b32_e32 v163, 0xffff0000, v165
	v_pk_mul_f32 v[24:25], v[24:25], v[144:145]
	v_pk_mul_f32 v[20:21], v[20:21], v[148:149]
	v_pk_mul_f32 v[150:151], v[152:153], v[150:151]
	v_max_f32_e32 v152, v163, v163
	v_max_f32_e32 v152, 0xda24260, v152
	v_rcp_f32_e32 v155, v152
	v_pk_mul_f32 v[26:27], v[26:27], v[150:151]
	v_pk_mul_f32 v[146:147], v[154:155], v[146:147]
	s_nop 0
	v_pk_mul_f32 v[22:23], v[22:23], v[146:147]
.LBB0_565:
	v_lshlrev_b64 v[144:145], 11, v[2:3]
	s_mov_b64 s[24:25], 0x50000
	v_lshl_add_u64 v[148:149], v[144:145], 0, s[24:25]
	v_lshl_add_u64 v[144:145], s[22:23], 0, v[148:149]
	v_lshl_add_u64 v[146:147], v[144:145], 0, v[0:1]
	v_lshl_add_u64 v[144:145], s[2:3], 0, v[148:149]
	s_and_b64 vcc, exec, s[6:7]
	v_lshl_add_u64 v[144:145], v[144:145], 0, v[0:1]
	s_mov_b64 s[24:25], -1
	v_add_u32_e32 v199, 0x50000, v198
	global_load_dwordx4 v[200:203], v199, s[22:23]
	global_load_dwordx4 v[204:207], v199, s[20:21]
	global_load_dwordx4 v[208:211], v199, s[22:23] offset:256
	global_load_dwordx4 v[212:215], v199, s[20:21] offset:256
	v_add_u32_e32 v199, 0x58000, v198
	global_load_dwordx4 v[216:219], v199, s[22:23]
	global_load_dwordx4 v[220:223], v199, s[20:21]
	global_load_dwordx4 v[224:227], v199, s[22:23] offset:256
	global_load_dwordx4 v[228:231], v199, s[20:21] offset:256
	s_waitcnt vmcnt(0)
	s_nop 1
	v_mov_b32_e32 v162, v200
	v_mov_b32_e32 v163, v201
	v_mov_b32_e32 v164, v202
	v_mov_b32_e32 v165, v203
	v_lshlrev_b32_e32 v156, 16, v162
	v_and_b32_e32 v157, 0xffff0000, v162
	v_lshlrev_b32_e32 v152, 16, v163
	v_and_b32_e32 v153, 0xffff0000, v163
	v_lshlrev_b32_e32 v154, 16, v164
	v_and_b32_e32 v155, 0xffff0000, v164
	v_lshlrev_b32_e32 v150, 16, v165
	v_and_b32_e32 v151, 0xffff0000, v165
	s_cbranch_vccnz .LBB0_567
	v_pk_mul_f32 v[164:165], v[50:51], v[152:153]
	v_pk_mul_f32 v[162:163], v[48:49], v[156:157]
	v_pk_mul_f32 v[192:193], v[46:47], v[150:151]
	v_pk_mul_f32 v[194:195], v[44:45], v[154:155]
	v_cvt_pk_bf16_f32 v162, v162, v163
	v_cvt_pk_bf16_f32 v163, v164, v165
	v_cvt_pk_bf16_f32 v164, v194, v195
	v_cvt_pk_bf16_f32 v165, v192, v193
	s_mov_b64 s[24:25], 0
	global_store_dwordx4 v[144:145], v[162:165], off
.LBB0_567:
	v_lshl_add_u64 v[148:149], s[20:21], 0, v[148:149]
	s_andn2_b64 vcc, exec, s[24:25]
	v_lshl_add_u64 v[148:149], v[148:149], 0, v[0:1]
	s_cbranch_vccnz .LBB0_569
	s_nop 1
	v_mov_b32_e32 v162, v204
	v_mov_b32_e32 v163, v205
	v_mov_b32_e32 v164, v206
	v_mov_b32_e32 v165, v207
	v_lshlrev_b32_e32 v193, 16, v163
	v_and_b32_e32 v194, 0xffff0000, v163
	v_lshlrev_b32_e32 v163, 16, v164
	v_max_f32_e32 v163, v163, v163
	v_lshlrev_b32_e32 v182, 16, v162
	v_and_b32_e32 v192, 0xffff0000, v162
	v_max_f32_e32 v163, 0xda24260, v163
	v_and_b32_e32 v195, 0xffff0000, v164
	v_max_f32_e32 v162, v182, v182
	v_rcp_f32_e32 v164, v163
	v_max_f32_e32 v163, v192, v192
	v_max_f32_e32 v162, 0xda24260, v162
	v_max_f32_e32 v163, 0xda24260, v163
	v_rcp_f32_e32 v162, v162
	v_rcp_f32_e32 v163, v163
	v_lshlrev_b32_e32 v196, 16, v165
	v_and_b32_e32 v197, 0xffff0000, v165
	v_pk_mul_f32 v[156:157], v[162:163], v[156:157]
	v_max_f32_e32 v162, v195, v195
	v_max_f32_e32 v162, 0xda24260, v162
	v_rcp_f32_e32 v165, v162
	v_max_f32_e32 v163, v196, v196
	v_max_f32_e32 v163, 0xda24260, v163
	v_max_f32_e32 v162, v193, v193
	v_pk_mul_f32 v[154:155], v[164:165], v[154:155]
	v_rcp_f32_e32 v164, v163
	v_max_f32_e32 v163, v194, v194
	v_max_f32_e32 v162, 0xda24260, v162
	v_max_f32_e32 v163, 0xda24260, v163
	v_rcp_f32_e32 v162, v162
	v_rcp_f32_e32 v163, v163
	v_pk_mul_f32 v[48:49], v[48:49], v[156:157]
	v_pk_mul_f32 v[44:45], v[44:45], v[154:155]
	v_pk_mul_f32 v[152:153], v[162:163], v[152:153]
	v_max_f32_e32 v162, v197, v197
	v_max_f32_e32 v162, 0xda24260, v162
	v_rcp_f32_e32 v165, v162
	v_pk_mul_f32 v[50:51], v[50:51], v[152:153]
	v_pk_mul_f32 v[150:151], v[164:165], v[150:151]
	s_nop 0
	v_pk_mul_f32 v[46:47], v[46:47], v[150:151]
; #define GAS __attribute__((address_space(1)))
; __device__ __forceinline__ float bf_lo(unsigned u) { return __uint_as_float(u << 16); }
; __device__ __forceinline__ float bf_hi(unsigned u) { return __uint_as_float(u & 0xffff0000u); }
;     __device__ __forceinline__ void operator()(f32x4 (&acc)[2][2][4][2], const Unit& u, int wr, int wc, int fr, int fq) const {
;     ...
;             for (int m = 0; m < 4; ++m) { const int row = row0 + ai * HALF + m * 16; const GAS bf16_t* gp = ((br < 2) ? g01 + (size_t)br * MROWS * 1024 : g2) + (size_t)row * 1024 + col0; const GAS bf16_t* gn = ((br == 0) ? g01 + (size_t)MROWS * 1024 : g2) + (size_t)row * 1024 + col0; GAS bf16_t* mp = Mg + (size_t)row * 1024 + col0;
; #pragma unroll
;                 for (int bj = 0; bj < 2; ++bj) { const u32x4 g = *(const GAS u32x4*)(gp + bj * HALF);
;                     f32x4 s0 = {bf_lo(g.x), bf_hi(g.x), bf_lo(g.y), bf_hi(g.y)}, s1 = {bf_lo(g.z), bf_hi(g.z), bf_lo(g.w), bf_hi(g.w)};
;                     if (br < 2) { const u32x4 h = *(const GAS u32x4*)(gn + bj * HALF);
;                         const f32x4 d0 = {bf_lo(h.x), bf_hi(h.x), bf_lo(h.y), bf_hi(h.y)}, d1 = {bf_lo(h.z), bf_hi(h.z), bf_lo(h.w), bf_hi(h.w)};
; #pragma unroll
;                         for (int e = 0; e < 4; ++e) { s0[e] *= __builtin_amdgcn_rcpf(fmaxf(d0[e], 1e-30f)); s1[e] *= __builtin_amdgcn_rcpf(fmaxf(d1[e], 1e-30f)); }
;                         acc[ai][bj][m][0] *= s0; acc[ai][bj][m][1] *= s1;
.LBB0_569:
	s_and_b64 vcc, exec, s[6:7]
	s_mov_b64 s[24:25], -1
	s_nop 1
	v_mov_b32_e32 v162, v208
	v_mov_b32_e32 v163, v209
	v_mov_b32_e32 v164, v210
	v_mov_b32_e32 v165, v211
	v_lshlrev_b32_e32 v154, 16, v162
	v_and_b32_e32 v155, 0xffff0000, v162
	v_lshlrev_b32_e32 v150, 16, v163
	v_and_b32_e32 v151, 0xffff0000, v163
	v_lshlrev_b32_e32 v152, 16, v164
	v_and_b32_e32 v153, 0xffff0000, v164
	v_lshlrev_b32_e32 v146, 16, v165
	v_and_b32_e32 v147, 0xffff0000, v165
	s_cbranch_vccnz .LBB0_571
	v_pk_mul_f32 v[156:157], v[18:19], v[150:151]
	v_pk_mul_f32 v[162:163], v[16:17], v[154:155]
	v_pk_mul_f32 v[192:193], v[14:15], v[146:147]
	v_pk_mul_f32 v[164:165], v[12:13], v[152:153]
	v_cvt_pk_bf16_f32 v162, v162, v163
	v_cvt_pk_bf16_f32 v163, v156, v157
	v_cvt_pk_bf16_f32 v164, v164, v165
	v_cvt_pk_bf16_f32 v165, v192, v193
	s_mov_b64 s[24:25], 0
	global_store_dwordx4 v[144:145], v[162:165], off offset:256
.LBB0_571:
	s_andn2_b64 vcc, exec, s[24:25]
	s_cbranch_vccnz .LBB0_573
	s_nop 1
	v_mov_b32_e32 v162, v212
	v_mov_b32_e32 v163, v213
	v_mov_b32_e32 v164, v214
	v_mov_b32_e32 v165, v215
	v_lshlrev_b32_e32 v148, 16, v164
	v_and_b32_e32 v149, 0xffff0000, v164
	v_max_f32_e32 v148, v148, v148
	v_max_f32_e32 v149, v149, v149
	v_lshlrev_b32_e32 v144, 16, v162
	v_and_b32_e32 v145, 0xffff0000, v162
	v_max_f32_e32 v148, 0xda24260, v148
	v_max_f32_e32 v149, 0xda24260, v149
	v_max_f32_e32 v144, v144, v144
	v_rcp_f32_e32 v148, v148
	v_max_f32_e32 v145, v145, v145
	v_rcp_f32_e32 v149, v149
	v_max_f32_e32 v144, 0xda24260, v144
	v_max_f32_e32 v145, 0xda24260, v145
	v_rcp_f32_e32 v144, v144
	v_rcp_f32_e32 v145, v145
	v_lshlrev_b32_e32 v162, 16, v165
	v_pk_mul_f32 v[148:149], v[148:149], v[152:153]
	v_max_f32_e32 v153, v162, v162
	v_lshlrev_b32_e32 v156, 16, v163
	v_and_b32_e32 v157, 0xffff0000, v163
	v_max_f32_e32 v153, 0xda24260, v153
	v_pk_mul_f32 v[144:145], v[144:145], v[154:155]
	v_max_f32_e32 v152, v156, v156
	v_rcp_f32_e32 v154, v153
	v_max_f32_e32 v153, v157, v157
	v_max_f32_e32 v152, 0xda24260, v152
	v_max_f32_e32 v153, 0xda24260, v153
	v_rcp_f32_e32 v152, v152
	v_rcp_f32_e32 v153, v153
	v_and_b32_e32 v163, 0xffff0000, v165
	v_pk_mul_f32 v[16:17], v[16:17], v[144:145]
	v_pk_mul_f32 v[12:13], v[12:13], v[148:149]
	v_pk_mul_f32 v[150:151], v[152:153], v[150:151]
	v_max_f32_e32 v152, v163, v163
	v_max_f32_e32 v152, 0xda24260, v152
	v_rcp_f32_e32 v155, v152
	v_pk_mul_f32 v[18:19], v[18:19], v[150:151]
	v_pk_mul_f32 v[146:147], v[154:155], v[146:147]
	s_nop 0
	v_pk_mul_f32 v[14:15], v[14:15], v[146:147]
.LBB0_573:
	v_lshlrev_b64 v[2:3], 11, v[2:3]
	s_mov_b64 s[24:25], 0x58000
	v_lshl_add_u64 v[146:147], v[2:3], 0, s[24:25]
	v_lshl_add_u64 v[2:3], s[22:23], 0, v[146:147]
	v_lshl_add_u64 v[144:145], v[2:3], 0, v[0:1]
	v_lshl_add_u64 v[2:3], s[2:3], 0, v[146:147]
	s_and_b64 vcc, exec, s[6:7]
	v_lshl_add_u64 v[2:3], v[2:3], 0, v[0:1]
	s_mov_b64 s[22:23], -1
	s_nop 1
	v_mov_b32_e32 v162, v216
	v_mov_b32_e32 v163, v217
	v_mov_b32_e32 v164, v218
	v_mov_b32_e32 v165, v219
	v_lshlrev_b32_e32 v154, 16, v162
	v_and_b32_e32 v155, 0xffff0000, v162
	v_lshlrev_b32_e32 v150, 16, v163
	v_and_b32_e32 v151, 0xffff0000, v163
	v_lshlrev_b32_e32 v152, 16, v164
	v_and_b32_e32 v153, 0xffff0000, v164
	v_lshlrev_b32_e32 v148, 16, v165
	v_and_b32_e32 v149, 0xffff0000, v165
	s_cbranch_vccnz .LBB0_575
	v_pk_mul_f32 v[156:157], v[42:43], v[150:151]
	v_pk_mul_f32 v[162:163], v[40:41], v[154:155]
	v_pk_mul_f32 v[192:193], v[38:39], v[148:149]
	v_pk_mul_f32 v[164:165], v[36:37], v[152:153]
	v_cvt_pk_bf16_f32 v162, v162, v163
	v_cvt_pk_bf16_f32 v163, v156, v157
	v_cvt_pk_bf16_f32 v164, v164, v165
	v_cvt_pk_bf16_f32 v165, v192, v193
	s_mov_b64 s[22:23], 0
	global_store_dwordx4 v[2:3], v[162:165], off
.LBB0_575:
	v_lshl_add_u64 v[146:147], s[20:21], 0, v[146:147]
	s_andn2_b64 vcc, exec, s[22:23]
	v_lshl_add_u64 v[146:147], v[146:147], 0, v[0:1]
	s_cbranch_vccnz .LBB0_577
	s_nop 1
	v_mov_b32_e32 v162, v220
	v_mov_b32_e32 v163, v221
	v_mov_b32_e32 v164, v222
	v_mov_b32_e32 v165, v223
	v_lshlrev_b32_e32 v0, 16, v162
	v_max_f32_e32 v0, v0, v0
	v_and_b32_e32 v157, 0xffff0000, v162
	v_lshlrev_b32_e32 v162, 16, v164
	v_max_f32_e32 v0, 0xda24260, v0
	v_rcp_f32_e32 v156, v0
	v_max_f32_e32 v0, v162, v162
	v_max_f32_e32 v0, 0xda24260, v0
	v_rcp_f32_e32 v162, v0
	v_max_f32_e32 v0, v157, v157
	v_lshlrev_b32_e32 v182, 16, v163
	v_and_b32_e32 v192, 0xffff0000, v163
	v_and_b32_e32 v163, 0xffff0000, v164
	v_max_f32_e32 v0, 0xda24260, v0
	v_rcp_f32_e32 v157, v0
	v_max_f32_e32 v0, v163, v163
	v_max_f32_e32 v0, 0xda24260, v0
	v_rcp_f32_e32 v163, v0
	v_max_f32_e32 v0, v182, v182
	v_lshlrev_b32_e32 v164, 16, v165
	v_max_f32_e32 v0, 0xda24260, v0
	v_pk_mul_f32 v[154:155], v[156:157], v[154:155]
	v_rcp_f32_e32 v156, v0
	v_max_f32_e32 v0, v164, v164
	v_max_f32_e32 v0, 0xda24260, v0
	v_pk_mul_f32 v[152:153], v[162:163], v[152:153]
	v_rcp_f32_e32 v162, v0
	v_max_f32_e32 v0, v192, v192
	v_and_b32_e32 v165, 0xffff0000, v165
	v_max_f32_e32 v0, 0xda24260, v0
	v_rcp_f32_e32 v157, v0
	v_max_f32_e32 v0, v165, v165
	v_max_f32_e32 v0, 0xda24260, v0
	v_rcp_f32_e32 v163, v0
	v_pk_mul_f32 v[150:151], v[156:157], v[150:151]
	v_pk_mul_f32 v[40:41], v[40:41], v[154:155]
	v_pk_mul_f32 v[42:43], v[42:43], v[150:151]
	v_pk_mul_f32 v[148:149], v[162:163], v[148:149]
	v_pk_mul_f32 v[36:37], v[36:37], v[152:153]
	v_pk_mul_f32 v[38:39], v[38:39], v[148:149]
.LBB0_577:
	s_and_b64 vcc, exec, s[6:7]
	s_mov_b64 s[6:7], -1
	s_nop 1
	v_mov_b32_e32 v154, v224
	v_mov_b32_e32 v155, v225
	v_mov_b32_e32 v156, v226
	v_mov_b32_e32 v157, v227
	v_lshlrev_b32_e32 v152, 16, v154
	v_and_b32_e32 v153, 0xffff0000, v154
	v_lshlrev_b32_e32 v148, 16, v155
	v_and_b32_e32 v149, 0xffff0000, v155
	v_lshlrev_b32_e32 v150, 16, v156
	v_and_b32_e32 v151, 0xffff0000, v156
	v_lshlrev_b32_e32 v144, 16, v157
	v_and_b32_e32 v145, 0xffff0000, v157
	s_cbranch_vccz .LBB0_580
	s_andn2_b64 vcc, exec, s[6:7]
	s_cbranch_vccz .LBB0_581

; #define GAS __attribute__((address_space(1)))
; __device__ __forceinline__ float bf_lo(unsigned u) { return __uint_as_float(u << 16); }
; __device__ __forceinline__ float bf_hi(unsigned u) { return __uint_as_float(u & 0xffff0000u); }
;     __device__ __forceinline__ void operator()(f32x4 (&acc)[2][2][4][2], const Unit& u, int wr, int wc, int fr, int fq) const {
;     ...
;             for (int m = 0; m < 4; ++m) { const int row = row0 + ai * HALF + m * 16; const GAS bf16_t* gp = ((br < 2) ? g01 + (size_t)br * MROWS * 1024 : g2) + (size_t)row * 1024 + col0; const GAS bf16_t* gn = ((br == 0) ? g01 + (size_t)MROWS * 1024 : g2) + (size_t)row * 1024 + col0; GAS bf16_t* mp = Mg + (size_t)row * 1024 + col0;
; #pragma unroll
;                 for (int bj = 0; bj < 2; ++bj) { const u32x4 g = *(const GAS u32x4*)(gp + bj * HALF);
;                     f32x4 s0 = {bf_lo(g.x), bf_hi(g.x), bf_lo(g.y), bf_hi(g.y)}, s1 = {bf_lo(g.z), bf_hi(g.z), bf_lo(g.w), bf_hi(g.w)};
;                     if (br < 2) { const u32x4 h = *(const GAS u32x4*)(gn + bj * HALF);
;                         const f32x4 d0 = {bf_lo(h.x), bf_hi(h.x), bf_lo(h.y), bf_hi(h.y)}, d1 = {bf_lo(h.z), bf_hi(h.z), bf_lo(h.w), bf_hi(h.w)};
; #pragma unroll
;                         for (int e = 0; e < 4; ++e) { s0[e] *= __builtin_amdgcn_rcpf(fmaxf(d0[e], 1e-30f)); s1[e] *= __builtin_amdgcn_rcpf(fmaxf(d1[e], 1e-30f)); }
;                         acc[ai][bj][m][0] *= s0; acc[ai][bj][m][1] *= s1;
.LBB0_581:
	s_nop 1
	v_mov_b32_e32 v154, v228
	v_mov_b32_e32 v155, v229
	v_mov_b32_e32 v156, v230
	v_mov_b32_e32 v157, v231
	v_lshlrev_b32_e32 v0, 16, v154
	v_max_f32_e32 v0, v0, v0
	v_lshlrev_b32_e32 v146, 16, v156
	v_max_f32_e32 v0, 0xda24260, v0
	v_rcp_f32_e32 v2, v0
	v_max_f32_e32 v0, v146, v146
	v_and_b32_e32 v3, 0xffff0000, v154
	v_max_f32_e32 v0, 0xda24260, v0
	v_rcp_f32_e32 v146, v0
	v_max_f32_e32 v0, v3, v3
	v_and_b32_e32 v147, 0xffff0000, v156
	v_max_f32_e32 v0, 0xda24260, v0
	v_rcp_f32_e32 v3, v0
	v_max_f32_e32 v0, v147, v147
	v_max_f32_e32 v0, 0xda24260, v0
	v_rcp_f32_e32 v147, v0
	v_lshlrev_b32_e32 v154, 16, v155
	v_max_f32_e32 v0, v154, v154
	v_lshlrev_b32_e32 v156, 16, v157
	v_max_f32_e32 v0, 0xda24260, v0
	v_pk_mul_f32 v[146:147], v[146:147], v[150:151]
	v_rcp_f32_e32 v150, v0
	v_max_f32_e32 v0, v156, v156
	v_and_b32_e32 v155, 0xffff0000, v155
	v_max_f32_e32 v0, 0xda24260, v0
	v_pk_mul_f32 v[2:3], v[2:3], v[152:153]
	v_rcp_f32_e32 v152, v0
	v_max_f32_e32 v0, v155, v155
	v_and_b32_e32 v157, 0xffff0000, v157
	v_max_f32_e32 v0, 0xda24260, v0
	v_rcp_f32_e32 v151, v0
	v_max_f32_e32 v0, v157, v157
	v_max_f32_e32 v0, 0xda24260, v0
	v_rcp_f32_e32 v153, v0
	v_pk_mul_f32 v[148:149], v[150:151], v[148:149]
	v_pk_mul_f32 v[8:9], v[8:9], v[2:3]
	v_pk_mul_f32 v[10:11], v[10:11], v[148:149]
	v_pk_mul_f32 v[144:145], v[152:153], v[144:145]
	v_pk_mul_f32 v[4:5], v[4:5], v[146:147]
	v_pk_mul_f32 v[6:7], v[6:7], v[144:145]
	s_andn2_b64 vcc, exec, s[18:19]
	s_mov_b64 s[6:7], -1
	s_cbranch_vccnz .LBB0_510

; #define GAS __attribute__((address_space(1)))
; __device__ __forceinline__ unsigned cvt_pk_bf16(float lo, float hi) { f32x2 v = {lo, hi}; bf16x2_t b = __builtin_convertvector(v, bf16x2_t); return __builtin_bit_cast(unsigned, b); }
; __device__ __forceinline__ float bf_lo(unsigned u) { return __uint_as_float(u << 16); }
; __device__ __forceinline__ float bf_hi(unsigned u) { return __uint_as_float(u & 0xffff0000u); }
;     __device__ __forceinline__ void operator()(const f32x4 (&acc)[2][2][4][2], const Unit& u, int wr, int wc, int fr, int fq) const {
;         const int row0 = u.pm * BM + wr * 64 + fr; const int col0 = u.pn * BM + wc * 32 + 8 * fq;
; #pragma unroll
;         for (int ai = 0; ai < 2; ++ai)
; #pragma unroll
;             for (int m = 0; m < 4; ++m) { const int row = row0 + ai * HALF + m * 16; const size_t off = (size_t)row * 1024 + col0; float q = 0.f;
; #pragma unroll
;                 for (int bj = 0; bj < 2; ++bj) { const u32x4 xo = *(const GAS u32x4*)(xb + off + bj * HALF);
;                     f32x4 v0 = acc[ai][bj][m][0], v1 = acc[ai][bj][m][1];
;                     v0[0] += bf_lo(xo.x); v0[1] += bf_hi(xo.x); v0[2] += bf_lo(xo.y); v0[3] += bf_hi(xo.y); v1[0] += bf_lo(xo.z); v1[1] += bf_hi(xo.z); v1[2] += bf_lo(xo.w); v1[3] += bf_hi(xo.w);
;                     if (out) { *(GAS f32x4*)(out + off + bj * HALF) = v0; *(GAS f32x4*)(out + off + bj * HALF + 4) = v1; }
;                     u32x4 w; w.x = cvt_pk_bf16(v0[0], v0[1]); w.y = cvt_pk_bf16(v0[2], v0[3]); w.z = cvt_pk_bf16(v1[0], v1[1]); w.w = cvt_pk_bf16(v1[2], v1[3]);
;                     *(GAS u32x4*)(xb + off + bj * HALF) = w;
;                     q += ((v0[0] * v0[0] + v0[1] * v0[1]) + (v0[2] * v0[2] + v0[3] * v0[3])) + ((v1[0] * v1[0] + v1[1] * v1[1]) + (v1[2] * v1[2] + v1[3] * v1[3])); }
;                 q += __shfl_xor(q, 16); q += __shfl_xor(q, 32);
;                 if (fq == 0) rowss[(size_t)row * 16 + u.pn * 4 + wc] = q; }
.LBB0_666:
	v_and_b32_e32 v144, 64, v240
	v_xor_b32_e32 v143, 16, v240
	v_add_u32_e32 v144, 64, v144
	v_cmp_lt_i32_e32 vcc, v143, v144
	v_lshl_add_u32 v142, s22, 8, v146
	v_lshl_or_b32 v140, s20, 8, v148
	v_cndmask_b32_e32 v143, v240, v143, vcc
	v_lshlrev_b32_e32 v151, 2, v143
	v_xor_b32_e32 v143, 32, v240
	v_cmp_lt_i32_e32 vcc, v143, v144
	v_ashrrev_i32_e32 v141, 31, v140
	s_lshl_b32 s20, s20, 2
	v_cndmask_b32_e32 v143, v240, v143, vcc
	v_lshlrev_b32_e32 v150, 2, v143
	v_ashrrev_i32_e32 v143, 31, v142
	v_lshlrev_b64 v[144:145], 11, v[142:143]
	v_lshl_add_u64 v[144:145], s[2:3], 0, v[144:145]
	v_lshl_add_u64 v[144:145], v[140:141], 1, v[144:145]
	s_ashr_i32 s21, s20, 31
	v_lshlrev_b32_e32 v224, 11, v142
	v_lshl_add_u32 v224, v140, 1, v224
	global_load_dwordx4 v[192:195], v224, s[2:3]
	global_load_dwordx4 v[196:199], v224, s[2:3] offset:256
	v_add_u32_e32 v225, 0x8000, v224
	global_load_dwordx4 v[200:203], v225, s[2:3]
	global_load_dwordx4 v[204:207], v225, s[2:3] offset:256
	v_add_u32_e32 v225, 0x10000, v224
	global_load_dwordx4 v[208:211], v225, s[2:3]
	global_load_dwordx4 v[212:215], v225, s[2:3] offset:256
	v_add_u32_e32 v225, 0x18000, v224
	global_load_dwordx4 v[216:219], v225, s[2:3]
	global_load_dwordx4 v[220:223], v225, s[2:3] offset:256
	s_waitcnt vmcnt(0)
	s_nop 1
	v_mov_b32_e32 v152, v192
	v_mov_b32_e32 v153, v193
	v_mov_b32_e32 v154, v194
	v_mov_b32_e32 v155, v195
	v_lshlrev_b32_e32 v156, 16, v152
	v_and_b32_e32 v157, 0xffff0000, v152
	v_lshlrev_b32_e32 v152, 16, v153
	v_and_b32_e32 v153, 0xffff0000, v153
	v_pk_add_f32 v[128:129], v[128:129], v[152:153]
	v_lshlrev_b32_e32 v152, 16, v154
	v_and_b32_e32 v153, 0xffff0000, v154
	v_pk_add_f32 v[152:153], v[122:123], v[152:153]
	v_lshlrev_b32_e32 v122, 16, v155
	v_and_b32_e32 v123, 0xffff0000, v155
	v_pk_add_f32 v[126:127], v[126:127], v[156:157]
	v_pk_add_f32 v[154:155], v[124:125], v[122:123]
	v_cvt_pk_bf16_f32 v122, v126, v127
	v_cvt_pk_bf16_f32 v123, v128, v129
	v_cvt_pk_bf16_f32 v124, v152, v153
	v_cvt_pk_bf16_f32 v125, v154, v155
	global_store_dwordx4 v[144:145], v[122:125], off
	s_nop 1
	v_pk_mul_f32 v[122:123], v[126:127], v[126:127]
	v_pk_mul_f32 v[124:125], v[128:129], v[128:129]
	v_pk_mul_f32 v[126:127], v[152:153], v[152:153]
	v_pk_mul_f32 v[128:129], v[154:155], v[154:155]
	s_nop 1
	v_mov_b32_e32 v152, v196
	v_mov_b32_e32 v153, v197
	v_mov_b32_e32 v154, v198
	v_mov_b32_e32 v155, v199
	v_lshlrev_b32_e32 v156, 16, v152
	v_and_b32_e32 v157, 0xffff0000, v152
	v_lshlrev_b32_e32 v152, 16, v153
	v_and_b32_e32 v153, 0xffff0000, v153
	v_pk_add_f32 v[120:121], v[120:121], v[152:153]
	v_lshlrev_b32_e32 v152, 16, v154
	v_and_b32_e32 v153, 0xffff0000, v154
	v_pk_add_f32 v[152:153], v[114:115], v[152:153]
	v_lshlrev_b32_e32 v114, 16, v155
	v_and_b32_e32 v115, 0xffff0000, v155
	v_pk_add_f32 v[118:119], v[118:119], v[156:157]
	v_pk_add_f32 v[154:155], v[116:117], v[114:115]
	v_cvt_pk_bf16_f32 v114, v118, v119
	v_cvt_pk_bf16_f32 v115, v120, v121
	v_cvt_pk_bf16_f32 v116, v152, v153
	v_cvt_pk_bf16_f32 v117, v154, v155
	global_store_dwordx4 v[144:145], v[114:117], off offset:256
	s_nop 1
	v_pk_mul_f32 v[114:115], v[118:119], v[118:119]
	v_pk_mul_f32 v[116:117], v[120:121], v[120:121]
	v_add_f32_e32 v114, v114, v115
	v_add_f32_e32 v116, v116, v117
	v_pk_mul_f32 v[118:119], v[152:153], v[152:153]
	v_pk_mul_f32 v[120:121], v[154:155], v[154:155]
	v_add_f32_e32 v114, v114, v116
	v_add_f32_e32 v115, v128, v129
	v_add_f32_e32 v116, v126, v127
	v_add_f32_e32 v120, v120, v121
	v_add_f32_e32 v118, v118, v119
	v_add_f32_e32 v115, v116, v115
	v_add_f32_e32 v116, v124, v125
	v_add_f32_e32 v117, v122, v123
	v_add_f32_e32 v118, v118, v120
	v_add_f32_e32 v116, v117, v116
	v_add_f32_e32 v114, v114, v118
	v_add_f32_e32 v115, v116, v115
	v_add_f32_e32 v114, v115, v114
	ds_bpermute_b32 v115, v151, v114
	s_waitcnt lgkmcnt(0)
	v_add_f32_e32 v114, v114, v115
	ds_bpermute_b32 v115, v150, v114
	s_and_saveexec_b64 s[22:23], s[6:7]
	s_mov_b32 s28, s58
	s_cbranch_execz .LBB0_668
	v_lshlrev_b64 v[116:117], 6, v[142:143]
	v_lshl_add_u64 v[116:117], s[4:5], 0, v[116:117]
	v_lshl_add_u64 v[116:117], s[20:21], 2, v[116:117]
	s_lshl_b32 s72, s42, 2
	v_lshl_add_u64 v[116:117], v[116:117], 0, s[72:73]
	s_waitcnt lgkmcnt(0)
	v_add_f32_e32 v114, v114, v115
	global_store_dword v[116:117], v114, off
; #define GAS __attribute__((address_space(1)))
; __device__ __forceinline__ unsigned cvt_pk_bf16(float lo, float hi) { f32x2 v = {lo, hi}; bf16x2_t b = __builtin_convertvector(v, bf16x2_t); return __builtin_bit_cast(unsigned, b); }
; __device__ __forceinline__ float bf_lo(unsigned u) { return __uint_as_float(u << 16); }
; __device__ __forceinline__ float bf_hi(unsigned u) { return __uint_as_float(u & 0xffff0000u); }
;     __device__ __forceinline__ void operator()(const f32x4 (&acc)[2][2][4][2], const Unit& u, int wr, int wc, int fr, int fq) const {
;     ...
;             for (int m = 0; m < 4; ++m) { const int row = row0 + ai * HALF + m * 16; const size_t off = (size_t)row * 1024 + col0; float q = 0.f;
; #pragma unroll
;                 for (int bj = 0; bj < 2; ++bj) { const u32x4 xo = *(const GAS u32x4*)(xb + off + bj * HALF);
;                     f32x4 v0 = acc[ai][bj][m][0], v1 = acc[ai][bj][m][1];
;                     v0[0] += bf_lo(xo.x); v0[1] += bf_hi(xo.x); v0[2] += bf_lo(xo.y); v0[3] += bf_hi(xo.y); v1[0] += bf_lo(xo.z); v1[1] += bf_hi(xo.z); v1[2] += bf_lo(xo.w); v1[3] += bf_hi(xo.w);
;                     if (out) { *(GAS f32x4*)(out + off + bj * HALF) = v0; *(GAS f32x4*)(out + off + bj * HALF + 4) = v1; }
;                     u32x4 w; w.x = cvt_pk_bf16(v0[0], v0[1]); w.y = cvt_pk_bf16(v0[2], v0[3]); w.z = cvt_pk_bf16(v1[0], v1[1]); w.w = cvt_pk_bf16(v1[2], v1[3]);
;                     *(GAS u32x4*)(xb + off + bj * HALF) = w;
;                     q += ((v0[0] * v0[0] + v0[1] * v0[1]) + (v0[2] * v0[2] + v0[3] * v0[3])) + ((v1[0] * v1[0] + v1[1] * v1[1]) + (v1[2] * v1[2] + v1[3] * v1[3])); }
;                 q += __shfl_xor(q, 16); q += __shfl_xor(q, 32);
;                 if (fq == 0) rowss[(size_t)row * 16 + u.pn * 4 + wc] = q; }
.LBB0_668:
	s_or_b64 exec, exec, s[22:23]
	v_or_b32_e32 v114, 16, v142
	s_waitcnt lgkmcnt(0)
	v_ashrrev_i32_e32 v115, 31, v114
	v_lshlrev_b64 v[116:117], 11, v[114:115]
	v_lshl_add_u64 v[116:117], s[2:3], 0, v[116:117]
	v_lshl_add_u64 v[120:121], v[140:141], 1, v[116:117]
	s_nop 1
	v_mov_b32_e32 v116, v200
	v_mov_b32_e32 v117, v201
	v_mov_b32_e32 v118, v202
	v_mov_b32_e32 v119, v203
	v_lshlrev_b32_e32 v122, 16, v116
	v_and_b32_e32 v123, 0xffff0000, v116
	v_lshlrev_b32_e32 v116, 16, v117
	v_and_b32_e32 v117, 0xffff0000, v117
	v_pk_add_f32 v[112:113], v[112:113], v[116:117]
	v_lshlrev_b32_e32 v116, 16, v118
	v_and_b32_e32 v117, 0xffff0000, v118
	v_pk_add_f32 v[116:117], v[106:107], v[116:117]
	v_lshlrev_b32_e32 v106, 16, v119
	v_and_b32_e32 v107, 0xffff0000, v119
	v_pk_add_f32 v[110:111], v[110:111], v[122:123]
	v_pk_add_f32 v[118:119], v[108:109], v[106:107]
	v_cvt_pk_bf16_f32 v106, v110, v111
	v_cvt_pk_bf16_f32 v107, v112, v113
	v_cvt_pk_bf16_f32 v108, v116, v117
	v_cvt_pk_bf16_f32 v109, v118, v119
	global_store_dwordx4 v[120:121], v[106:109], off
	s_nop 1
	v_pk_mul_f32 v[106:107], v[110:111], v[110:111]
	v_pk_mul_f32 v[108:109], v[112:113], v[112:113]
	v_pk_mul_f32 v[110:111], v[116:117], v[116:117]
	v_pk_mul_f32 v[112:113], v[118:119], v[118:119]
	s_nop 1
	v_mov_b32_e32 v116, v204
	v_mov_b32_e32 v117, v205
	v_mov_b32_e32 v118, v206
	v_mov_b32_e32 v119, v207
	v_lshlrev_b32_e32 v122, 16, v116
	v_and_b32_e32 v123, 0xffff0000, v116
	v_lshlrev_b32_e32 v116, 16, v117
	v_and_b32_e32 v117, 0xffff0000, v117
	v_pk_add_f32 v[104:105], v[104:105], v[116:117]
	v_lshlrev_b32_e32 v116, 16, v118
	v_and_b32_e32 v117, 0xffff0000, v118
	v_pk_add_f32 v[116:117], v[98:99], v[116:117]
	v_lshlrev_b32_e32 v98, 16, v119
	v_and_b32_e32 v99, 0xffff0000, v119
	v_pk_add_f32 v[102:103], v[102:103], v[122:123]
	v_pk_add_f32 v[118:119], v[100:101], v[98:99]
	v_cvt_pk_bf16_f32 v98, v102, v103
	v_cvt_pk_bf16_f32 v99, v104, v105
	v_cvt_pk_bf16_f32 v100, v116, v117
	v_cvt_pk_bf16_f32 v101, v118, v119
	global_store_dwordx4 v[120:121], v[98:101], off offset:256
	s_nop 1
	v_pk_mul_f32 v[98:99], v[102:103], v[102:103]
	v_pk_mul_f32 v[100:101], v[104:105], v[104:105]
	v_add_f32_e32 v98, v98, v99
	v_add_f32_e32 v100, v100, v101
	v_pk_mul_f32 v[102:103], v[116:117], v[116:117]
	v_pk_mul_f32 v[104:105], v[118:119], v[118:119]
	v_add_f32_e32 v98, v98, v100
	v_add_f32_e32 v99, v112, v113
	v_add_f32_e32 v100, v110, v111
	v_add_f32_e32 v104, v104, v105
	v_add_f32_e32 v102, v102, v103
	v_add_f32_e32 v99, v100, v99
	v_add_f32_e32 v100, v108, v109
	v_add_f32_e32 v101, v106, v107
	v_add_f32_e32 v102, v102, v104
	v_add_f32_e32 v100, v101, v100
	v_add_f32_e32 v98, v98, v102
	v_add_f32_e32 v99, v100, v99
	v_add_f32_e32 v98, v99, v98
	ds_bpermute_b32 v99, v151, v98
	s_waitcnt lgkmcnt(0)
	v_add_f32_e32 v98, v98, v99
	ds_bpermute_b32 v99, v150, v98
	s_and_saveexec_b64 s[22:23], s[6:7]
	s_cbranch_execz .LBB0_670
	v_lshlrev_b64 v[100:101], 6, v[114:115]
	v_lshl_add_u64 v[100:101], s[4:5], 0, v[100:101]
	v_lshl_add_u64 v[100:101], s[20:21], 2, v[100:101]
	s_lshl_b32 s72, s42, 2
	v_lshl_add_u64 v[100:101], v[100:101], 0, s[72:73]
	s_waitcnt lgkmcnt(0)
	v_add_f32_e32 v98, v98, v99
	global_store_dword v[100:101], v98, off
.LBB0_670:
	s_or_b64 exec, exec, s[22:23]
	v_or_b32_e32 v98, 32, v142
	s_waitcnt lgkmcnt(0)
	v_ashrrev_i32_e32 v99, 31, v98
	v_lshlrev_b64 v[100:101], 11, v[98:99]
	v_lshl_add_u64 v[100:101], s[2:3], 0, v[100:101]
	v_lshl_add_u64 v[104:105], v[140:141], 1, v[100:101]
	s_nop 1
	v_mov_b32_e32 v100, v208
	v_mov_b32_e32 v101, v209
	v_mov_b32_e32 v102, v210
	v_mov_b32_e32 v103, v211
	v_lshlrev_b32_e32 v106, 16, v100
	v_and_b32_e32 v107, 0xffff0000, v100
	v_lshlrev_b32_e32 v100, 16, v101
	v_and_b32_e32 v101, 0xffff0000, v101
	v_pk_add_f32 v[96:97], v[96:97], v[100:101]
	v_lshlrev_b32_e32 v100, 16, v102
	v_and_b32_e32 v101, 0xffff0000, v102
	v_pk_add_f32 v[100:101], v[90:91], v[100:101]
	v_lshlrev_b32_e32 v90, 16, v103
	v_and_b32_e32 v91, 0xffff0000, v103
	v_pk_add_f32 v[94:95], v[94:95], v[106:107]
	v_pk_add_f32 v[102:103], v[92:93], v[90:91]
	v_cvt_pk_bf16_f32 v90, v94, v95
	v_cvt_pk_bf16_f32 v91, v96, v97
	v_cvt_pk_bf16_f32 v92, v100, v101
	v_cvt_pk_bf16_f32 v93, v102, v103
	global_store_dwordx4 v[104:105], v[90:93], off
	s_nop 1
	v_pk_mul_f32 v[90:91], v[94:95], v[94:95]
	v_pk_mul_f32 v[92:93], v[96:97], v[96:97]
	v_pk_mul_f32 v[94:95], v[100:101], v[100:101]
	v_pk_mul_f32 v[96:97], v[102:103], v[102:103]
	s_nop 1
	v_mov_b32_e32 v100, v212
	v_mov_b32_e32 v101, v213
	v_mov_b32_e32 v102, v214
	v_mov_b32_e32 v103, v215
	v_lshlrev_b32_e32 v106, 16, v100
	v_and_b32_e32 v107, 0xffff0000, v100
	v_lshlrev_b32_e32 v100, 16, v101
	v_and_b32_e32 v101, 0xffff0000, v101
	v_pk_add_f32 v[88:89], v[88:89], v[100:101]
	v_lshlrev_b32_e32 v100, 16, v102
	v_and_b32_e32 v101, 0xffff0000, v102
	v_pk_add_f32 v[100:101], v[82:83], v[100:101]
	v_lshlrev_b32_e32 v82, 16, v103
	v_and_b32_e32 v83, 0xffff0000, v103
	v_pk_add_f32 v[86:87], v[86:87], v[106:107]
	v_pk_add_f32 v[102:103], v[84:85], v[82:83]
	v_cvt_pk_bf16_f32 v82, v86, v87
	v_cvt_pk_bf16_f32 v83, v88, v89
	v_cvt_pk_bf16_f32 v84, v100, v101
	v_cvt_pk_bf16_f32 v85, v102, v103
	global_store_dwordx4 v[104:105], v[82:85], off offset:256
	s_nop 1
	v_pk_mul_f32 v[82:83], v[86:87], v[86:87]
	v_pk_mul_f32 v[84:85], v[88:89], v[88:89]
	v_add_f32_e32 v82, v82, v83
	v_add_f32_e32 v84, v84, v85
	v_pk_mul_f32 v[86:87], v[100:101], v[100:101]
	v_pk_mul_f32 v[88:89], v[102:103], v[102:103]
	v_add_f32_e32 v82, v82, v84
	v_add_f32_e32 v83, v96, v97
	v_add_f32_e32 v84, v94, v95
	v_add_f32_e32 v88, v88, v89
	v_add_f32_e32 v86, v86, v87
	v_add_f32_e32 v83, v84, v83
	v_add_f32_e32 v84, v92, v93
	v_add_f32_e32 v85, v90, v91
	v_add_f32_e32 v86, v86, v88
	v_add_f32_e32 v84, v85, v84
	v_add_f32_e32 v82, v82, v86
	v_add_f32_e32 v83, v84, v83
	v_add_f32_e32 v82, v83, v82
	ds_bpermute_b32 v83, v151, v82
	s_waitcnt lgkmcnt(0)
	v_add_f32_e32 v82, v82, v83
	ds_bpermute_b32 v83, v150, v82
	s_and_saveexec_b64 s[22:23], s[6:7]
	s_cbranch_execz .LBB0_672
	v_lshlrev_b64 v[84:85], 6, v[98:99]
	v_lshl_add_u64 v[84:85], s[4:5], 0, v[84:85]
	v_lshl_add_u64 v[84:85], s[20:21], 2, v[84:85]
	s_lshl_b32 s72, s42, 2
	v_lshl_add_u64 v[84:85], v[84:85], 0, s[72:73]
	s_waitcnt lgkmcnt(0)
	v_add_f32_e32 v82, v82, v83
	global_store_dword v[84:85], v82, off
; #define GAS __attribute__((address_space(1)))
; __device__ __forceinline__ unsigned cvt_pk_bf16(float lo, float hi) { f32x2 v = {lo, hi}; bf16x2_t b = __builtin_convertvector(v, bf16x2_t); return __builtin_bit_cast(unsigned, b); }
; __device__ __forceinline__ float bf_lo(unsigned u) { return __uint_as_float(u << 16); }
; __device__ __forceinline__ float bf_hi(unsigned u) { return __uint_as_float(u & 0xffff0000u); }
;     __device__ __forceinline__ void operator()(const f32x4 (&acc)[2][2][4][2], const Unit& u, int wr, int wc, int fr, int fq) const {
;     ...
;             for (int m = 0; m < 4; ++m) { const int row = row0 + ai * HALF + m * 16; const size_t off = (size_t)row * 1024 + col0; float q = 0.f;
; #pragma unroll
;                 for (int bj = 0; bj < 2; ++bj) { const u32x4 xo = *(const GAS u32x4*)(xb + off + bj * HALF);
;                     f32x4 v0 = acc[ai][bj][m][0], v1 = acc[ai][bj][m][1];
;                     v0[0] += bf_lo(xo.x); v0[1] += bf_hi(xo.x); v0[2] += bf_lo(xo.y); v0[3] += bf_hi(xo.y); v1[0] += bf_lo(xo.z); v1[1] += bf_hi(xo.z); v1[2] += bf_lo(xo.w); v1[3] += bf_hi(xo.w);
;                     if (out) { *(GAS f32x4*)(out + off + bj * HALF) = v0; *(GAS f32x4*)(out + off + bj * HALF + 4) = v1; }
;                     u32x4 w; w.x = cvt_pk_bf16(v0[0], v0[1]); w.y = cvt_pk_bf16(v0[2], v0[3]); w.z = cvt_pk_bf16(v1[0], v1[1]); w.w = cvt_pk_bf16(v1[2], v1[3]);
;                     *(GAS u32x4*)(xb + off + bj * HALF) = w;
;                     q += ((v0[0] * v0[0] + v0[1] * v0[1]) + (v0[2] * v0[2] + v0[3] * v0[3])) + ((v1[0] * v1[0] + v1[1] * v1[1]) + (v1[2] * v1[2] + v1[3] * v1[3])); }
;                 q += __shfl_xor(q, 16); q += __shfl_xor(q, 32);
;                 if (fq == 0) rowss[(size_t)row * 16 + u.pn * 4 + wc] = q; }
.LBB0_672:
	s_or_b64 exec, exec, s[22:23]
	v_or_b32_e32 v82, 48, v142
	s_waitcnt lgkmcnt(0)
	v_ashrrev_i32_e32 v83, 31, v82
	v_lshlrev_b64 v[84:85], 11, v[82:83]
	v_lshl_add_u64 v[84:85], s[2:3], 0, v[84:85]
	v_lshl_add_u64 v[88:89], v[140:141], 1, v[84:85]
	s_nop 1
	v_mov_b32_e32 v84, v216
	v_mov_b32_e32 v85, v217
	v_mov_b32_e32 v86, v218
	v_mov_b32_e32 v87, v219
	v_lshlrev_b32_e32 v90, 16, v84
	v_and_b32_e32 v91, 0xffff0000, v84
	v_lshlrev_b32_e32 v84, 16, v85
	v_and_b32_e32 v85, 0xffff0000, v85
	v_pk_add_f32 v[80:81], v[80:81], v[84:85]
	v_lshlrev_b32_e32 v84, 16, v86
	v_and_b32_e32 v85, 0xffff0000, v86
	v_pk_add_f32 v[84:85], v[74:75], v[84:85]
	v_lshlrev_b32_e32 v74, 16, v87
	v_and_b32_e32 v75, 0xffff0000, v87
	v_pk_add_f32 v[78:79], v[78:79], v[90:91]
	v_pk_add_f32 v[86:87], v[76:77], v[74:75]
	v_cvt_pk_bf16_f32 v74, v78, v79
	v_cvt_pk_bf16_f32 v75, v80, v81
	v_cvt_pk_bf16_f32 v76, v84, v85
	v_cvt_pk_bf16_f32 v77, v86, v87
	global_store_dwordx4 v[88:89], v[74:77], off
	s_nop 1
	v_pk_mul_f32 v[74:75], v[78:79], v[78:79]
	v_pk_mul_f32 v[76:77], v[80:81], v[80:81]
	v_pk_mul_f32 v[78:79], v[84:85], v[84:85]
	v_pk_mul_f32 v[80:81], v[86:87], v[86:87]
	s_nop 1
	v_mov_b32_e32 v84, v220
	v_mov_b32_e32 v85, v221
	v_mov_b32_e32 v86, v222
	v_mov_b32_e32 v87, v223
	v_lshlrev_b32_e32 v90, 16, v84
	v_and_b32_e32 v91, 0xffff0000, v84
	v_lshlrev_b32_e32 v84, 16, v85
	v_and_b32_e32 v85, 0xffff0000, v85
	v_pk_add_f32 v[72:73], v[72:73], v[84:85]
	v_lshlrev_b32_e32 v84, 16, v86
	v_and_b32_e32 v85, 0xffff0000, v86
	v_pk_add_f32 v[84:85], v[66:67], v[84:85]
	v_lshlrev_b32_e32 v66, 16, v87
	v_and_b32_e32 v67, 0xffff0000, v87
	v_pk_add_f32 v[70:71], v[70:71], v[90:91]
	v_pk_add_f32 v[86:87], v[68:69], v[66:67]
	v_cvt_pk_bf16_f32 v66, v70, v71
	v_cvt_pk_bf16_f32 v67, v72, v73
	v_cvt_pk_bf16_f32 v68, v84, v85
	v_cvt_pk_bf16_f32 v69, v86, v87
	global_store_dwordx4 v[88:89], v[66:69], off offset:256
	s_nop 1
	v_pk_mul_f32 v[66:67], v[70:71], v[70:71]
	v_pk_mul_f32 v[68:69], v[72:73], v[72:73]
	v_add_f32_e32 v66, v66, v67
	v_add_f32_e32 v68, v68, v69
	v_pk_mul_f32 v[70:71], v[84:85], v[84:85]
	v_pk_mul_f32 v[72:73], v[86:87], v[86:87]
	v_add_f32_e32 v66, v66, v68
	v_add_f32_e32 v67, v80, v81
	v_add_f32_e32 v68, v78, v79
	v_add_f32_e32 v72, v72, v73
	v_add_f32_e32 v70, v70, v71
	v_add_f32_e32 v67, v68, v67
	v_add_f32_e32 v68, v76, v77
	v_add_f32_e32 v69, v74, v75
	v_add_f32_e32 v70, v70, v72
	v_add_f32_e32 v68, v69, v68
	v_add_f32_e32 v66, v66, v70
	v_add_f32_e32 v67, v68, v67
	v_add_f32_e32 v66, v67, v66
	ds_bpermute_b32 v67, v151, v66
	s_waitcnt lgkmcnt(0)
	v_add_f32_e32 v66, v66, v67
	ds_bpermute_b32 v67, v150, v66
	s_and_saveexec_b64 s[22:23], s[6:7]
	s_cbranch_execz .LBB0_674
	v_lshlrev_b64 v[68:69], 6, v[82:83]
	v_lshl_add_u64 v[68:69], s[4:5], 0, v[68:69]
	v_lshl_add_u64 v[68:69], s[20:21], 2, v[68:69]
	s_lshl_b32 s72, s42, 2
	v_lshl_add_u64 v[68:69], v[68:69], 0, s[72:73]
	s_waitcnt lgkmcnt(0)
	v_add_f32_e32 v66, v66, v67
	global_store_dword v[68:69], v66, off
.LBB0_674:
	s_or_b64 exec, exec, s[22:23]
	v_add_u32_e32 v66, 0x80, v142
	s_waitcnt lgkmcnt(0)
	v_ashrrev_i32_e32 v67, 31, v66
	v_lshlrev_b64 v[68:69], 11, v[66:67]
	v_lshl_add_u64 v[68:69], s[2:3], 0, v[68:69]
	v_lshl_add_u64 v[72:73], v[140:141], 1, v[68:69]
	v_add_u32_e32 v225, 0x40000, v224
	global_load_dwordx4 v[192:195], v225, s[2:3]
	global_load_dwordx4 v[196:199], v225, s[2:3] offset:256
	v_add_u32_e32 v225, 0x48000, v224
	global_load_dwordx4 v[200:203], v225, s[2:3]
	global_load_dwordx4 v[204:207], v225, s[2:3] offset:256
	v_add_u32_e32 v225, 0x50000, v224
	global_load_dwordx4 v[208:211], v225, s[2:3]
	global_load_dwordx4 v[212:215], v225, s[2:3] offset:256
	v_add_u32_e32 v225, 0x58000, v224
	global_load_dwordx4 v[216:219], v225, s[2:3]
	global_load_dwordx4 v[220:223], v225, s[2:3] offset:256
	s_waitcnt vmcnt(0)
	s_nop 1
	v_mov_b32_e32 v68, v192
	v_mov_b32_e32 v69, v193
	v_mov_b32_e32 v70, v194
	v_mov_b32_e32 v71, v195
	v_lshlrev_b32_e32 v74, 16, v68
	v_and_b32_e32 v75, 0xffff0000, v68
	v_lshlrev_b32_e32 v68, 16, v69
	v_and_b32_e32 v69, 0xffff0000, v69
	v_pk_add_f32 v[64:65], v[64:65], v[68:69]
	v_lshlrev_b32_e32 v68, 16, v70
	v_and_b32_e32 v69, 0xffff0000, v70
	v_pk_add_f32 v[68:69], v[58:59], v[68:69]
	v_lshlrev_b32_e32 v58, 16, v71
	v_and_b32_e32 v59, 0xffff0000, v71
	v_pk_add_f32 v[62:63], v[62:63], v[74:75]
	v_pk_add_f32 v[70:71], v[60:61], v[58:59]
	v_cvt_pk_bf16_f32 v58, v62, v63
	v_cvt_pk_bf16_f32 v59, v64, v65
	v_cvt_pk_bf16_f32 v60, v68, v69
	v_cvt_pk_bf16_f32 v61, v70, v71
	global_store_dwordx4 v[72:73], v[58:61], off
	s_nop 1
	v_pk_mul_f32 v[58:59], v[62:63], v[62:63]
	v_pk_mul_f32 v[60:61], v[64:65], v[64:65]
	v_pk_mul_f32 v[62:63], v[68:69], v[68:69]
	v_pk_mul_f32 v[64:65], v[70:71], v[70:71]
	s_nop 1
	v_mov_b32_e32 v68, v196
	v_mov_b32_e32 v69, v197
	v_mov_b32_e32 v70, v198
	v_mov_b32_e32 v71, v199
	v_lshlrev_b32_e32 v74, 16, v68
	v_and_b32_e32 v75, 0xffff0000, v68
	v_lshlrev_b32_e32 v68, 16, v69
	v_and_b32_e32 v69, 0xffff0000, v69
	v_pk_add_f32 v[56:57], v[56:57], v[68:69]
	v_lshlrev_b32_e32 v68, 16, v70
	v_and_b32_e32 v69, 0xffff0000, v70
	v_pk_add_f32 v[68:69], v[50:51], v[68:69]
	v_lshlrev_b32_e32 v50, 16, v71
	v_and_b32_e32 v51, 0xffff0000, v71
	v_pk_add_f32 v[54:55], v[54:55], v[74:75]
	v_pk_add_f32 v[70:71], v[52:53], v[50:51]
	v_cvt_pk_bf16_f32 v50, v54, v55
	v_cvt_pk_bf16_f32 v51, v56, v57
	v_cvt_pk_bf16_f32 v52, v68, v69
	v_cvt_pk_bf16_f32 v53, v70, v71
	global_store_dwordx4 v[72:73], v[50:53], off offset:256
	s_nop 1
	v_pk_mul_f32 v[50:51], v[54:55], v[54:55]
	v_pk_mul_f32 v[52:53], v[56:57], v[56:57]
	v_add_f32_e32 v50, v50, v51
	v_add_f32_e32 v52, v52, v53
	v_pk_mul_f32 v[54:55], v[68:69], v[68:69]
	v_pk_mul_f32 v[56:57], v[70:71], v[70:71]
	v_add_f32_e32 v50, v50, v52
	v_add_f32_e32 v51, v64, v65
	v_add_f32_e32 v52, v62, v63
	v_add_f32_e32 v56, v56, v57
	v_add_f32_e32 v54, v54, v55
	v_add_f32_e32 v51, v52, v51
	v_add_f32_e32 v52, v60, v61
	v_add_f32_e32 v53, v58, v59
	v_add_f32_e32 v54, v54, v56
	v_add_f32_e32 v52, v53, v52
	v_add_f32_e32 v50, v50, v54
	v_add_f32_e32 v51, v52, v51
	v_add_f32_e32 v50, v51, v50
	ds_bpermute_b32 v51, v151, v50
	s_waitcnt lgkmcnt(0)
	v_add_f32_e32 v50, v50, v51
	ds_bpermute_b32 v51, v150, v50
	s_and_saveexec_b64 s[22:23], s[6:7]
	s_cbranch_execz .LBB0_676
	v_lshlrev_b64 v[52:53], 6, v[66:67]
	v_lshl_add_u64 v[52:53], s[4:5], 0, v[52:53]
	v_lshl_add_u64 v[52:53], s[20:21], 2, v[52:53]
	s_lshl_b32 s72, s42, 2
	v_lshl_add_u64 v[52:53], v[52:53], 0, s[72:73]
	s_waitcnt lgkmcnt(0)
	v_add_f32_e32 v50, v50, v51
	global_store_dword v[52:53], v50, off
; #define GAS __attribute__((address_space(1)))
; __device__ __forceinline__ unsigned cvt_pk_bf16(float lo, float hi) { f32x2 v = {lo, hi}; bf16x2_t b = __builtin_convertvector(v, bf16x2_t); return __builtin_bit_cast(unsigned, b); }
; __device__ __forceinline__ float bf_lo(unsigned u) { return __uint_as_float(u << 16); }
; __device__ __forceinline__ float bf_hi(unsigned u) { return __uint_as_float(u & 0xffff0000u); }
;     __device__ __forceinline__ void operator()(const f32x4 (&acc)[2][2][4][2], const Unit& u, int wr, int wc, int fr, int fq) const {
;     ...
;             for (int m = 0; m < 4; ++m) { const int row = row0 + ai * HALF + m * 16; const size_t off = (size_t)row * 1024 + col0; float q = 0.f;
; #pragma unroll
;                 for (int bj = 0; bj < 2; ++bj) { const u32x4 xo = *(const GAS u32x4*)(xb + off + bj * HALF);
;                     f32x4 v0 = acc[ai][bj][m][0], v1 = acc[ai][bj][m][1];
;                     v0[0] += bf_lo(xo.x); v0[1] += bf_hi(xo.x); v0[2] += bf_lo(xo.y); v0[3] += bf_hi(xo.y); v1[0] += bf_lo(xo.z); v1[1] += bf_hi(xo.z); v1[2] += bf_lo(xo.w); v1[3] += bf_hi(xo.w);
;                     if (out) { *(GAS f32x4*)(out + off + bj * HALF) = v0; *(GAS f32x4*)(out + off + bj * HALF + 4) = v1; }
;                     u32x4 w; w.x = cvt_pk_bf16(v0[0], v0[1]); w.y = cvt_pk_bf16(v0[2], v0[3]); w.z = cvt_pk_bf16(v1[0], v1[1]); w.w = cvt_pk_bf16(v1[2], v1[3]);
;                     *(GAS u32x4*)(xb + off + bj * HALF) = w;
;                     q += ((v0[0] * v0[0] + v0[1] * v0[1]) + (v0[2] * v0[2] + v0[3] * v0[3])) + ((v1[0] * v1[0] + v1[1] * v1[1]) + (v1[2] * v1[2] + v1[3] * v1[3])); }
;                 q += __shfl_xor(q, 16); q += __shfl_xor(q, 32);
;                 if (fq == 0) rowss[(size_t)row * 16 + u.pn * 4 + wc] = q; }
.LBB0_676:
	s_or_b64 exec, exec, s[22:23]
	v_add_u32_e32 v50, 0x90, v142
	s_waitcnt lgkmcnt(0)
	v_ashrrev_i32_e32 v51, 31, v50
	v_lshlrev_b64 v[52:53], 11, v[50:51]
	v_lshl_add_u64 v[52:53], s[2:3], 0, v[52:53]
	v_lshl_add_u64 v[56:57], v[140:141], 1, v[52:53]
	s_nop 1
	v_mov_b32_e32 v52, v200
	v_mov_b32_e32 v53, v201
	v_mov_b32_e32 v54, v202
	v_mov_b32_e32 v55, v203
	v_lshlrev_b32_e32 v58, 16, v52
	v_and_b32_e32 v59, 0xffff0000, v52
	v_lshlrev_b32_e32 v52, 16, v53
	v_and_b32_e32 v53, 0xffff0000, v53
	v_pk_add_f32 v[48:49], v[48:49], v[52:53]
	v_lshlrev_b32_e32 v52, 16, v54
	v_and_b32_e32 v53, 0xffff0000, v54
	v_pk_add_f32 v[52:53], v[42:43], v[52:53]
	v_lshlrev_b32_e32 v42, 16, v55
	v_and_b32_e32 v43, 0xffff0000, v55
	v_pk_add_f32 v[46:47], v[46:47], v[58:59]
	v_pk_add_f32 v[54:55], v[44:45], v[42:43]
	v_cvt_pk_bf16_f32 v42, v46, v47
	v_cvt_pk_bf16_f32 v43, v48, v49
	v_cvt_pk_bf16_f32 v44, v52, v53
	v_cvt_pk_bf16_f32 v45, v54, v55
	global_store_dwordx4 v[56:57], v[42:45], off
	s_nop 1
	v_pk_mul_f32 v[42:43], v[46:47], v[46:47]
	v_pk_mul_f32 v[44:45], v[48:49], v[48:49]
	v_pk_mul_f32 v[46:47], v[52:53], v[52:53]
	v_pk_mul_f32 v[48:49], v[54:55], v[54:55]
	s_nop 1
	v_mov_b32_e32 v52, v204
	v_mov_b32_e32 v53, v205
	v_mov_b32_e32 v54, v206
	v_mov_b32_e32 v55, v207
	v_lshlrev_b32_e32 v58, 16, v52
	v_and_b32_e32 v59, 0xffff0000, v52
	v_lshlrev_b32_e32 v52, 16, v53
	v_and_b32_e32 v53, 0xffff0000, v53
	v_pk_add_f32 v[40:41], v[40:41], v[52:53]
	v_lshlrev_b32_e32 v52, 16, v54
	v_and_b32_e32 v53, 0xffff0000, v54
	v_pk_add_f32 v[52:53], v[34:35], v[52:53]
	v_lshlrev_b32_e32 v34, 16, v55
	v_and_b32_e32 v35, 0xffff0000, v55
	v_pk_add_f32 v[38:39], v[38:39], v[58:59]
	v_pk_add_f32 v[54:55], v[36:37], v[34:35]
	v_cvt_pk_bf16_f32 v34, v38, v39
	v_cvt_pk_bf16_f32 v35, v40, v41
	v_cvt_pk_bf16_f32 v36, v52, v53
	v_cvt_pk_bf16_f32 v37, v54, v55
	global_store_dwordx4 v[56:57], v[34:37], off offset:256
	s_nop 1
	v_pk_mul_f32 v[34:35], v[38:39], v[38:39]
	v_pk_mul_f32 v[36:37], v[40:41], v[40:41]
	v_add_f32_e32 v34, v34, v35
	v_add_f32_e32 v36, v36, v37
	v_pk_mul_f32 v[38:39], v[52:53], v[52:53]
	v_pk_mul_f32 v[40:41], v[54:55], v[54:55]
	v_add_f32_e32 v34, v34, v36
	v_add_f32_e32 v35, v48, v49
	v_add_f32_e32 v36, v46, v47
	v_add_f32_e32 v40, v40, v41
	v_add_f32_e32 v38, v38, v39
	v_add_f32_e32 v35, v36, v35
	v_add_f32_e32 v36, v44, v45
	v_add_f32_e32 v37, v42, v43
	v_add_f32_e32 v38, v38, v40
	v_add_f32_e32 v36, v37, v36
	v_add_f32_e32 v34, v34, v38
	v_add_f32_e32 v35, v36, v35
	v_add_f32_e32 v34, v35, v34
	ds_bpermute_b32 v35, v151, v34
	s_waitcnt lgkmcnt(0)
	v_add_f32_e32 v34, v34, v35
	ds_bpermute_b32 v35, v150, v34
	s_and_saveexec_b64 s[22:23], s[6:7]
	s_cbranch_execz .LBB0_678
	v_lshlrev_b64 v[36:37], 6, v[50:51]
	v_lshl_add_u64 v[36:37], s[4:5], 0, v[36:37]
	v_lshl_add_u64 v[36:37], s[20:21], 2, v[36:37]
	s_lshl_b32 s72, s42, 2
	v_lshl_add_u64 v[36:37], v[36:37], 0, s[72:73]
	s_waitcnt lgkmcnt(0)
	v_add_f32_e32 v34, v34, v35
	global_store_dword v[36:37], v34, off
; #define GAS __attribute__((address_space(1)))
; __device__ __forceinline__ unsigned cvt_pk_bf16(float lo, float hi) { f32x2 v = {lo, hi}; bf16x2_t b = __builtin_convertvector(v, bf16x2_t); return __builtin_bit_cast(unsigned, b); }
; __device__ __forceinline__ float bf_lo(unsigned u) { return __uint_as_float(u << 16); }
; __device__ __forceinline__ float bf_hi(unsigned u) { return __uint_as_float(u & 0xffff0000u); }
;     __device__ __forceinline__ void operator()(const f32x4 (&acc)[2][2][4][2], const Unit& u, int wr, int wc, int fr, int fq) const {
;     ...
;             for (int m = 0; m < 4; ++m) { const int row = row0 + ai * HALF + m * 16; const size_t off = (size_t)row * 1024 + col0; float q = 0.f;
; #pragma unroll
;                 for (int bj = 0; bj < 2; ++bj) { const u32x4 xo = *(const GAS u32x4*)(xb + off + bj * HALF);
;                     f32x4 v0 = acc[ai][bj][m][0], v1 = acc[ai][bj][m][1];
;                     v0[0] += bf_lo(xo.x); v0[1] += bf_hi(xo.x); v0[2] += bf_lo(xo.y); v0[3] += bf_hi(xo.y); v1[0] += bf_lo(xo.z); v1[1] += bf_hi(xo.z); v1[2] += bf_lo(xo.w); v1[3] += bf_hi(xo.w);
;                     if (out) { *(GAS f32x4*)(out + off + bj * HALF) = v0; *(GAS f32x4*)(out + off + bj * HALF + 4) = v1; }
;                     u32x4 w; w.x = cvt_pk_bf16(v0[0], v0[1]); w.y = cvt_pk_bf16(v0[2], v0[3]); w.z = cvt_pk_bf16(v1[0], v1[1]); w.w = cvt_pk_bf16(v1[2], v1[3]);
;                     *(GAS u32x4*)(xb + off + bj * HALF) = w;
;                     q += ((v0[0] * v0[0] + v0[1] * v0[1]) + (v0[2] * v0[2] + v0[3] * v0[3])) + ((v1[0] * v1[0] + v1[1] * v1[1]) + (v1[2] * v1[2] + v1[3] * v1[3])); }
;                 q += __shfl_xor(q, 16); q += __shfl_xor(q, 32);
;                 if (fq == 0) rowss[(size_t)row * 16 + u.pn * 4 + wc] = q; }
.LBB0_678:
	s_or_b64 exec, exec, s[22:23]
	v_add_u32_e32 v34, 0xa0, v142
	s_waitcnt lgkmcnt(0)
	v_ashrrev_i32_e32 v35, 31, v34
	v_lshlrev_b64 v[36:37], 11, v[34:35]
	v_lshl_add_u64 v[36:37], s[2:3], 0, v[36:37]
	v_lshl_add_u64 v[40:41], v[140:141], 1, v[36:37]
	s_nop 1
	v_mov_b32_e32 v36, v208
	v_mov_b32_e32 v37, v209
	v_mov_b32_e32 v38, v210
	v_mov_b32_e32 v39, v211
	v_lshlrev_b32_e32 v42, 16, v36
	v_and_b32_e32 v43, 0xffff0000, v36
	v_lshlrev_b32_e32 v36, 16, v37
	v_and_b32_e32 v37, 0xffff0000, v37
	v_pk_add_f32 v[32:33], v[32:33], v[36:37]
	v_lshlrev_b32_e32 v36, 16, v38
	v_and_b32_e32 v37, 0xffff0000, v38
	v_pk_add_f32 v[36:37], v[26:27], v[36:37]
	v_lshlrev_b32_e32 v26, 16, v39
	v_and_b32_e32 v27, 0xffff0000, v39
	v_pk_add_f32 v[30:31], v[30:31], v[42:43]
	v_pk_add_f32 v[38:39], v[28:29], v[26:27]
	v_cvt_pk_bf16_f32 v26, v30, v31
	v_cvt_pk_bf16_f32 v27, v32, v33
	v_cvt_pk_bf16_f32 v28, v36, v37
	v_cvt_pk_bf16_f32 v29, v38, v39
	global_store_dwordx4 v[40:41], v[26:29], off
	s_nop 1
	v_pk_mul_f32 v[26:27], v[30:31], v[30:31]
	v_pk_mul_f32 v[28:29], v[32:33], v[32:33]
	v_pk_mul_f32 v[30:31], v[36:37], v[36:37]
	v_pk_mul_f32 v[32:33], v[38:39], v[38:39]
	s_nop 1
	v_mov_b32_e32 v36, v212
	v_mov_b32_e32 v37, v213
	v_mov_b32_e32 v38, v214
	v_mov_b32_e32 v39, v215
	v_lshlrev_b32_e32 v42, 16, v36
	v_and_b32_e32 v43, 0xffff0000, v36
	v_lshlrev_b32_e32 v36, 16, v37
	v_and_b32_e32 v37, 0xffff0000, v37
	v_pk_add_f32 v[24:25], v[24:25], v[36:37]
	v_lshlrev_b32_e32 v36, 16, v38
	v_and_b32_e32 v37, 0xffff0000, v38
	v_pk_add_f32 v[36:37], v[18:19], v[36:37]
	v_lshlrev_b32_e32 v18, 16, v39
	v_and_b32_e32 v19, 0xffff0000, v39
	v_pk_add_f32 v[22:23], v[22:23], v[42:43]
	v_pk_add_f32 v[38:39], v[20:21], v[18:19]
	v_cvt_pk_bf16_f32 v18, v22, v23
	v_cvt_pk_bf16_f32 v19, v24, v25
	v_cvt_pk_bf16_f32 v20, v36, v37
	v_cvt_pk_bf16_f32 v21, v38, v39
	global_store_dwordx4 v[40:41], v[18:21], off offset:256
	s_nop 1
	v_pk_mul_f32 v[18:19], v[22:23], v[22:23]
	v_pk_mul_f32 v[20:21], v[24:25], v[24:25]
	v_add_f32_e32 v18, v18, v19
	v_add_f32_e32 v20, v20, v21
	v_pk_mul_f32 v[22:23], v[36:37], v[36:37]
	v_pk_mul_f32 v[24:25], v[38:39], v[38:39]
	v_add_f32_e32 v18, v18, v20
	v_add_f32_e32 v19, v32, v33
	v_add_f32_e32 v20, v30, v31
	v_add_f32_e32 v24, v24, v25
	v_add_f32_e32 v22, v22, v23
	v_add_f32_e32 v19, v20, v19
	v_add_f32_e32 v20, v28, v29
	v_add_f32_e32 v21, v26, v27
	v_add_f32_e32 v22, v22, v24
	v_add_f32_e32 v20, v21, v20
	v_add_f32_e32 v18, v18, v22
	v_add_f32_e32 v19, v20, v19
	v_add_f32_e32 v18, v19, v18
	ds_bpermute_b32 v19, v151, v18
	s_waitcnt lgkmcnt(0)
	v_add_f32_e32 v18, v18, v19
	ds_bpermute_b32 v19, v150, v18
	s_and_saveexec_b64 s[22:23], s[6:7]
	s_cbranch_execz .LBB0_680
	v_lshlrev_b64 v[20:21], 6, v[34:35]
	v_lshl_add_u64 v[20:21], s[4:5], 0, v[20:21]
	v_lshl_add_u64 v[20:21], s[20:21], 2, v[20:21]
	s_lshl_b32 s72, s42, 2
	v_lshl_add_u64 v[20:21], v[20:21], 0, s[72:73]
	s_waitcnt lgkmcnt(0)
	v_add_f32_e32 v18, v18, v19
	global_store_dword v[20:21], v18, off
.LBB0_680:
	s_or_b64 exec, exec, s[22:23]
	v_add_u32_e32 v18, 0xb0, v142
	s_waitcnt lgkmcnt(0)
	v_ashrrev_i32_e32 v19, 31, v18
	v_lshlrev_b64 v[20:21], 11, v[18:19]
	v_lshl_add_u64 v[20:21], s[2:3], 0, v[20:21]
	v_lshl_add_u64 v[24:25], v[140:141], 1, v[20:21]
	s_nop 1
	v_mov_b32_e32 v20, v216
	v_mov_b32_e32 v21, v217
	v_mov_b32_e32 v22, v218
	v_mov_b32_e32 v23, v219
	v_lshlrev_b32_e32 v26, 16, v20
	v_and_b32_e32 v27, 0xffff0000, v20
	v_lshlrev_b32_e32 v20, 16, v21
	v_and_b32_e32 v21, 0xffff0000, v21
	v_pk_add_f32 v[16:17], v[16:17], v[20:21]
	v_lshlrev_b32_e32 v20, 16, v22
	v_and_b32_e32 v21, 0xffff0000, v22
	v_pk_add_f32 v[20:21], v[10:11], v[20:21]
	v_lshlrev_b32_e32 v10, 16, v23
	v_and_b32_e32 v11, 0xffff0000, v23
	v_pk_add_f32 v[14:15], v[14:15], v[26:27]
	v_pk_add_f32 v[22:23], v[12:13], v[10:11]
	v_cvt_pk_bf16_f32 v10, v14, v15
	v_cvt_pk_bf16_f32 v11, v16, v17
	v_cvt_pk_bf16_f32 v12, v20, v21
	v_cvt_pk_bf16_f32 v13, v22, v23
	global_store_dwordx4 v[24:25], v[10:13], off
	s_nop 1
	v_pk_mul_f32 v[10:11], v[14:15], v[14:15]
	v_pk_mul_f32 v[12:13], v[16:17], v[16:17]
	v_pk_mul_f32 v[14:15], v[20:21], v[20:21]
	v_pk_mul_f32 v[16:17], v[22:23], v[22:23]
	s_nop 1
	v_mov_b32_e32 v20, v220
	v_mov_b32_e32 v21, v221
	v_mov_b32_e32 v22, v222
	v_mov_b32_e32 v23, v223
	v_lshlrev_b32_e32 v26, 16, v20
	v_and_b32_e32 v27, 0xffff0000, v20
	v_lshlrev_b32_e32 v20, 16, v21
	v_and_b32_e32 v21, 0xffff0000, v21
	v_pk_add_f32 v[8:9], v[8:9], v[20:21]
	v_lshlrev_b32_e32 v20, 16, v22
	v_and_b32_e32 v21, 0xffff0000, v22
	v_pk_add_f32 v[20:21], v[2:3], v[20:21]
	v_lshlrev_b32_e32 v2, 16, v23
	v_and_b32_e32 v3, 0xffff0000, v23
	v_pk_add_f32 v[6:7], v[6:7], v[26:27]
	v_pk_add_f32 v[22:23], v[4:5], v[2:3]
	v_cvt_pk_bf16_f32 v2, v6, v7
	v_cvt_pk_bf16_f32 v3, v8, v9
	v_cvt_pk_bf16_f32 v4, v20, v21
	v_cvt_pk_bf16_f32 v5, v22, v23
	global_store_dwordx4 v[24:25], v[2:5], off offset:256
	s_nop 1
	v_pk_mul_f32 v[2:3], v[6:7], v[6:7]
	v_pk_mul_f32 v[4:5], v[8:9], v[8:9]
	v_add_f32_e32 v2, v2, v3
	v_add_f32_e32 v4, v4, v5
	v_pk_mul_f32 v[6:7], v[20:21], v[20:21]
	v_pk_mul_f32 v[8:9], v[22:23], v[22:23]
	v_add_f32_e32 v2, v2, v4
	v_add_f32_e32 v3, v16, v17
	v_add_f32_e32 v4, v14, v15
	v_add_f32_e32 v8, v8, v9
	v_add_f32_e32 v6, v6, v7
	v_add_f32_e32 v3, v4, v3
	v_add_f32_e32 v4, v12, v13
	v_add_f32_e32 v5, v10, v11
	v_add_f32_e32 v6, v6, v8
	v_add_f32_e32 v4, v5, v4
	v_add_f32_e32 v2, v2, v6
	v_add_f32_e32 v3, v4, v3
	v_add_f32_e32 v2, v3, v2
	ds_bpermute_b32 v3, v151, v2
	s_waitcnt lgkmcnt(0)
	v_add_f32_e32 v2, v2, v3
	ds_bpermute_b32 v3, v150, v2
	s_and_saveexec_b64 s[22:23], s[6:7]
	s_cbranch_execz .LBB0_682
	v_lshlrev_b64 v[4:5], 6, v[18:19]
	v_lshl_add_u64 v[4:5], s[4:5], 0, v[4:5]
	v_lshl_add_u64 v[4:5], s[20:21], 2, v[4:5]
	s_lshl_b32 s72, s42, 2
	v_lshl_add_u64 v[4:5], v[4:5], 0, s[72:73]
	s_waitcnt lgkmcnt(0)
	v_add_f32_e32 v2, v2, v3
	global_store_dword v[4:5], v2, off

; #define GAS __attribute__((address_space(1)))
; __device__ __forceinline__ unsigned cvt_pk_bf16(float lo, float hi) { f32x2 v = {lo, hi}; bf16x2_t b = __builtin_convertvector(v, bf16x2_t); return __builtin_bit_cast(unsigned, b); }
; __device__ __forceinline__ float sigmoid_f(float x) { return __builtin_amdgcn_rcpf(1.0f + __builtin_amdgcn_exp2f(-x * LOG2E)); }
; __device__ __forceinline__ float row_rs(const GAS float* rowss, int row) {
;     const GAS f32x4* p = (const GAS f32x4*)(rowss + (size_t)row * 16); const f32x4 a = p[0], b = p[1], c = p[2], d = p[3];
;     const float s = ((a[0] + a[1]) + (a[2] + a[3])) + ((b[0] + b[1]) + (b[2] + b[3])) + ((c[0] + c[1]) + (c[2] + c[3])) + ((d[0] + d[1]) + (d[2] + d[3]));
;     return __builtin_amdgcn_rsqf(s * (1.0f / 1024.0f) + 1e-6f);
; }
;     __device__ __forceinline__ void operator()(const f32x4 (&acc)[2][2][4][2], const Unit& u, int wr, int wc, int fr, int fq) const {
;         const int row0 = u.pm * BM + wr * 64 + fr; const int col0 = (u.pn * BM + wc * 32 + 8 * fq) >> 1;
; #pragma unroll
;         for (int ai = 0; ai < 2; ++ai)
; #pragma unroll
;             for (int m = 0; m < 4; ++m) { const int row = row0 + ai * HALF + m * 16; const float rs = row_rs(rowss, row); GAS bf16_t* rowp = H + (size_t)row * 2816 + col0;
; #pragma unroll
;                 for (int bj = 0; bj < 2; ++bj) { const f32x4 g = acc[ai][bj][m][0] * rs, uu = acc[ai][bj][m][1] * rs;
;                     u32x2 w; w.x = cvt_pk_bf16(g[0] * sigmoid_f(g[0]) * uu[0], g[1] * sigmoid_f(g[1]) * uu[1]); w.y = cvt_pk_bf16(g[2] * sigmoid_f(g[2]) * uu[2], g[3] * sigmoid_f(g[3]) * uu[3]);
;                     *(GAS u32x2*)(rowp + bj * (HALF / 2)) = w; } }
.LBB0_755:
	v_lshl_add_u32 v144, s18, 8, v146
	v_lshl_or_b32 v140, s19, 8, v148
	v_ashrrev_i32_e32 v145, 31, v144
	v_ashrrev_i32_e32 v162, 1, v140
	v_lshlrev_b64 v[140:141], 6, v[144:145]
	v_lshl_add_u64 v[158:159], s[4:5], 0, v[140:141]
	s_nop 0
	v_ashrrev_i32_e32 v163, 31, v162
	s_movk_i32 s11, 0x1600
	s_andn2_b64 vcc, exec, s[6:7]
	v_mov_b32_e32 v224, v140
	global_load_dwordx4 v[192:195], v224, s[4:5]
	global_load_dwordx4 v[196:199], v224, s[4:5] offset:16
	global_load_dwordx4 v[200:203], v224, s[4:5] offset:32
	global_load_dwordx4 v[204:207], v224, s[4:5] offset:48
	v_add_u32_e32 v225, 0x400, v224
	global_load_dwordx4 v[208:211], v225, s[4:5]
	global_load_dwordx4 v[212:215], v225, s[4:5] offset:16
	global_load_dwordx4 v[216:219], v225, s[4:5] offset:32
	global_load_dwordx4 v[220:223], v225, s[4:5] offset:48
	s_waitcnt vmcnt(4)
	s_nop 1
	v_mov_b32_e32 v140, v204
	v_mov_b32_e32 v141, v205
	v_mov_b32_e32 v142, v206
	v_mov_b32_e32 v143, v207
	v_mov_b32_e32 v150, v200
	v_mov_b32_e32 v151, v201
	v_mov_b32_e32 v152, v202
	v_mov_b32_e32 v153, v203
	v_mov_b32_e32 v154, v196
	v_mov_b32_e32 v155, v197
	v_mov_b32_e32 v156, v198
	v_mov_b32_e32 v157, v199
	v_mov_b32_e32 v158, v192
	v_mov_b32_e32 v159, v193
	v_mov_b32_e32 v160, v194
	v_mov_b32_e32 v161, v195
	v_add_f32_e32 v150, v150, v151
	v_add_f32_e32 v152, v152, v153
	v_mov_b32_e32 v164, v159
	v_mov_b32_e32 v165, v160
	v_mov_b32_e32 v159, v161
	v_mov_b32_e32 v160, v155
	v_mov_b32_e32 v161, v156
	v_mov_b32_e32 v155, v157
	v_pk_add_f32 v[158:159], v[164:165], v[158:159]
	v_pk_add_f32 v[154:155], v[160:161], v[154:155]
	v_pk_add_f32 v[158:159], v[158:159], v[158:159] op_sel:[0,1] op_sel_hi:[1,0]
	v_pk_add_f32 v[154:155], v[154:155], v[154:155] op_sel:[0,1] op_sel_hi:[1,0]
	v_mov_b32_e32 v159, v140
	v_mov_b32_e32 v155, v141
	v_mov_b32_e32 v151, v142
	v_mov_b32_e32 v153, v143
	v_pk_add_f32 v[140:141], v[158:159], v[154:155]
	v_pk_add_f32 v[142:143], v[150:151], v[152:153]
	s_nop 0
	v_pk_add_f32 v[140:141], v[140:141], v[142:143]
	v_lshlrev_b64 v[142:143], 1, v[162:163]
	v_add_f32_e32 v140, v140, v141
	v_fmamk_f32 v140, v140, 0x3a800000, v234
	v_rsq_f32_e32 v150, v140
	v_mov_b64_e32 v[140:141], s[2:3]
	v_mad_i64_i32 v[152:153], s[18:19], v144, s11, v[140:141]
	v_pk_mul_f32 v[126:127], v[126:127], v[150:151] op_sel_hi:[1,0]
	v_pk_mul_f32 v[122:123], v[122:123], v[150:151] op_sel_hi:[1,0]
	v_mul_f32_e32 v145, 0xbfb8aa3b, v126
	v_exp_f32_e32 v145, v145
	v_pk_mul_f32 v[128:129], v[128:129], v[150:151] op_sel_hi:[1,0]
	v_pk_mul_f32 v[124:125], v[124:125], v[150:151] op_sel_hi:[1,0]
	v_lshl_add_u64 v[152:153], v[152:153], 0, v[142:143]
	v_add_f32_e32 v145, 1.0, v145
	v_rcp_f32_e32 v154, v145
	v_mul_f32_e32 v145, 0xbfb8aa3b, v127
	v_exp_f32_e32 v145, v145
	v_pk_mul_f32 v[118:119], v[118:119], v[150:151] op_sel_hi:[1,0]
	v_pk_mul_f32 v[114:115], v[114:115], v[150:151] op_sel_hi:[1,0]
	v_pk_mul_f32 v[120:121], v[120:121], v[150:151] op_sel_hi:[1,0]
	v_add_f32_e32 v145, 1.0, v145
	v_rcp_f32_e32 v155, v145
	v_pk_mul_f32 v[116:117], v[116:117], v[150:151] op_sel_hi:[1,0]
	v_pk_mul_f32 v[126:127], v[126:127], v[154:155]
	s_nop 0
	v_pk_mul_f32 v[122:123], v[122:123], v[126:127]
	s_nop 0
	v_cvt_pk_bf16_f32 v122, v122, v123
	v_mul_f32_e32 v123, 0xbfb8aa3b, v128
	v_exp_f32_e32 v123, v123
	s_nop 0
	v_add_f32_e32 v123, 1.0, v123
	v_rcp_f32_e32 v126, v123
	v_mul_f32_e32 v123, 0xbfb8aa3b, v129
	v_exp_f32_e32 v123, v123
	s_nop 0
	v_add_f32_e32 v123, 1.0, v123
	v_rcp_f32_e32 v127, v123
	s_nop 0
	v_pk_mul_f32 v[126:127], v[128:129], v[126:127]
	s_nop 0
	v_pk_mul_f32 v[124:125], v[124:125], v[126:127]
	s_nop 0
	v_cvt_pk_bf16_f32 v123, v124, v125
	global_store_dwordx2 v[152:153], v[122:123], off
	v_mul_f32_e32 v122, 0xbfb8aa3b, v118
	v_mul_f32_e32 v123, 0xbfb8aa3b, v119
	v_exp_f32_e32 v122, v122
	v_exp_f32_e32 v123, v123
	v_add_f32_e32 v122, 1.0, v122
	v_add_f32_e32 v123, 1.0, v123
	v_rcp_f32_e32 v122, v122
	v_rcp_f32_e32 v123, v123
	s_nop 0
	v_pk_mul_f32 v[118:119], v[118:119], v[122:123]
	s_nop 0
	v_pk_mul_f32 v[114:115], v[114:115], v[118:119]
	s_nop 0
	v_cvt_pk_bf16_f32 v114, v114, v115
	v_mul_f32_e32 v115, 0xbfb8aa3b, v120
	v_exp_f32_e32 v115, v115
	s_nop 0
	v_add_f32_e32 v115, 1.0, v115
	v_rcp_f32_e32 v118, v115
	v_mul_f32_e32 v115, 0xbfb8aa3b, v121
	v_exp_f32_e32 v115, v115
	s_nop 0
	v_add_f32_e32 v115, 1.0, v115
	v_rcp_f32_e32 v119, v115
	s_nop 0
	v_pk_mul_f32 v[118:119], v[120:121], v[118:119]
	s_nop 0
	v_pk_mul_f32 v[116:117], v[116:117], v[118:119]
	s_nop 0
	v_cvt_pk_bf16_f32 v115, v116, v117
	global_store_dwordx2 v[152:153], v[114:115], off offset:128
	v_or_b32_e32 v114, 16, v144
	v_ashrrev_i32_e32 v115, 31, v114
	v_lshlrev_b64 v[116:117], 6, v[114:115]
	v_lshl_add_u64 v[128:129], s[4:5], 0, v[116:117]
	v_add_u32_e32 v225, 0x800, v224
	global_load_dwordx4 v[192:195], v225, s[4:5]
	global_load_dwordx4 v[196:199], v225, s[4:5] offset:16
	global_load_dwordx4 v[200:203], v225, s[4:5] offset:32
	global_load_dwordx4 v[204:207], v225, s[4:5] offset:48
	s_waitcnt vmcnt(4)
; #define GAS __attribute__((address_space(1)))
; __device__ __forceinline__ unsigned cvt_pk_bf16(float lo, float hi) { f32x2 v = {lo, hi}; bf16x2_t b = __builtin_convertvector(v, bf16x2_t); return __builtin_bit_cast(unsigned, b); }
; __device__ __forceinline__ float sigmoid_f(float x) { return __builtin_amdgcn_rcpf(1.0f + __builtin_amdgcn_exp2f(-x * LOG2E)); }
; __device__ __forceinline__ float row_rs(const GAS float* rowss, int row) {
;     const GAS f32x4* p = (const GAS f32x4*)(rowss + (size_t)row * 16); const f32x4 a = p[0], b = p[1], c = p[2], d = p[3];
;     const float s = ((a[0] + a[1]) + (a[2] + a[3])) + ((b[0] + b[1]) + (b[2] + b[3])) + ((c[0] + c[1]) + (c[2] + c[3])) + ((d[0] + d[1]) + (d[2] + d[3]));
;     return __builtin_amdgcn_rsqf(s * (1.0f / 1024.0f) + 1e-6f);
; }
;     __device__ __forceinline__ void operator()(const f32x4 (&acc)[2][2][4][2], const Unit& u, int wr, int wc, int fr, int fq) const {
;         const int row0 = u.pm * BM + wr * 64 + fr; const int col0 = (u.pn * BM + wc * 32 + 8 * fq) >> 1;
; #pragma unroll
;         for (int ai = 0; ai < 2; ++ai)
; #pragma unroll
;             for (int m = 0; m < 4; ++m) { const int row = row0 + ai * HALF + m * 16; const float rs = row_rs(rowss, row); GAS bf16_t* rowp = H + (size_t)row * 2816 + col0;
; #pragma unroll
;                 for (int bj = 0; bj < 2; ++bj) { const f32x4 g = acc[ai][bj][m][0] * rs, uu = acc[ai][bj][m][1] * rs;
;                     u32x2 w; w.x = cvt_pk_bf16(g[0] * sigmoid_f(g[0]) * uu[0], g[1] * sigmoid_f(g[1]) * uu[1]); w.y = cvt_pk_bf16(g[2] * sigmoid_f(g[2]) * uu[2], g[3] * sigmoid_f(g[3]) * uu[3]);
;                     *(GAS u32x2*)(rowp + bj * (HALF / 2)) = w; } }
	s_nop 1
	v_mov_b32_e32 v116, v220
	v_mov_b32_e32 v117, v221
	v_mov_b32_e32 v118, v222
	v_mov_b32_e32 v119, v223
	v_mov_b32_e32 v120, v216
	v_mov_b32_e32 v121, v217
	v_mov_b32_e32 v122, v218
	v_mov_b32_e32 v123, v219
	v_mov_b32_e32 v124, v212
	v_mov_b32_e32 v125, v213
	v_mov_b32_e32 v126, v214
	v_mov_b32_e32 v127, v215
	v_mov_b32_e32 v150, v208
	v_mov_b32_e32 v151, v209
	v_mov_b32_e32 v152, v210
	v_mov_b32_e32 v153, v211
	v_add_f32_e32 v120, v120, v121
	v_add_f32_e32 v122, v122, v123
	v_mov_b32_e32 v128, v151
	v_mov_b32_e32 v129, v152
	v_mov_b32_e32 v151, v153
	v_pk_add_f32 v[128:129], v[128:129], v[150:151]
	v_mov_b32_e32 v150, v125
	v_mov_b32_e32 v151, v126
	v_mov_b32_e32 v125, v127
	v_pk_add_f32 v[124:125], v[150:151], v[124:125]
	v_pk_add_f32 v[128:129], v[128:129], v[128:129] op_sel:[0,1] op_sel_hi:[1,0]
	v_pk_add_f32 v[124:125], v[124:125], v[124:125] op_sel:[0,1] op_sel_hi:[1,0]
	v_mov_b32_e32 v129, v116
	v_mov_b32_e32 v125, v117
	v_mov_b32_e32 v121, v118
	v_mov_b32_e32 v123, v119
	v_pk_add_f32 v[116:117], v[128:129], v[124:125]
	v_pk_add_f32 v[118:119], v[120:121], v[122:123]
	s_nop 0
	v_pk_add_f32 v[116:117], v[116:117], v[118:119]
	s_nop 0
	v_add_f32_e32 v115, v116, v117
	v_fmamk_f32 v115, v115, 0x3a800000, v234
	v_rsq_f32_e32 v116, v115
	v_mad_i64_i32 v[114:115], s[18:19], v114, s11, v[140:141]
	v_lshl_add_u64 v[114:115], v[114:115], 0, v[142:143]
	v_pk_mul_f32 v[110:111], v[110:111], v[116:117] op_sel_hi:[1,0]
	v_pk_mul_f32 v[112:113], v[112:113], v[116:117] op_sel_hi:[1,0]
	v_pk_mul_f32 v[108:109], v[108:109], v[116:117] op_sel_hi:[1,0]
	v_pk_mul_f32 v[106:107], v[106:107], v[116:117] op_sel_hi:[1,0]
	v_mul_f32_e32 v117, 0xbfb8aa3b, v110
	v_exp_f32_e32 v117, v117
	s_nop 0
	v_add_f32_e32 v117, 1.0, v117
	v_rcp_f32_e32 v118, v117
	v_mul_f32_e32 v117, 0xbfb8aa3b, v111
	v_exp_f32_e32 v117, v117
	s_nop 0
	v_add_f32_e32 v117, 1.0, v117
	v_rcp_f32_e32 v119, v117
	v_pk_mul_f32 v[102:103], v[102:103], v[116:117] op_sel_hi:[1,0]
	v_pk_mul_f32 v[98:99], v[98:99], v[116:117] op_sel_hi:[1,0]
	v_pk_mul_f32 v[104:105], v[104:105], v[116:117] op_sel_hi:[1,0]
	v_pk_mul_f32 v[110:111], v[110:111], v[118:119]
	v_pk_mul_f32 v[100:101], v[100:101], v[116:117] op_sel_hi:[1,0]
	v_pk_mul_f32 v[106:107], v[106:107], v[110:111]
	s_nop 0
	v_cvt_pk_bf16_f32 v106, v106, v107
	v_mul_f32_e32 v107, 0xbfb8aa3b, v112
	v_exp_f32_e32 v107, v107
	s_nop 0
	v_add_f32_e32 v107, 1.0, v107
	v_rcp_f32_e32 v110, v107
	v_mul_f32_e32 v107, 0xbfb8aa3b, v113
	v_exp_f32_e32 v107, v107
	s_nop 0
	v_add_f32_e32 v107, 1.0, v107
	v_rcp_f32_e32 v111, v107
	s_nop 0
	v_pk_mul_f32 v[110:111], v[112:113], v[110:111]
	s_nop 0
	v_pk_mul_f32 v[108:109], v[108:109], v[110:111]
	s_nop 0
	v_cvt_pk_bf16_f32 v107, v108, v109
	global_store_dwordx2 v[114:115], v[106:107], off
	v_mul_f32_e32 v106, 0xbfb8aa3b, v102
	v_mul_f32_e32 v107, 0xbfb8aa3b, v103
	v_exp_f32_e32 v106, v106
	v_exp_f32_e32 v107, v107
	v_add_f32_e32 v106, 1.0, v106
	v_add_f32_e32 v107, 1.0, v107
	v_rcp_f32_e32 v106, v106
	v_rcp_f32_e32 v107, v107
	s_nop 0
	v_pk_mul_f32 v[102:103], v[102:103], v[106:107]
	s_nop 0
	v_pk_mul_f32 v[98:99], v[98:99], v[102:103]
	s_nop 0
	v_cvt_pk_bf16_f32 v98, v98, v99
	v_mul_f32_e32 v99, 0xbfb8aa3b, v104
	v_exp_f32_e32 v99, v99
	s_nop 0
	v_add_f32_e32 v99, 1.0, v99
	v_rcp_f32_e32 v102, v99
	v_mul_f32_e32 v99, 0xbfb8aa3b, v105
	v_exp_f32_e32 v99, v99
	s_nop 0
	v_add_f32_e32 v99, 1.0, v99
	v_rcp_f32_e32 v103, v99
	s_nop 0
	v_pk_mul_f32 v[102:103], v[104:105], v[102:103]
	s_nop 0
	v_pk_mul_f32 v[100:101], v[100:101], v[102:103]
	s_nop 0
	v_cvt_pk_bf16_f32 v99, v100, v101
	global_store_dwordx2 v[114:115], v[98:99], off offset:128
	v_or_b32_e32 v98, 32, v144
	v_ashrrev_i32_e32 v99, 31, v98
	v_lshlrev_b64 v[100:101], 6, v[98:99]
	v_lshl_add_u64 v[112:113], s[4:5], 0, v[100:101]
	s_nop 0
	v_add_u32_e32 v225, 0xc00, v224
	global_load_dwordx4 v[208:211], v225, s[4:5]
	global_load_dwordx4 v[212:215], v225, s[4:5] offset:16
	global_load_dwordx4 v[216:219], v225, s[4:5] offset:32
	global_load_dwordx4 v[220:223], v225, s[4:5] offset:48
	s_waitcnt vmcnt(4)
	s_nop 1
	v_mov_b32_e32 v100, v204
	v_mov_b32_e32 v101, v205
	v_mov_b32_e32 v102, v206
	v_mov_b32_e32 v103, v207
	v_mov_b32_e32 v104, v200
	v_mov_b32_e32 v105, v201
	v_mov_b32_e32 v106, v202
	v_mov_b32_e32 v107, v203
	v_mov_b32_e32 v108, v196
	v_mov_b32_e32 v109, v197
	v_mov_b32_e32 v110, v198
	v_mov_b32_e32 v111, v199
	v_mov_b32_e32 v112, v192
	v_mov_b32_e32 v113, v193
	v_mov_b32_e32 v114, v194
	v_mov_b32_e32 v115, v195
	v_add_f32_e32 v104, v104, v105
	v_add_f32_e32 v106, v106, v107
	v_mov_b32_e32 v116, v113
	v_mov_b32_e32 v117, v114
	v_mov_b32_e32 v113, v115
	v_mov_b32_e32 v114, v109
	v_mov_b32_e32 v115, v110
	v_mov_b32_e32 v109, v111
	v_pk_add_f32 v[112:113], v[116:117], v[112:113]
	v_pk_add_f32 v[108:109], v[114:115], v[108:109]
	v_pk_add_f32 v[112:113], v[112:113], v[112:113] op_sel:[0,1] op_sel_hi:[1,0]
	v_pk_add_f32 v[108:109], v[108:109], v[108:109] op_sel:[0,1] op_sel_hi:[1,0]
	v_mov_b32_e32 v113, v100
	v_mov_b32_e32 v109, v101
	v_mov_b32_e32 v105, v102
	v_mov_b32_e32 v107, v103
	v_pk_add_f32 v[100:101], v[112:113], v[108:109]
	v_pk_add_f32 v[102:103], v[104:105], v[106:107]
	s_nop 0
	v_pk_add_f32 v[100:101], v[100:101], v[102:103]
	s_nop 0
	v_add_f32_e32 v99, v100, v101
	v_fmamk_f32 v99, v99, 0x3a800000, v234
	v_rsq_f32_e32 v100, v99
	v_mad_i64_i32 v[98:99], s[18:19], v98, s11, v[140:141]
	v_lshl_add_u64 v[98:99], v[98:99], 0, v[142:143]
	v_pk_mul_f32 v[94:95], v[94:95], v[100:101] op_sel_hi:[1,0]
	v_pk_mul_f32 v[96:97], v[96:97], v[100:101] op_sel_hi:[1,0]
	v_pk_mul_f32 v[92:93], v[92:93], v[100:101] op_sel_hi:[1,0]
; #define GAS __attribute__((address_space(1)))
; __device__ __forceinline__ unsigned cvt_pk_bf16(float lo, float hi) { f32x2 v = {lo, hi}; bf16x2_t b = __builtin_convertvector(v, bf16x2_t); return __builtin_bit_cast(unsigned, b); }
; __device__ __forceinline__ float sigmoid_f(float x) { return __builtin_amdgcn_rcpf(1.0f + __builtin_amdgcn_exp2f(-x * LOG2E)); }
; __device__ __forceinline__ float row_rs(const GAS float* rowss, int row) {
;     const GAS f32x4* p = (const GAS f32x4*)(rowss + (size_t)row * 16); const f32x4 a = p[0], b = p[1], c = p[2], d = p[3];
;     const float s = ((a[0] + a[1]) + (a[2] + a[3])) + ((b[0] + b[1]) + (b[2] + b[3])) + ((c[0] + c[1]) + (c[2] + c[3])) + ((d[0] + d[1]) + (d[2] + d[3]));
;     return __builtin_amdgcn_rsqf(s * (1.0f / 1024.0f) + 1e-6f);
; }
;     __device__ __forceinline__ void operator()(const f32x4 (&acc)[2][2][4][2], const Unit& u, int wr, int wc, int fr, int fq) const {
;         const int row0 = u.pm * BM + wr * 64 + fr; const int col0 = (u.pn * BM + wc * 32 + 8 * fq) >> 1;
; #pragma unroll
;         for (int ai = 0; ai < 2; ++ai)
; #pragma unroll
;             for (int m = 0; m < 4; ++m) { const int row = row0 + ai * HALF + m * 16; const float rs = row_rs(rowss, row); GAS bf16_t* rowp = H + (size_t)row * 2816 + col0;
; #pragma unroll
;                 for (int bj = 0; bj < 2; ++bj) { const f32x4 g = acc[ai][bj][m][0] * rs, uu = acc[ai][bj][m][1] * rs;
;                     u32x2 w; w.x = cvt_pk_bf16(g[0] * sigmoid_f(g[0]) * uu[0], g[1] * sigmoid_f(g[1]) * uu[1]); w.y = cvt_pk_bf16(g[2] * sigmoid_f(g[2]) * uu[2], g[3] * sigmoid_f(g[3]) * uu[3]);
;                     *(GAS u32x2*)(rowp + bj * (HALF / 2)) = w; } }
	v_pk_mul_f32 v[90:91], v[90:91], v[100:101] op_sel_hi:[1,0]
	v_mul_f32_e32 v101, 0xbfb8aa3b, v94
	v_exp_f32_e32 v101, v101
	s_nop 0
	v_add_f32_e32 v101, 1.0, v101
	v_rcp_f32_e32 v102, v101
	v_mul_f32_e32 v101, 0xbfb8aa3b, v95
	v_exp_f32_e32 v101, v101
	s_nop 0
	v_add_f32_e32 v101, 1.0, v101
	v_rcp_f32_e32 v103, v101
	v_pk_mul_f32 v[86:87], v[86:87], v[100:101] op_sel_hi:[1,0]
	v_pk_mul_f32 v[82:83], v[82:83], v[100:101] op_sel_hi:[1,0]
	v_pk_mul_f32 v[88:89], v[88:89], v[100:101] op_sel_hi:[1,0]
	v_pk_mul_f32 v[94:95], v[94:95], v[102:103]
	v_pk_mul_f32 v[84:85], v[84:85], v[100:101] op_sel_hi:[1,0]
	v_pk_mul_f32 v[90:91], v[90:91], v[94:95]
	s_nop 0
	v_cvt_pk_bf16_f32 v90, v90, v91
	v_mul_f32_e32 v91, 0xbfb8aa3b, v96
	v_exp_f32_e32 v91, v91
	s_nop 0
	v_add_f32_e32 v91, 1.0, v91
	v_rcp_f32_e32 v94, v91
	v_mul_f32_e32 v91, 0xbfb8aa3b, v97
	v_exp_f32_e32 v91, v91
	s_nop 0
	v_add_f32_e32 v91, 1.0, v91
	v_rcp_f32_e32 v95, v91
	s_nop 0
	v_pk_mul_f32 v[94:95], v[96:97], v[94:95]
	s_nop 0
	v_pk_mul_f32 v[92:93], v[92:93], v[94:95]
	s_nop 0
	v_cvt_pk_bf16_f32 v91, v92, v93
	global_store_dwordx2 v[98:99], v[90:91], off
	v_mul_f32_e32 v90, 0xbfb8aa3b, v86
	v_mul_f32_e32 v91, 0xbfb8aa3b, v87
	v_exp_f32_e32 v90, v90
	v_exp_f32_e32 v91, v91
	v_add_f32_e32 v90, 1.0, v90
	v_add_f32_e32 v91, 1.0, v91
	v_rcp_f32_e32 v90, v90
	v_rcp_f32_e32 v91, v91
	s_nop 0
	v_pk_mul_f32 v[86:87], v[86:87], v[90:91]
	s_nop 0
	v_pk_mul_f32 v[82:83], v[82:83], v[86:87]
	s_nop 0
	v_cvt_pk_bf16_f32 v82, v82, v83
	v_mul_f32_e32 v83, 0xbfb8aa3b, v88
	v_exp_f32_e32 v83, v83
	s_nop 0
	v_add_f32_e32 v83, 1.0, v83
	v_rcp_f32_e32 v86, v83
	v_mul_f32_e32 v83, 0xbfb8aa3b, v89
	v_exp_f32_e32 v83, v83
	s_nop 0
	v_add_f32_e32 v83, 1.0, v83
	v_rcp_f32_e32 v87, v83
	s_nop 0
	v_pk_mul_f32 v[86:87], v[88:89], v[86:87]
	s_nop 0
	v_pk_mul_f32 v[84:85], v[84:85], v[86:87]
	s_nop 0
	v_cvt_pk_bf16_f32 v83, v84, v85
	global_store_dwordx2 v[98:99], v[82:83], off offset:128
	v_or_b32_e32 v82, 48, v144
	v_ashrrev_i32_e32 v83, 31, v82
	v_lshlrev_b64 v[84:85], 6, v[82:83]
	v_lshl_add_u64 v[96:97], s[4:5], 0, v[84:85]
	s_nop 0
	v_add_u32_e32 v225, 0x2000, v224
	global_load_dwordx4 v[192:195], v225, s[4:5]
	global_load_dwordx4 v[196:199], v225, s[4:5] offset:16
	global_load_dwordx4 v[200:203], v225, s[4:5] offset:32
	global_load_dwordx4 v[204:207], v225, s[4:5] offset:48
	s_waitcnt vmcnt(4)
	s_nop 1
	v_mov_b32_e32 v84, v220
	v_mov_b32_e32 v85, v221
	v_mov_b32_e32 v86, v222
	v_mov_b32_e32 v87, v223
	v_mov_b32_e32 v88, v216
	v_mov_b32_e32 v89, v217
	v_mov_b32_e32 v90, v218
	v_mov_b32_e32 v91, v219
	v_mov_b32_e32 v92, v212
	v_mov_b32_e32 v93, v213
	v_mov_b32_e32 v94, v214
	v_mov_b32_e32 v95, v215
	v_mov_b32_e32 v96, v208
	v_mov_b32_e32 v97, v209
	v_mov_b32_e32 v98, v210
	v_mov_b32_e32 v99, v211
	v_add_f32_e32 v88, v88, v89
	v_add_f32_e32 v90, v90, v91
	v_mov_b32_e32 v100, v97
	v_mov_b32_e32 v101, v98
	v_mov_b32_e32 v97, v99
	v_mov_b32_e32 v98, v93
	v_mov_b32_e32 v99, v94
	v_mov_b32_e32 v93, v95
	v_pk_add_f32 v[96:97], v[100:101], v[96:97]
	v_pk_add_f32 v[92:93], v[98:99], v[92:93]
	v_pk_add_f32 v[96:97], v[96:97], v[96:97] op_sel:[0,1] op_sel_hi:[1,0]
	v_pk_add_f32 v[92:93], v[92:93], v[92:93] op_sel:[0,1] op_sel_hi:[1,0]
	v_mov_b32_e32 v97, v84
	v_mov_b32_e32 v93, v85
	v_mov_b32_e32 v89, v86
	v_mov_b32_e32 v91, v87
	v_pk_add_f32 v[84:85], v[96:97], v[92:93]
	v_pk_add_f32 v[86:87], v[88:89], v[90:91]
	s_nop 0
	v_pk_add_f32 v[84:85], v[84:85], v[86:87]
	s_nop 0
	v_add_f32_e32 v83, v84, v85
	v_fmamk_f32 v83, v83, 0x3a800000, v234
	v_rsq_f32_e32 v84, v83
	v_mad_i64_i32 v[82:83], s[18:19], v82, s11, v[140:141]
	v_lshl_add_u64 v[82:83], v[82:83], 0, v[142:143]
	v_pk_mul_f32 v[78:79], v[78:79], v[84:85] op_sel_hi:[1,0]
	v_pk_mul_f32 v[80:81], v[80:81], v[84:85] op_sel_hi:[1,0]
	v_pk_mul_f32 v[76:77], v[76:77], v[84:85] op_sel_hi:[1,0]
	v_pk_mul_f32 v[74:75], v[74:75], v[84:85] op_sel_hi:[1,0]
	v_mul_f32_e32 v85, 0xbfb8aa3b, v78
	v_exp_f32_e32 v85, v85
	s_nop 0
	v_add_f32_e32 v85, 1.0, v85
	v_rcp_f32_e32 v86, v85
	v_mul_f32_e32 v85, 0xbfb8aa3b, v79
	v_exp_f32_e32 v85, v85
	s_nop 0
	v_add_f32_e32 v85, 1.0, v85
	v_rcp_f32_e32 v87, v85
	v_pk_mul_f32 v[70:71], v[70:71], v[84:85] op_sel_hi:[1,0]
	v_pk_mul_f32 v[66:67], v[66:67], v[84:85] op_sel_hi:[1,0]
	v_pk_mul_f32 v[72:73], v[72:73], v[84:85] op_sel_hi:[1,0]
	v_pk_mul_f32 v[78:79], v[78:79], v[86:87]
	v_pk_mul_f32 v[68:69], v[68:69], v[84:85] op_sel_hi:[1,0]
	v_pk_mul_f32 v[74:75], v[74:75], v[78:79]
	s_nop 0
	v_cvt_pk_bf16_f32 v74, v74, v75
	v_mul_f32_e32 v75, 0xbfb8aa3b, v80
	v_exp_f32_e32 v75, v75
	s_nop 0
	v_add_f32_e32 v75, 1.0, v75
	v_rcp_f32_e32 v78, v75
	v_mul_f32_e32 v75, 0xbfb8aa3b, v81
	v_exp_f32_e32 v75, v75
	s_nop 0
	v_add_f32_e32 v75, 1.0, v75
	v_rcp_f32_e32 v79, v75
	s_nop 0
	v_pk_mul_f32 v[78:79], v[80:81], v[78:79]
	s_nop 0
	v_pk_mul_f32 v[76:77], v[76:77], v[78:79]
	s_nop 0
	v_cvt_pk_bf16_f32 v75, v76, v77
	global_store_dwordx2 v[82:83], v[74:75], off
	v_mul_f32_e32 v74, 0xbfb8aa3b, v70
	v_mul_f32_e32 v75, 0xbfb8aa3b, v71
	v_exp_f32_e32 v74, v74
	v_exp_f32_e32 v75, v75
	v_add_f32_e32 v74, 1.0, v74
	v_add_f32_e32 v75, 1.0, v75
	v_rcp_f32_e32 v74, v74
	v_rcp_f32_e32 v75, v75
	s_nop 0
	v_pk_mul_f32 v[70:71], v[70:71], v[74:75]
	s_nop 0
	v_pk_mul_f32 v[66:67], v[66:67], v[70:71]
	s_nop 0
	v_cvt_pk_bf16_f32 v66, v66, v67
	v_mul_f32_e32 v67, 0xbfb8aa3b, v72
	v_exp_f32_e32 v67, v67
	s_nop 0
	v_add_f32_e32 v67, 1.0, v67
	v_rcp_f32_e32 v70, v67
	v_mul_f32_e32 v67, 0xbfb8aa3b, v73
	v_exp_f32_e32 v67, v67
	s_nop 0
	v_add_f32_e32 v67, 1.0, v67
	v_rcp_f32_e32 v71, v67
	s_nop 0
	v_pk_mul_f32 v[70:71], v[72:73], v[70:71]
	s_nop 0
	v_pk_mul_f32 v[68:69], v[68:69], v[70:71]
	s_nop 0
	v_cvt_pk_bf16_f32 v67, v68, v69
	global_store_dwordx2 v[82:83], v[66:67], off offset:128
	v_add_u32_e32 v66, 0x80, v144
	v_ashrrev_i32_e32 v67, 31, v66
	v_lshlrev_b64 v[68:69], 6, v[66:67]
	v_lshl_add_u64 v[80:81], s[4:5], 0, v[68:69]
	s_nop 0
	v_add_u32_e32 v225, 0x2400, v224
	global_load_dwordx4 v[208:211], v225, s[4:5]
	global_load_dwordx4 v[212:215], v225, s[4:5] offset:16
	global_load_dwordx4 v[216:219], v225, s[4:5] offset:32
	global_load_dwordx4 v[220:223], v225, s[4:5] offset:48
	s_waitcnt vmcnt(4)
; #define GAS __attribute__((address_space(1)))
; __device__ __forceinline__ unsigned cvt_pk_bf16(float lo, float hi) { f32x2 v = {lo, hi}; bf16x2_t b = __builtin_convertvector(v, bf16x2_t); return __builtin_bit_cast(unsigned, b); }
; __device__ __forceinline__ float sigmoid_f(float x) { return __builtin_amdgcn_rcpf(1.0f + __builtin_amdgcn_exp2f(-x * LOG2E)); }
; __device__ __forceinline__ float row_rs(const GAS float* rowss, int row) {
;     const GAS f32x4* p = (const GAS f32x4*)(rowss + (size_t)row * 16); const f32x4 a = p[0], b = p[1], c = p[2], d = p[3];
;     const float s = ((a[0] + a[1]) + (a[2] + a[3])) + ((b[0] + b[1]) + (b[2] + b[3])) + ((c[0] + c[1]) + (c[2] + c[3])) + ((d[0] + d[1]) + (d[2] + d[3]));
;     return __builtin_amdgcn_rsqf(s * (1.0f / 1024.0f) + 1e-6f);
; }
;     __device__ __forceinline__ void operator()(const f32x4 (&acc)[2][2][4][2], const Unit& u, int wr, int wc, int fr, int fq) const {
;         const int row0 = u.pm * BM + wr * 64 + fr; const int col0 = (u.pn * BM + wc * 32 + 8 * fq) >> 1;
; #pragma unroll
;         for (int ai = 0; ai < 2; ++ai)
; #pragma unroll
;             for (int m = 0; m < 4; ++m) { const int row = row0 + ai * HALF + m * 16; const float rs = row_rs(rowss, row); GAS bf16_t* rowp = H + (size_t)row * 2816 + col0;
; #pragma unroll
;                 for (int bj = 0; bj < 2; ++bj) { const f32x4 g = acc[ai][bj][m][0] * rs, uu = acc[ai][bj][m][1] * rs;
;                     u32x2 w; w.x = cvt_pk_bf16(g[0] * sigmoid_f(g[0]) * uu[0], g[1] * sigmoid_f(g[1]) * uu[1]); w.y = cvt_pk_bf16(g[2] * sigmoid_f(g[2]) * uu[2], g[3] * sigmoid_f(g[3]) * uu[3]);
;                     *(GAS u32x2*)(rowp + bj * (HALF / 2)) = w; } }
	s_nop 1
	v_mov_b32_e32 v68, v204
	v_mov_b32_e32 v69, v205
	v_mov_b32_e32 v70, v206
	v_mov_b32_e32 v71, v207
	v_mov_b32_e32 v72, v200
	v_mov_b32_e32 v73, v201
	v_mov_b32_e32 v74, v202
	v_mov_b32_e32 v75, v203
	v_mov_b32_e32 v76, v196
	v_mov_b32_e32 v77, v197
	v_mov_b32_e32 v78, v198
	v_mov_b32_e32 v79, v199
	v_mov_b32_e32 v80, v192
	v_mov_b32_e32 v81, v193
	v_mov_b32_e32 v82, v194
	v_mov_b32_e32 v83, v195
	v_add_f32_e32 v72, v72, v73
	v_add_f32_e32 v74, v74, v75
	v_mov_b32_e32 v84, v81
	v_mov_b32_e32 v85, v82
	v_mov_b32_e32 v81, v83
	v_mov_b32_e32 v82, v77
	v_mov_b32_e32 v83, v78
	v_mov_b32_e32 v77, v79
	v_pk_add_f32 v[80:81], v[84:85], v[80:81]
	v_pk_add_f32 v[76:77], v[82:83], v[76:77]
	v_pk_add_f32 v[80:81], v[80:81], v[80:81] op_sel:[0,1] op_sel_hi:[1,0]
	v_pk_add_f32 v[76:77], v[76:77], v[76:77] op_sel:[0,1] op_sel_hi:[1,0]
	v_mov_b32_e32 v81, v68
	v_mov_b32_e32 v77, v69
	v_mov_b32_e32 v73, v70
	v_mov_b32_e32 v75, v71
	v_pk_add_f32 v[68:69], v[80:81], v[76:77]
	v_pk_add_f32 v[70:71], v[72:73], v[74:75]
	s_nop 0
	v_pk_add_f32 v[68:69], v[68:69], v[70:71]
	s_nop 0
	v_add_f32_e32 v67, v68, v69
	v_fmamk_f32 v67, v67, 0x3a800000, v234
	v_rsq_f32_e32 v68, v67
	v_mad_i64_i32 v[66:67], s[18:19], v66, s11, v[140:141]
	v_lshl_add_u64 v[66:67], v[66:67], 0, v[142:143]
	v_pk_mul_f32 v[62:63], v[62:63], v[68:69] op_sel_hi:[1,0]
	v_pk_mul_f32 v[64:65], v[64:65], v[68:69] op_sel_hi:[1,0]
	v_pk_mul_f32 v[60:61], v[60:61], v[68:69] op_sel_hi:[1,0]
	v_pk_mul_f32 v[58:59], v[58:59], v[68:69] op_sel_hi:[1,0]
	v_mul_f32_e32 v69, 0xbfb8aa3b, v62
	v_exp_f32_e32 v69, v69
	s_nop 0
	v_add_f32_e32 v69, 1.0, v69
	v_rcp_f32_e32 v70, v69
	v_mul_f32_e32 v69, 0xbfb8aa3b, v63
	v_exp_f32_e32 v69, v69
	s_nop 0
	v_add_f32_e32 v69, 1.0, v69
	v_rcp_f32_e32 v71, v69
	v_pk_mul_f32 v[54:55], v[54:55], v[68:69] op_sel_hi:[1,0]
	v_pk_mul_f32 v[50:51], v[50:51], v[68:69] op_sel_hi:[1,0]
	v_pk_mul_f32 v[56:57], v[56:57], v[68:69] op_sel_hi:[1,0]
	v_pk_mul_f32 v[62:63], v[62:63], v[70:71]
	v_pk_mul_f32 v[52:53], v[52:53], v[68:69] op_sel_hi:[1,0]
	v_pk_mul_f32 v[58:59], v[58:59], v[62:63]
	s_nop 0
	v_cvt_pk_bf16_f32 v58, v58, v59
	v_mul_f32_e32 v59, 0xbfb8aa3b, v64
	v_exp_f32_e32 v59, v59
	s_nop 0
	v_add_f32_e32 v59, 1.0, v59
	v_rcp_f32_e32 v62, v59
	v_mul_f32_e32 v59, 0xbfb8aa3b, v65
	v_exp_f32_e32 v59, v59
	s_nop 0
	v_add_f32_e32 v59, 1.0, v59
	v_rcp_f32_e32 v63, v59
	s_nop 0
	v_pk_mul_f32 v[62:63], v[64:65], v[62:63]
	s_nop 0
	v_pk_mul_f32 v[60:61], v[60:61], v[62:63]
	s_nop 0
	v_cvt_pk_bf16_f32 v59, v60, v61
	global_store_dwordx2 v[66:67], v[58:59], off
	v_mul_f32_e32 v58, 0xbfb8aa3b, v54
	v_mul_f32_e32 v59, 0xbfb8aa3b, v55
	v_exp_f32_e32 v58, v58
	v_exp_f32_e32 v59, v59
	v_add_f32_e32 v58, 1.0, v58
	v_add_f32_e32 v59, 1.0, v59
	v_rcp_f32_e32 v58, v58
	v_rcp_f32_e32 v59, v59
	s_nop 0
	v_pk_mul_f32 v[54:55], v[54:55], v[58:59]
	s_nop 0
	v_pk_mul_f32 v[50:51], v[50:51], v[54:55]
	s_nop 0
	v_cvt_pk_bf16_f32 v50, v50, v51
	v_mul_f32_e32 v51, 0xbfb8aa3b, v56
	v_exp_f32_e32 v51, v51
	s_nop 0
	v_add_f32_e32 v51, 1.0, v51
	v_rcp_f32_e32 v54, v51
	v_mul_f32_e32 v51, 0xbfb8aa3b, v57
	v_exp_f32_e32 v51, v51
	s_nop 0
	v_add_f32_e32 v51, 1.0, v51
	v_rcp_f32_e32 v55, v51
	s_nop 0
	v_pk_mul_f32 v[54:55], v[56:57], v[54:55]
	s_nop 0
	v_pk_mul_f32 v[52:53], v[52:53], v[54:55]
	s_nop 0
	v_cvt_pk_bf16_f32 v51, v52, v53
	global_store_dwordx2 v[66:67], v[50:51], off offset:128
	v_add_u32_e32 v50, 0x90, v144
	v_ashrrev_i32_e32 v51, 31, v50
	v_lshlrev_b64 v[52:53], 6, v[50:51]
	v_lshl_add_u64 v[64:65], s[4:5], 0, v[52:53]
	s_nop 0
	v_add_u32_e32 v225, 0x2800, v224
	global_load_dwordx4 v[192:195], v225, s[4:5]
	global_load_dwordx4 v[196:199], v225, s[4:5] offset:16
	global_load_dwordx4 v[200:203], v225, s[4:5] offset:32
	global_load_dwordx4 v[204:207], v225, s[4:5] offset:48
	s_waitcnt vmcnt(4)
	s_nop 1
	v_mov_b32_e32 v52, v220
	v_mov_b32_e32 v53, v221
	v_mov_b32_e32 v54, v222
	v_mov_b32_e32 v55, v223
	v_mov_b32_e32 v56, v216
	v_mov_b32_e32 v57, v217
	v_mov_b32_e32 v58, v218
	v_mov_b32_e32 v59, v219
	v_mov_b32_e32 v60, v212
	v_mov_b32_e32 v61, v213
	v_mov_b32_e32 v62, v214
	v_mov_b32_e32 v63, v215
	v_mov_b32_e32 v64, v208
	v_mov_b32_e32 v65, v209
	v_mov_b32_e32 v66, v210
	v_mov_b32_e32 v67, v211
	v_add_f32_e32 v56, v56, v57
	v_add_f32_e32 v58, v58, v59
	v_mov_b32_e32 v68, v65
	v_mov_b32_e32 v69, v66
	v_mov_b32_e32 v65, v67
	v_mov_b32_e32 v66, v61
	v_mov_b32_e32 v67, v62
	v_mov_b32_e32 v61, v63
	v_pk_add_f32 v[64:65], v[68:69], v[64:65]
	v_pk_add_f32 v[60:61], v[66:67], v[60:61]
	v_pk_add_f32 v[64:65], v[64:65], v[64:65] op_sel:[0,1] op_sel_hi:[1,0]
	v_pk_add_f32 v[60:61], v[60:61], v[60:61] op_sel:[0,1] op_sel_hi:[1,0]
	v_mov_b32_e32 v65, v52
	v_mov_b32_e32 v61, v53
	v_mov_b32_e32 v57, v54
	v_mov_b32_e32 v59, v55
	v_pk_add_f32 v[52:53], v[64:65], v[60:61]
	v_pk_add_f32 v[54:55], v[56:57], v[58:59]
	s_nop 0
	v_pk_add_f32 v[52:53], v[52:53], v[54:55]
	s_nop 0
	v_add_f32_e32 v51, v52, v53
	v_fmamk_f32 v51, v51, 0x3a800000, v234
	v_rsq_f32_e32 v52, v51
	v_mad_i64_i32 v[50:51], s[18:19], v50, s11, v[140:141]
	v_lshl_add_u64 v[50:51], v[50:51], 0, v[142:143]
	v_pk_mul_f32 v[46:47], v[46:47], v[52:53] op_sel_hi:[1,0]
	v_pk_mul_f32 v[48:49], v[48:49], v[52:53] op_sel_hi:[1,0]
	v_pk_mul_f32 v[44:45], v[44:45], v[52:53] op_sel_hi:[1,0]
	v_pk_mul_f32 v[42:43], v[42:43], v[52:53] op_sel_hi:[1,0]
	v_mul_f32_e32 v53, 0xbfb8aa3b, v46
	v_exp_f32_e32 v53, v53
	s_nop 0
	v_add_f32_e32 v53, 1.0, v53
	v_rcp_f32_e32 v54, v53
	v_mul_f32_e32 v53, 0xbfb8aa3b, v47
	v_exp_f32_e32 v53, v53
	s_nop 0
	v_add_f32_e32 v53, 1.0, v53
	v_rcp_f32_e32 v55, v53
	v_pk_mul_f32 v[38:39], v[38:39], v[52:53] op_sel_hi:[1,0]
; #define GAS __attribute__((address_space(1)))
; __device__ __forceinline__ unsigned cvt_pk_bf16(float lo, float hi) { f32x2 v = {lo, hi}; bf16x2_t b = __builtin_convertvector(v, bf16x2_t); return __builtin_bit_cast(unsigned, b); }
; __device__ __forceinline__ float sigmoid_f(float x) { return __builtin_amdgcn_rcpf(1.0f + __builtin_amdgcn_exp2f(-x * LOG2E)); }
; __device__ __forceinline__ float row_rs(const GAS float* rowss, int row) {
;     const GAS f32x4* p = (const GAS f32x4*)(rowss + (size_t)row * 16); const f32x4 a = p[0], b = p[1], c = p[2], d = p[3];
;     const float s = ((a[0] + a[1]) + (a[2] + a[3])) + ((b[0] + b[1]) + (b[2] + b[3])) + ((c[0] + c[1]) + (c[2] + c[3])) + ((d[0] + d[1]) + (d[2] + d[3]));
;     return __builtin_amdgcn_rsqf(s * (1.0f / 1024.0f) + 1e-6f);
; }
;     __device__ __forceinline__ void operator()(const f32x4 (&acc)[2][2][4][2], const Unit& u, int wr, int wc, int fr, int fq) const {
;         const int row0 = u.pm * BM + wr * 64 + fr; const int col0 = (u.pn * BM + wc * 32 + 8 * fq) >> 1;
; #pragma unroll
;         for (int ai = 0; ai < 2; ++ai)
; #pragma unroll
;             for (int m = 0; m < 4; ++m) { const int row = row0 + ai * HALF + m * 16; const float rs = row_rs(rowss, row); GAS bf16_t* rowp = H + (size_t)row * 2816 + col0;
; #pragma unroll
;                 for (int bj = 0; bj < 2; ++bj) { const f32x4 g = acc[ai][bj][m][0] * rs, uu = acc[ai][bj][m][1] * rs;
;                     u32x2 w; w.x = cvt_pk_bf16(g[0] * sigmoid_f(g[0]) * uu[0], g[1] * sigmoid_f(g[1]) * uu[1]); w.y = cvt_pk_bf16(g[2] * sigmoid_f(g[2]) * uu[2], g[3] * sigmoid_f(g[3]) * uu[3]);
;                     *(GAS u32x2*)(rowp + bj * (HALF / 2)) = w; } }
	v_pk_mul_f32 v[34:35], v[34:35], v[52:53] op_sel_hi:[1,0]
	v_pk_mul_f32 v[40:41], v[40:41], v[52:53] op_sel_hi:[1,0]
	v_pk_mul_f32 v[46:47], v[46:47], v[54:55]
	v_pk_mul_f32 v[36:37], v[36:37], v[52:53] op_sel_hi:[1,0]
	v_pk_mul_f32 v[42:43], v[42:43], v[46:47]
	s_nop 0
	v_cvt_pk_bf16_f32 v42, v42, v43
	v_mul_f32_e32 v43, 0xbfb8aa3b, v48
	v_exp_f32_e32 v43, v43
	s_nop 0
	v_add_f32_e32 v43, 1.0, v43
	v_rcp_f32_e32 v46, v43
	v_mul_f32_e32 v43, 0xbfb8aa3b, v49
	v_exp_f32_e32 v43, v43
	s_nop 0
	v_add_f32_e32 v43, 1.0, v43
	v_rcp_f32_e32 v47, v43
	s_nop 0
	v_pk_mul_f32 v[46:47], v[48:49], v[46:47]
	s_nop 0
	v_pk_mul_f32 v[44:45], v[44:45], v[46:47]
	s_nop 0
	v_cvt_pk_bf16_f32 v43, v44, v45
	global_store_dwordx2 v[50:51], v[42:43], off
	v_mul_f32_e32 v42, 0xbfb8aa3b, v38
	v_mul_f32_e32 v43, 0xbfb8aa3b, v39
	v_exp_f32_e32 v42, v42
	v_exp_f32_e32 v43, v43
	v_add_f32_e32 v42, 1.0, v42
	v_add_f32_e32 v43, 1.0, v43
	v_rcp_f32_e32 v42, v42
	v_rcp_f32_e32 v43, v43
	s_nop 0
	v_pk_mul_f32 v[38:39], v[38:39], v[42:43]
	s_nop 0
	v_pk_mul_f32 v[34:35], v[34:35], v[38:39]
	s_nop 0
	v_cvt_pk_bf16_f32 v34, v34, v35
	v_mul_f32_e32 v35, 0xbfb8aa3b, v40
	v_exp_f32_e32 v35, v35
	s_nop 0
	v_add_f32_e32 v35, 1.0, v35
	v_rcp_f32_e32 v38, v35
	v_mul_f32_e32 v35, 0xbfb8aa3b, v41
	v_exp_f32_e32 v35, v35
	s_nop 0
	v_add_f32_e32 v35, 1.0, v35
	v_rcp_f32_e32 v39, v35
	s_nop 0
	v_pk_mul_f32 v[38:39], v[40:41], v[38:39]
	s_nop 0
	v_pk_mul_f32 v[36:37], v[36:37], v[38:39]
	s_nop 0
	v_cvt_pk_bf16_f32 v35, v36, v37
	global_store_dwordx2 v[50:51], v[34:35], off offset:128
	v_add_u32_e32 v34, 0xa0, v144
	v_ashrrev_i32_e32 v35, 31, v34
	v_lshlrev_b64 v[36:37], 6, v[34:35]
	v_lshl_add_u64 v[48:49], s[4:5], 0, v[36:37]
	s_nop 0
	v_add_u32_e32 v225, 0x2c00, v224
	global_load_dwordx4 v[208:211], v225, s[4:5]
	global_load_dwordx4 v[212:215], v225, s[4:5] offset:16
	global_load_dwordx4 v[216:219], v225, s[4:5] offset:32
	global_load_dwordx4 v[220:223], v225, s[4:5] offset:48
	s_waitcnt vmcnt(4)
	s_nop 1
	v_mov_b32_e32 v36, v204
	v_mov_b32_e32 v37, v205
	v_mov_b32_e32 v38, v206
	v_mov_b32_e32 v39, v207
	v_mov_b32_e32 v40, v200
	v_mov_b32_e32 v41, v201
	v_mov_b32_e32 v42, v202
	v_mov_b32_e32 v43, v203
	v_mov_b32_e32 v44, v196
	v_mov_b32_e32 v45, v197
	v_mov_b32_e32 v46, v198
	v_mov_b32_e32 v47, v199
	v_mov_b32_e32 v48, v192
	v_mov_b32_e32 v49, v193
	v_mov_b32_e32 v50, v194
	v_mov_b32_e32 v51, v195
	v_add_f32_e32 v40, v40, v41
	v_add_f32_e32 v42, v42, v43
	v_mov_b32_e32 v52, v49
	v_mov_b32_e32 v53, v50
	v_mov_b32_e32 v49, v51
	v_mov_b32_e32 v50, v45
	v_mov_b32_e32 v51, v46
	v_mov_b32_e32 v45, v47
	v_pk_add_f32 v[48:49], v[52:53], v[48:49]
	v_pk_add_f32 v[44:45], v[50:51], v[44:45]
	v_pk_add_f32 v[48:49], v[48:49], v[48:49] op_sel:[0,1] op_sel_hi:[1,0]
	v_pk_add_f32 v[44:45], v[44:45], v[44:45] op_sel:[0,1] op_sel_hi:[1,0]
	v_mov_b32_e32 v49, v36
	v_mov_b32_e32 v45, v37
	v_mov_b32_e32 v41, v38
	v_mov_b32_e32 v43, v39
	v_pk_add_f32 v[36:37], v[48:49], v[44:45]
	v_pk_add_f32 v[38:39], v[40:41], v[42:43]
	s_nop 0
	v_pk_add_f32 v[36:37], v[36:37], v[38:39]
	s_nop 0
	v_add_f32_e32 v35, v36, v37
	v_fmamk_f32 v35, v35, 0x3a800000, v234
	v_rsq_f32_e32 v36, v35
	v_mad_i64_i32 v[34:35], s[18:19], v34, s11, v[140:141]
	v_lshl_add_u64 v[34:35], v[34:35], 0, v[142:143]
	v_pk_mul_f32 v[30:31], v[30:31], v[36:37] op_sel_hi:[1,0]
	v_pk_mul_f32 v[32:33], v[32:33], v[36:37] op_sel_hi:[1,0]
	v_pk_mul_f32 v[28:29], v[28:29], v[36:37] op_sel_hi:[1,0]
	v_pk_mul_f32 v[26:27], v[26:27], v[36:37] op_sel_hi:[1,0]
	v_mul_f32_e32 v37, 0xbfb8aa3b, v30
	v_exp_f32_e32 v37, v37
	s_nop 0
	v_add_f32_e32 v37, 1.0, v37
	v_rcp_f32_e32 v38, v37
	v_mul_f32_e32 v37, 0xbfb8aa3b, v31
	v_exp_f32_e32 v37, v37
	s_nop 0
	v_add_f32_e32 v37, 1.0, v37
	v_rcp_f32_e32 v39, v37
	v_pk_mul_f32 v[22:23], v[22:23], v[36:37] op_sel_hi:[1,0]
	v_pk_mul_f32 v[18:19], v[18:19], v[36:37] op_sel_hi:[1,0]
	v_pk_mul_f32 v[24:25], v[24:25], v[36:37] op_sel_hi:[1,0]
	v_pk_mul_f32 v[30:31], v[30:31], v[38:39]
	v_pk_mul_f32 v[20:21], v[20:21], v[36:37] op_sel_hi:[1,0]
	v_pk_mul_f32 v[26:27], v[26:27], v[30:31]
	s_nop 0
	v_cvt_pk_bf16_f32 v26, v26, v27
	v_mul_f32_e32 v27, 0xbfb8aa3b, v32
	v_exp_f32_e32 v27, v27
	s_nop 0
	v_add_f32_e32 v27, 1.0, v27
	v_rcp_f32_e32 v30, v27
	v_mul_f32_e32 v27, 0xbfb8aa3b, v33
	v_exp_f32_e32 v27, v27
	s_nop 0
	v_add_f32_e32 v27, 1.0, v27
	v_rcp_f32_e32 v31, v27
	s_nop 0
	v_pk_mul_f32 v[30:31], v[32:33], v[30:31]
	s_nop 0
	v_pk_mul_f32 v[28:29], v[28:29], v[30:31]
	s_nop 0
	v_cvt_pk_bf16_f32 v27, v28, v29
	global_store_dwordx2 v[34:35], v[26:27], off
	v_mul_f32_e32 v26, 0xbfb8aa3b, v22
	v_mul_f32_e32 v27, 0xbfb8aa3b, v23
	v_exp_f32_e32 v26, v26
	v_exp_f32_e32 v27, v27
	v_add_f32_e32 v26, 1.0, v26
	v_add_f32_e32 v27, 1.0, v27
	v_rcp_f32_e32 v26, v26
	v_rcp_f32_e32 v27, v27
	s_nop 0
	v_pk_mul_f32 v[22:23], v[22:23], v[26:27]
	s_nop 0
	v_pk_mul_f32 v[18:19], v[18:19], v[22:23]
	s_nop 0
	v_cvt_pk_bf16_f32 v18, v18, v19
	v_mul_f32_e32 v19, 0xbfb8aa3b, v24
	v_exp_f32_e32 v19, v19
	s_nop 0
	v_add_f32_e32 v19, 1.0, v19
	v_rcp_f32_e32 v22, v19
	v_mul_f32_e32 v19, 0xbfb8aa3b, v25
	v_exp_f32_e32 v19, v19
	s_nop 0
	v_add_f32_e32 v19, 1.0, v19
	v_rcp_f32_e32 v23, v19
	s_nop 0
	v_pk_mul_f32 v[22:23], v[24:25], v[22:23]
	s_nop 0
	v_pk_mul_f32 v[20:21], v[20:21], v[22:23]
	s_nop 0
	v_cvt_pk_bf16_f32 v19, v20, v21
	global_store_dwordx2 v[34:35], v[18:19], off offset:128
	v_add_u32_e32 v18, 0xb0, v144
	v_ashrrev_i32_e32 v19, 31, v18
	v_lshlrev_b64 v[20:21], 6, v[18:19]
	v_lshl_add_u64 v[32:33], s[4:5], 0, v[20:21]
	s_nop 0
	s_waitcnt vmcnt(0)
; #define GAS __attribute__((address_space(1)))
; __device__ __forceinline__ unsigned cvt_pk_bf16(float lo, float hi) { f32x2 v = {lo, hi}; bf16x2_t b = __builtin_convertvector(v, bf16x2_t); return __builtin_bit_cast(unsigned, b); }
; __device__ __forceinline__ float sigmoid_f(float x) { return __builtin_amdgcn_rcpf(1.0f + __builtin_amdgcn_exp2f(-x * LOG2E)); }
; __device__ __forceinline__ float row_rs(const GAS float* rowss, int row) {
;     const GAS f32x4* p = (const GAS f32x4*)(rowss + (size_t)row * 16); const f32x4 a = p[0], b = p[1], c = p[2], d = p[3];
;     const float s = ((a[0] + a[1]) + (a[2] + a[3])) + ((b[0] + b[1]) + (b[2] + b[3])) + ((c[0] + c[1]) + (c[2] + c[3])) + ((d[0] + d[1]) + (d[2] + d[3]));
;     return __builtin_amdgcn_rsqf(s * (1.0f / 1024.0f) + 1e-6f);
; }
;     __device__ __forceinline__ void operator()(const f32x4 (&acc)[2][2][4][2], const Unit& u, int wr, int wc, int fr, int fq) const {
;         const int row0 = u.pm * BM + wr * 64 + fr; const int col0 = (u.pn * BM + wc * 32 + 8 * fq) >> 1;
; #pragma unroll
;         for (int ai = 0; ai < 2; ++ai)
; #pragma unroll
;             for (int m = 0; m < 4; ++m) { const int row = row0 + ai * HALF + m * 16; const float rs = row_rs(rowss, row); GAS bf16_t* rowp = H + (size_t)row * 2816 + col0;
; #pragma unroll
;                 for (int bj = 0; bj < 2; ++bj) { const f32x4 g = acc[ai][bj][m][0] * rs, uu = acc[ai][bj][m][1] * rs;
;                     u32x2 w; w.x = cvt_pk_bf16(g[0] * sigmoid_f(g[0]) * uu[0], g[1] * sigmoid_f(g[1]) * uu[1]); w.y = cvt_pk_bf16(g[2] * sigmoid_f(g[2]) * uu[2], g[3] * sigmoid_f(g[3]) * uu[3]);
;                     *(GAS u32x2*)(rowp + bj * (HALF / 2)) = w; } }
	s_nop 1
	v_mov_b32_e32 v20, v220
	v_mov_b32_e32 v21, v221
	v_mov_b32_e32 v22, v222
	v_mov_b32_e32 v23, v223
	v_mov_b32_e32 v24, v216
	v_mov_b32_e32 v25, v217
	v_mov_b32_e32 v26, v218
	v_mov_b32_e32 v27, v219
	v_mov_b32_e32 v28, v212
	v_mov_b32_e32 v29, v213
	v_mov_b32_e32 v30, v214
	v_mov_b32_e32 v31, v215
	v_mov_b32_e32 v32, v208
	v_mov_b32_e32 v33, v209
	v_mov_b32_e32 v34, v210
	v_mov_b32_e32 v35, v211
	v_add_f32_e32 v24, v24, v25
	v_add_f32_e32 v26, v26, v27
	v_mov_b32_e32 v36, v33
	v_mov_b32_e32 v37, v34
	v_mov_b32_e32 v33, v35
	v_mov_b32_e32 v34, v29
	v_mov_b32_e32 v35, v30
	v_mov_b32_e32 v29, v31
	v_pk_add_f32 v[32:33], v[36:37], v[32:33]
	v_pk_add_f32 v[28:29], v[34:35], v[28:29]
	v_pk_add_f32 v[32:33], v[32:33], v[32:33] op_sel:[0,1] op_sel_hi:[1,0]
	v_pk_add_f32 v[28:29], v[28:29], v[28:29] op_sel:[0,1] op_sel_hi:[1,0]
	v_mov_b32_e32 v33, v20
	v_mov_b32_e32 v29, v21
	v_mov_b32_e32 v25, v22
	v_mov_b32_e32 v27, v23
	v_pk_add_f32 v[20:21], v[32:33], v[28:29]
	v_pk_add_f32 v[22:23], v[24:25], v[26:27]
	s_nop 0
	v_pk_add_f32 v[20:21], v[20:21], v[22:23]
	s_nop 0
	v_add_f32_e32 v19, v20, v21
	v_fmamk_f32 v19, v19, 0x3a800000, v234
	v_rsq_f32_e32 v20, v19
	v_mad_i64_i32 v[18:19], s[18:19], v18, s11, v[140:141]
	v_lshl_add_u64 v[18:19], v[18:19], 0, v[142:143]
	v_pk_mul_f32 v[14:15], v[14:15], v[20:21] op_sel_hi:[1,0]
	v_pk_mul_f32 v[16:17], v[16:17], v[20:21] op_sel_hi:[1,0]
	v_pk_mul_f32 v[12:13], v[12:13], v[20:21] op_sel_hi:[1,0]
	v_pk_mul_f32 v[10:11], v[10:11], v[20:21] op_sel_hi:[1,0]
	v_mul_f32_e32 v21, 0xbfb8aa3b, v14
	v_exp_f32_e32 v21, v21
	s_mov_b64 s[18:19], -1
	v_add_f32_e32 v21, 1.0, v21
	v_rcp_f32_e32 v22, v21
	v_mul_f32_e32 v21, 0xbfb8aa3b, v15
	v_exp_f32_e32 v21, v21
	s_nop 0
	v_add_f32_e32 v21, 1.0, v21
	v_rcp_f32_e32 v23, v21
	v_pk_mul_f32 v[6:7], v[6:7], v[20:21] op_sel_hi:[1,0]
	v_pk_mul_f32 v[2:3], v[2:3], v[20:21] op_sel_hi:[1,0]
	v_pk_mul_f32 v[8:9], v[8:9], v[20:21] op_sel_hi:[1,0]
	v_pk_mul_f32 v[14:15], v[14:15], v[22:23]
	v_pk_mul_f32 v[4:5], v[4:5], v[20:21] op_sel_hi:[1,0]
	v_pk_mul_f32 v[10:11], v[10:11], v[14:15]
	s_nop 0
	v_cvt_pk_bf16_f32 v10, v10, v11
	v_mul_f32_e32 v11, 0xbfb8aa3b, v16
	v_exp_f32_e32 v11, v11
	s_nop 0
	v_add_f32_e32 v11, 1.0, v11
	v_rcp_f32_e32 v14, v11
	v_mul_f32_e32 v11, 0xbfb8aa3b, v17
	v_exp_f32_e32 v11, v11
	s_nop 0
	v_add_f32_e32 v11, 1.0, v11
	v_rcp_f32_e32 v15, v11
	s_nop 0
	v_pk_mul_f32 v[14:15], v[16:17], v[14:15]
	s_nop 0
	v_pk_mul_f32 v[12:13], v[12:13], v[14:15]
	s_nop 0
	v_cvt_pk_bf16_f32 v11, v12, v13
	global_store_dwordx2 v[18:19], v[10:11], off
	v_mul_f32_e32 v10, 0xbfb8aa3b, v6
	v_mul_f32_e32 v11, 0xbfb8aa3b, v7
	v_exp_f32_e32 v10, v10
	v_exp_f32_e32 v11, v11
	v_add_f32_e32 v10, 1.0, v10
	v_add_f32_e32 v11, 1.0, v11
	v_rcp_f32_e32 v10, v10
	v_rcp_f32_e32 v11, v11
	s_nop 0
	v_pk_mul_f32 v[6:7], v[6:7], v[10:11]
	s_nop 0
	v_pk_mul_f32 v[2:3], v[2:3], v[6:7]
	s_nop 0
	v_cvt_pk_bf16_f32 v2, v2, v3
	v_mul_f32_e32 v3, 0xbfb8aa3b, v8
	v_exp_f32_e32 v3, v3
	s_nop 0
	v_add_f32_e32 v3, 1.0, v3
	v_rcp_f32_e32 v6, v3
	v_mul_f32_e32 v3, 0xbfb8aa3b, v9
	v_exp_f32_e32 v3, v3
	s_nop 0
	v_add_f32_e32 v3, 1.0, v3
	v_rcp_f32_e32 v7, v3
	s_nop 0
	v_pk_mul_f32 v[6:7], v[8:9], v[6:7]
	s_nop 0
	v_pk_mul_f32 v[4:5], v[4:5], v[6:7]
	s_nop 0
	v_cvt_pk_bf16_f32 v3, v4, v5
	global_store_dwordx2 v[18:19], v[2:3], off offset:128
	s_cbranch_vccnz .LBB0_748
	s_andn2_b64 vcc, exec, s[0:1]
	s_cbranch_vccnz .LBB0_747
	s_barrier
	s_branch .LBB0_747

; #define GAS __attribute__((address_space(1)))
; __device__ __forceinline__ unsigned cvt_pk_bf16(float lo, float hi) { f32x2 v = {lo, hi}; bf16x2_t b = __builtin_convertvector(v, bf16x2_t); return __builtin_bit_cast(unsigned, b); }
; __device__ __forceinline__ float bf_lo(unsigned u) { return __uint_as_float(u << 16); }
; __device__ __forceinline__ float bf_hi(unsigned u) { return __uint_as_float(u & 0xffff0000u); }
;     __device__ __forceinline__ void operator()(const f32x4 (&acc)[2][2][4][2], const Unit& u, int wr, int wc, int fr, int fq) const {
;     ...
;             for (int m = 0; m < 4; ++m) { const int row = row0 + ai * HALF + m * 16; const size_t off = (size_t)row * 1024 + col0; float q = 0.f;
; #pragma unroll
;                 for (int bj = 0; bj < 2; ++bj) { const u32x4 xo = *(const GAS u32x4*)(xb + off + bj * HALF);
;                     f32x4 v0 = acc[ai][bj][m][0], v1 = acc[ai][bj][m][1];
;                     v0[0] += bf_lo(xo.x); v0[1] += bf_hi(xo.x); v0[2] += bf_lo(xo.y); v0[3] += bf_hi(xo.y); v1[0] += bf_lo(xo.z); v1[1] += bf_hi(xo.z); v1[2] += bf_lo(xo.w); v1[3] += bf_hi(xo.w);
;                     if (out) { *(GAS f32x4*)(out + off + bj * HALF) = v0; *(GAS f32x4*)(out + off + bj * HALF + 4) = v1; }
;                     u32x4 w; w.x = cvt_pk_bf16(v0[0], v0[1]); w.y = cvt_pk_bf16(v0[2], v0[3]); w.z = cvt_pk_bf16(v1[0], v1[1]); w.w = cvt_pk_bf16(v1[2], v1[3]);
;                     *(GAS u32x4*)(xb + off + bj * HALF) = w;
;                     q += ((v0[0] * v0[0] + v0[1] * v0[1]) + (v0[2] * v0[2] + v0[3] * v0[3])) + ((v1[0] * v1[0] + v1[1] * v1[1]) + (v1[2] * v1[2] + v1[3] * v1[3])); }
;                 q += __shfl_xor(q, 16); q += __shfl_xor(q, 32);
;                 if (fq == 0) rowss[(size_t)row * 16 + u.pn * 4 + wc] = q; }
.LBB0_842:
	v_lshl_add_u32 v142, s49, 8, v148
	v_lshl_or_b32 v140, s48, 8, v150
	v_ashrrev_i32_e32 v143, 31, v142
	v_ashrrev_i32_e32 v141, 31, v140
	v_lshlrev_b64 v[144:145], 10, v[142:143]
	v_lshl_add_u64 v[146:147], v[144:145], 0, v[140:141]
	v_lshl_add_u64 v[144:145], v[146:147], 1, s[12:13]
	s_andn2_b64 vcc, exec, s[18:19]
	v_lshl_add_u64 v[146:147], v[146:147], 2, s[2:3]
	v_lshlrev_b32_e32 v224, 11, v142
	v_lshl_add_u32 v224, v140, 1, v224
	global_load_dwordx4 v[192:195], v224, s[12:13]
	global_load_dwordx4 v[196:199], v224, s[12:13] offset:256
	v_add_u32_e32 v225, 0x8000, v224
	global_load_dwordx4 v[200:203], v225, s[12:13]
	global_load_dwordx4 v[204:207], v225, s[12:13] offset:256
	v_add_u32_e32 v225, 0x10000, v224
	global_load_dwordx4 v[208:211], v225, s[12:13]
	global_load_dwordx4 v[212:215], v225, s[12:13] offset:256
	v_add_u32_e32 v225, 0x18000, v224
	global_load_dwordx4 v[216:219], v225, s[12:13]
	global_load_dwordx4 v[220:223], v225, s[12:13] offset:256
	s_waitcnt vmcnt(0)
	s_nop 1
	v_mov_b32_e32 v152, v192
	v_mov_b32_e32 v153, v193
	v_mov_b32_e32 v154, v194
	v_mov_b32_e32 v155, v195
	v_lshlrev_b32_e32 v156, 16, v152
	v_and_b32_e32 v157, 0xffff0000, v152
	v_lshlrev_b32_e32 v152, 16, v153
	v_and_b32_e32 v153, 0xffff0000, v153
	v_pk_add_f32 v[128:129], v[128:129], v[152:153]
	v_lshlrev_b32_e32 v152, 16, v154
	v_and_b32_e32 v153, 0xffff0000, v154
	v_pk_add_f32 v[122:123], v[122:123], v[152:153]
	v_lshlrev_b32_e32 v152, 16, v155
	v_and_b32_e32 v153, 0xffff0000, v155
	v_pk_add_f32 v[124:125], v[124:125], v[152:153]
	v_cndmask_b32_e64 v152, 0, 1, s[18:19]
	v_pk_add_f32 v[126:127], v[126:127], v[156:157]
	v_cmp_ne_u32_e64 s[10:11], 1, v152
	s_cbranch_vccnz .LBB0_844
	global_store_dwordx4 v[146:147], v[126:129], off
	global_store_dwordx4 v[146:147], v[122:125], off offset:16
.LBB0_844:
	v_cvt_pk_bf16_f32 v152, v126, v127
	v_cvt_pk_bf16_f32 v153, v128, v129
	v_cvt_pk_bf16_f32 v154, v122, v123
	v_cvt_pk_bf16_f32 v155, v124, v125
	global_store_dwordx4 v[144:145], v[152:155], off
	s_and_b64 vcc, exec, s[10:11]
	s_nop 1
	v_mov_b32_e32 v152, v196
	v_mov_b32_e32 v153, v197
	v_mov_b32_e32 v154, v198
	v_mov_b32_e32 v155, v199
	v_lshlrev_b32_e32 v156, 16, v152
	v_and_b32_e32 v157, 0xffff0000, v152
	v_lshlrev_b32_e32 v152, 16, v153
	v_and_b32_e32 v153, 0xffff0000, v153
	v_pk_add_f32 v[120:121], v[120:121], v[152:153]
	v_lshlrev_b32_e32 v152, 16, v154
	v_and_b32_e32 v153, 0xffff0000, v154
	v_pk_add_f32 v[114:115], v[114:115], v[152:153]
	v_lshlrev_b32_e32 v152, 16, v155
	v_and_b32_e32 v153, 0xffff0000, v155
	v_pk_add_f32 v[118:119], v[118:119], v[156:157]
	v_pk_add_f32 v[116:117], v[116:117], v[152:153]
	s_cbranch_vccnz .LBB0_846
	global_store_dwordx4 v[146:147], v[118:121], off offset:512
	global_store_dwordx4 v[146:147], v[114:117], off offset:528

; #define GAS __attribute__((address_space(1)))
; __device__ __forceinline__ unsigned cvt_pk_bf16(float lo, float hi) { f32x2 v = {lo, hi}; bf16x2_t b = __builtin_convertvector(v, bf16x2_t); return __builtin_bit_cast(unsigned, b); }
; __device__ __forceinline__ float bf_lo(unsigned u) { return __uint_as_float(u << 16); }
; __device__ __forceinline__ float bf_hi(unsigned u) { return __uint_as_float(u & 0xffff0000u); }
;     __device__ __forceinline__ void operator()(const f32x4 (&acc)[2][2][4][2], const Unit& u, int wr, int wc, int fr, int fq) const {
;     ...
;             for (int m = 0; m < 4; ++m) { const int row = row0 + ai * HALF + m * 16; const size_t off = (size_t)row * 1024 + col0; float q = 0.f;
; #pragma unroll
;                 for (int bj = 0; bj < 2; ++bj) { const u32x4 xo = *(const GAS u32x4*)(xb + off + bj * HALF);
;                     f32x4 v0 = acc[ai][bj][m][0], v1 = acc[ai][bj][m][1];
;                     v0[0] += bf_lo(xo.x); v0[1] += bf_hi(xo.x); v0[2] += bf_lo(xo.y); v0[3] += bf_hi(xo.y); v1[0] += bf_lo(xo.z); v1[1] += bf_hi(xo.z); v1[2] += bf_lo(xo.w); v1[3] += bf_hi(xo.w);
;                     if (out) { *(GAS f32x4*)(out + off + bj * HALF) = v0; *(GAS f32x4*)(out + off + bj * HALF + 4) = v1; }
;                     u32x4 w; w.x = cvt_pk_bf16(v0[0], v0[1]); w.y = cvt_pk_bf16(v0[2], v0[3]); w.z = cvt_pk_bf16(v1[0], v1[1]); w.w = cvt_pk_bf16(v1[2], v1[3]);
;                     *(GAS u32x4*)(xb + off + bj * HALF) = w;
;                     q += ((v0[0] * v0[0] + v0[1] * v0[1]) + (v0[2] * v0[2] + v0[3] * v0[3])) + ((v1[0] * v1[0] + v1[1] * v1[1]) + (v1[2] * v1[2] + v1[3] * v1[3])); }
;                 q += __shfl_xor(q, 16); q += __shfl_xor(q, 32);
;                 if (fq == 0) rowss[(size_t)row * 16 + u.pn * 4 + wc] = q; }
.LBB0_848:
	s_or_b64 exec, exec, s[24:25]
	v_or_b32_e32 v114, 16, v142
	s_waitcnt lgkmcnt(0)
	v_ashrrev_i32_e32 v115, 31, v114
	v_lshlrev_b64 v[116:117], 10, v[114:115]
	v_lshl_add_u64 v[124:125], v[116:117], 0, v[140:141]
	v_lshl_add_u64 v[116:117], v[124:125], 1, s[12:13]
	s_and_b64 vcc, exec, s[10:11]
	s_nop 1
	v_mov_b32_e32 v118, v200
	v_mov_b32_e32 v119, v201
	v_mov_b32_e32 v120, v202
	v_mov_b32_e32 v121, v203
	v_lshlrev_b32_e32 v126, 16, v118
	v_and_b32_e32 v127, 0xffff0000, v118
	v_lshlrev_b32_e32 v118, 16, v119
	v_and_b32_e32 v119, 0xffff0000, v119
	v_pk_add_f32 v[112:113], v[112:113], v[118:119]
	v_lshlrev_b32_e32 v118, 16, v120
	v_and_b32_e32 v119, 0xffff0000, v120
	v_pk_add_f32 v[106:107], v[106:107], v[118:119]
	v_lshlrev_b32_e32 v118, 16, v121
	v_and_b32_e32 v119, 0xffff0000, v121
	v_pk_add_f32 v[110:111], v[110:111], v[126:127]
	v_pk_add_f32 v[108:109], v[108:109], v[118:119]
	v_lshl_add_u64 v[118:119], v[124:125], 2, s[2:3]
	s_cbranch_vccnz .LBB0_850
	global_store_dwordx4 v[118:119], v[110:113], off
	global_store_dwordx4 v[118:119], v[106:109], off offset:16
.LBB0_850:
	v_cvt_pk_bf16_f32 v124, v110, v111
	v_cvt_pk_bf16_f32 v125, v112, v113
	v_cvt_pk_bf16_f32 v126, v106, v107
	v_cvt_pk_bf16_f32 v127, v108, v109
	global_store_dwordx4 v[116:117], v[124:127], off
	s_and_b64 vcc, exec, s[10:11]
	s_nop 1
	v_mov_b32_e32 v124, v204
	v_mov_b32_e32 v125, v205
	v_mov_b32_e32 v126, v206
	v_mov_b32_e32 v127, v207
	v_lshlrev_b32_e32 v120, 16, v124
	v_and_b32_e32 v121, 0xffff0000, v124
	v_pk_add_f32 v[102:103], v[102:103], v[120:121]
	v_lshlrev_b32_e32 v120, 16, v125
	v_and_b32_e32 v121, 0xffff0000, v125
	v_pk_add_f32 v[104:105], v[104:105], v[120:121]
	v_lshlrev_b32_e32 v120, 16, v126
	v_and_b32_e32 v121, 0xffff0000, v126
	v_pk_add_f32 v[98:99], v[98:99], v[120:121]
	v_lshlrev_b32_e32 v120, 16, v127
	v_and_b32_e32 v121, 0xffff0000, v127
	v_pk_add_f32 v[100:101], v[100:101], v[120:121]
	s_cbranch_vccnz .LBB0_852
	global_store_dwordx4 v[118:119], v[102:105], off offset:512
	global_store_dwordx4 v[118:119], v[98:101], off offset:528

; #define GAS __attribute__((address_space(1)))
; __device__ __forceinline__ unsigned cvt_pk_bf16(float lo, float hi) { f32x2 v = {lo, hi}; bf16x2_t b = __builtin_convertvector(v, bf16x2_t); return __builtin_bit_cast(unsigned, b); }
; __device__ __forceinline__ float bf_lo(unsigned u) { return __uint_as_float(u << 16); }
; __device__ __forceinline__ float bf_hi(unsigned u) { return __uint_as_float(u & 0xffff0000u); }
;     __device__ __forceinline__ void operator()(const f32x4 (&acc)[2][2][4][2], const Unit& u, int wr, int wc, int fr, int fq) const {
;     ...
;             for (int m = 0; m < 4; ++m) { const int row = row0 + ai * HALF + m * 16; const size_t off = (size_t)row * 1024 + col0; float q = 0.f;
; #pragma unroll
;                 for (int bj = 0; bj < 2; ++bj) { const u32x4 xo = *(const GAS u32x4*)(xb + off + bj * HALF);
;                     f32x4 v0 = acc[ai][bj][m][0], v1 = acc[ai][bj][m][1];
;                     v0[0] += bf_lo(xo.x); v0[1] += bf_hi(xo.x); v0[2] += bf_lo(xo.y); v0[3] += bf_hi(xo.y); v1[0] += bf_lo(xo.z); v1[1] += bf_hi(xo.z); v1[2] += bf_lo(xo.w); v1[3] += bf_hi(xo.w);
;                     if (out) { *(GAS f32x4*)(out + off + bj * HALF) = v0; *(GAS f32x4*)(out + off + bj * HALF + 4) = v1; }
;                     u32x4 w; w.x = cvt_pk_bf16(v0[0], v0[1]); w.y = cvt_pk_bf16(v0[2], v0[3]); w.z = cvt_pk_bf16(v1[0], v1[1]); w.w = cvt_pk_bf16(v1[2], v1[3]);
;                     *(GAS u32x4*)(xb + off + bj * HALF) = w;
;                     q += ((v0[0] * v0[0] + v0[1] * v0[1]) + (v0[2] * v0[2] + v0[3] * v0[3])) + ((v1[0] * v1[0] + v1[1] * v1[1]) + (v1[2] * v1[2] + v1[3] * v1[3])); }
;                 q += __shfl_xor(q, 16); q += __shfl_xor(q, 32);
;                 if (fq == 0) rowss[(size_t)row * 16 + u.pn * 4 + wc] = q; }
.LBB0_854:
	s_or_b64 exec, exec, s[24:25]
	v_or_b32_e32 v98, 32, v142
	s_waitcnt lgkmcnt(0)
	v_ashrrev_i32_e32 v99, 31, v98
	v_lshlrev_b64 v[100:101], 10, v[98:99]
	v_lshl_add_u64 v[106:107], v[100:101], 0, v[140:141]
	v_lshl_add_u64 v[100:101], v[106:107], 1, s[12:13]
	s_and_b64 vcc, exec, s[10:11]
	s_nop 1
	v_mov_b32_e32 v102, v208
	v_mov_b32_e32 v103, v209
	v_mov_b32_e32 v104, v210
	v_mov_b32_e32 v105, v211
	v_lshlrev_b32_e32 v108, 16, v102
	v_and_b32_e32 v109, 0xffff0000, v102
	v_lshlrev_b32_e32 v102, 16, v103
	v_and_b32_e32 v103, 0xffff0000, v103
	v_pk_add_f32 v[96:97], v[96:97], v[102:103]
	v_lshlrev_b32_e32 v102, 16, v104
	v_and_b32_e32 v103, 0xffff0000, v104
	v_pk_add_f32 v[90:91], v[90:91], v[102:103]
	v_lshlrev_b32_e32 v102, 16, v105
	v_and_b32_e32 v103, 0xffff0000, v105
	v_pk_add_f32 v[94:95], v[94:95], v[108:109]
	v_pk_add_f32 v[92:93], v[92:93], v[102:103]
	v_lshl_add_u64 v[102:103], v[106:107], 2, s[2:3]
	s_cbranch_vccnz .LBB0_856
	global_store_dwordx4 v[102:103], v[94:97], off
	global_store_dwordx4 v[102:103], v[90:93], off offset:16
.LBB0_856:
	v_cvt_pk_bf16_f32 v104, v94, v95
	v_cvt_pk_bf16_f32 v105, v96, v97
	v_cvt_pk_bf16_f32 v106, v90, v91
	v_cvt_pk_bf16_f32 v107, v92, v93
	global_store_dwordx4 v[100:101], v[104:107], off
	s_and_b64 vcc, exec, s[10:11]
	s_nop 1
	v_mov_b32_e32 v104, v212
	v_mov_b32_e32 v105, v213
	v_mov_b32_e32 v106, v214
	v_mov_b32_e32 v107, v215
	v_lshlrev_b32_e32 v108, 16, v104
	v_and_b32_e32 v109, 0xffff0000, v104
	v_lshlrev_b32_e32 v104, 16, v105
	v_and_b32_e32 v105, 0xffff0000, v105
	v_pk_add_f32 v[88:89], v[88:89], v[104:105]
	v_lshlrev_b32_e32 v104, 16, v106
	v_and_b32_e32 v105, 0xffff0000, v106
	v_pk_add_f32 v[82:83], v[82:83], v[104:105]
	v_lshlrev_b32_e32 v104, 16, v107
	v_and_b32_e32 v105, 0xffff0000, v107
	v_pk_add_f32 v[86:87], v[86:87], v[108:109]
	v_pk_add_f32 v[84:85], v[84:85], v[104:105]
	s_cbranch_vccnz .LBB0_858
	global_store_dwordx4 v[102:103], v[86:89], off offset:512
	global_store_dwordx4 v[102:103], v[82:85], off offset:528

; #define GAS __attribute__((address_space(1)))
; __device__ __forceinline__ unsigned cvt_pk_bf16(float lo, float hi) { f32x2 v = {lo, hi}; bf16x2_t b = __builtin_convertvector(v, bf16x2_t); return __builtin_bit_cast(unsigned, b); }
; __device__ __forceinline__ float bf_lo(unsigned u) { return __uint_as_float(u << 16); }
; __device__ __forceinline__ float bf_hi(unsigned u) { return __uint_as_float(u & 0xffff0000u); }
;     __device__ __forceinline__ void operator()(const f32x4 (&acc)[2][2][4][2], const Unit& u, int wr, int wc, int fr, int fq) const {
;     ...
;             for (int m = 0; m < 4; ++m) { const int row = row0 + ai * HALF + m * 16; const size_t off = (size_t)row * 1024 + col0; float q = 0.f;
; #pragma unroll
;                 for (int bj = 0; bj < 2; ++bj) { const u32x4 xo = *(const GAS u32x4*)(xb + off + bj * HALF);
;                     f32x4 v0 = acc[ai][bj][m][0], v1 = acc[ai][bj][m][1];
;                     v0[0] += bf_lo(xo.x); v0[1] += bf_hi(xo.x); v0[2] += bf_lo(xo.y); v0[3] += bf_hi(xo.y); v1[0] += bf_lo(xo.z); v1[1] += bf_hi(xo.z); v1[2] += bf_lo(xo.w); v1[3] += bf_hi(xo.w);
;                     if (out) { *(GAS f32x4*)(out + off + bj * HALF) = v0; *(GAS f32x4*)(out + off + bj * HALF + 4) = v1; }
;                     u32x4 w; w.x = cvt_pk_bf16(v0[0], v0[1]); w.y = cvt_pk_bf16(v0[2], v0[3]); w.z = cvt_pk_bf16(v1[0], v1[1]); w.w = cvt_pk_bf16(v1[2], v1[3]);
;                     *(GAS u32x4*)(xb + off + bj * HALF) = w;
;                     q += ((v0[0] * v0[0] + v0[1] * v0[1]) + (v0[2] * v0[2] + v0[3] * v0[3])) + ((v1[0] * v1[0] + v1[1] * v1[1]) + (v1[2] * v1[2] + v1[3] * v1[3])); }
;                 q += __shfl_xor(q, 16); q += __shfl_xor(q, 32);
;                 if (fq == 0) rowss[(size_t)row * 16 + u.pn * 4 + wc] = q; }
.LBB0_860:
	s_or_b64 exec, exec, s[24:25]
	v_or_b32_e32 v82, 48, v142
	s_waitcnt lgkmcnt(0)
	v_ashrrev_i32_e32 v83, 31, v82
	v_lshlrev_b64 v[84:85], 10, v[82:83]
	v_lshl_add_u64 v[90:91], v[84:85], 0, v[140:141]
	v_lshl_add_u64 v[84:85], v[90:91], 1, s[12:13]
	s_and_b64 vcc, exec, s[10:11]
	s_nop 1
	v_mov_b32_e32 v86, v216
	v_mov_b32_e32 v87, v217
	v_mov_b32_e32 v88, v218
	v_mov_b32_e32 v89, v219
	v_lshlrev_b32_e32 v92, 16, v86
	v_and_b32_e32 v93, 0xffff0000, v86
	v_lshlrev_b32_e32 v86, 16, v87
	v_and_b32_e32 v87, 0xffff0000, v87
	v_pk_add_f32 v[80:81], v[80:81], v[86:87]
	v_lshlrev_b32_e32 v86, 16, v88
	v_and_b32_e32 v87, 0xffff0000, v88
	v_pk_add_f32 v[74:75], v[74:75], v[86:87]
	v_lshlrev_b32_e32 v86, 16, v89
	v_and_b32_e32 v87, 0xffff0000, v89
	v_pk_add_f32 v[78:79], v[78:79], v[92:93]
	v_pk_add_f32 v[76:77], v[76:77], v[86:87]
	v_lshl_add_u64 v[86:87], v[90:91], 2, s[2:3]
	s_cbranch_vccnz .LBB0_862
	global_store_dwordx4 v[86:87], v[78:81], off
	global_store_dwordx4 v[86:87], v[74:77], off offset:16
.LBB0_862:
	v_cvt_pk_bf16_f32 v88, v78, v79
	v_cvt_pk_bf16_f32 v89, v80, v81
	v_cvt_pk_bf16_f32 v90, v74, v75
	v_cvt_pk_bf16_f32 v91, v76, v77
	global_store_dwordx4 v[84:85], v[88:91], off
	s_and_b64 vcc, exec, s[10:11]
	s_nop 1
	v_mov_b32_e32 v88, v220
	v_mov_b32_e32 v89, v221
	v_mov_b32_e32 v90, v222
	v_mov_b32_e32 v91, v223
	v_lshlrev_b32_e32 v92, 16, v88
	v_and_b32_e32 v93, 0xffff0000, v88
	v_lshlrev_b32_e32 v88, 16, v89
	v_and_b32_e32 v89, 0xffff0000, v89
	v_pk_add_f32 v[72:73], v[72:73], v[88:89]
	v_lshlrev_b32_e32 v88, 16, v90
	v_and_b32_e32 v89, 0xffff0000, v90
	v_pk_add_f32 v[66:67], v[66:67], v[88:89]
	v_lshlrev_b32_e32 v88, 16, v91
	v_and_b32_e32 v89, 0xffff0000, v91
	v_pk_add_f32 v[70:71], v[70:71], v[92:93]
	v_pk_add_f32 v[68:69], v[68:69], v[88:89]
	s_cbranch_vccnz .LBB0_864
	global_store_dwordx4 v[86:87], v[70:73], off offset:512
	global_store_dwordx4 v[86:87], v[66:69], off offset:528

; #define GAS __attribute__((address_space(1)))
; __device__ __forceinline__ unsigned cvt_pk_bf16(float lo, float hi) { f32x2 v = {lo, hi}; bf16x2_t b = __builtin_convertvector(v, bf16x2_t); return __builtin_bit_cast(unsigned, b); }
; __device__ __forceinline__ float bf_lo(unsigned u) { return __uint_as_float(u << 16); }
; __device__ __forceinline__ float bf_hi(unsigned u) { return __uint_as_float(u & 0xffff0000u); }
;     __device__ __forceinline__ void operator()(const f32x4 (&acc)[2][2][4][2], const Unit& u, int wr, int wc, int fr, int fq) const {
;     ...
;             for (int m = 0; m < 4; ++m) { const int row = row0 + ai * HALF + m * 16; const size_t off = (size_t)row * 1024 + col0; float q = 0.f;
; #pragma unroll
;                 for (int bj = 0; bj < 2; ++bj) { const u32x4 xo = *(const GAS u32x4*)(xb + off + bj * HALF);
;                     f32x4 v0 = acc[ai][bj][m][0], v1 = acc[ai][bj][m][1];
;                     v0[0] += bf_lo(xo.x); v0[1] += bf_hi(xo.x); v0[2] += bf_lo(xo.y); v0[3] += bf_hi(xo.y); v1[0] += bf_lo(xo.z); v1[1] += bf_hi(xo.z); v1[2] += bf_lo(xo.w); v1[3] += bf_hi(xo.w);
;                     if (out) { *(GAS f32x4*)(out + off + bj * HALF) = v0; *(GAS f32x4*)(out + off + bj * HALF + 4) = v1; }
;                     u32x4 w; w.x = cvt_pk_bf16(v0[0], v0[1]); w.y = cvt_pk_bf16(v0[2], v0[3]); w.z = cvt_pk_bf16(v1[0], v1[1]); w.w = cvt_pk_bf16(v1[2], v1[3]);
;                     *(GAS u32x4*)(xb + off + bj * HALF) = w;
;                     q += ((v0[0] * v0[0] + v0[1] * v0[1]) + (v0[2] * v0[2] + v0[3] * v0[3])) + ((v1[0] * v1[0] + v1[1] * v1[1]) + (v1[2] * v1[2] + v1[3] * v1[3])); }
;                 q += __shfl_xor(q, 16); q += __shfl_xor(q, 32);
;                 if (fq == 0) rowss[(size_t)row * 16 + u.pn * 4 + wc] = q; }
.LBB0_866:
	s_or_b64 exec, exec, s[24:25]
	v_add_u32_e32 v66, 0x80, v142
	s_waitcnt lgkmcnt(0)
	v_ashrrev_i32_e32 v67, 31, v66
	v_lshlrev_b64 v[68:69], 10, v[66:67]
	v_lshl_add_u64 v[74:75], v[68:69], 0, v[140:141]
	v_lshl_add_u64 v[68:69], v[74:75], 1, s[12:13]
	s_and_b64 vcc, exec, s[10:11]
	v_add_u32_e32 v225, 0x40000, v224
	global_load_dwordx4 v[192:195], v225, s[12:13]
	global_load_dwordx4 v[196:199], v225, s[12:13] offset:256
	v_add_u32_e32 v225, 0x48000, v224
	global_load_dwordx4 v[200:203], v225, s[12:13]
	global_load_dwordx4 v[204:207], v225, s[12:13] offset:256
	v_add_u32_e32 v225, 0x50000, v224
	global_load_dwordx4 v[208:211], v225, s[12:13]
	global_load_dwordx4 v[212:215], v225, s[12:13] offset:256
	v_add_u32_e32 v225, 0x58000, v224
	global_load_dwordx4 v[216:219], v225, s[12:13]
	global_load_dwordx4 v[220:223], v225, s[12:13] offset:256
	s_waitcnt vmcnt(0)
	s_nop 1
	v_mov_b32_e32 v70, v192
	v_mov_b32_e32 v71, v193
	v_mov_b32_e32 v72, v194
	v_mov_b32_e32 v73, v195
	v_lshlrev_b32_e32 v76, 16, v70
	v_and_b32_e32 v77, 0xffff0000, v70
	v_lshlrev_b32_e32 v70, 16, v71
	v_and_b32_e32 v71, 0xffff0000, v71
	v_pk_add_f32 v[64:65], v[64:65], v[70:71]
	v_lshlrev_b32_e32 v70, 16, v72
	v_and_b32_e32 v71, 0xffff0000, v72
	v_pk_add_f32 v[58:59], v[58:59], v[70:71]
	v_lshlrev_b32_e32 v70, 16, v73
	v_and_b32_e32 v71, 0xffff0000, v73
	v_pk_add_f32 v[62:63], v[62:63], v[76:77]
	v_pk_add_f32 v[60:61], v[60:61], v[70:71]
	v_lshl_add_u64 v[70:71], v[74:75], 2, s[2:3]
	s_cbranch_vccnz .LBB0_868
	global_store_dwordx4 v[70:71], v[62:65], off
	global_store_dwordx4 v[70:71], v[58:61], off offset:16
.LBB0_868:
	v_cvt_pk_bf16_f32 v72, v62, v63
	v_cvt_pk_bf16_f32 v73, v64, v65
	v_cvt_pk_bf16_f32 v74, v58, v59
	v_cvt_pk_bf16_f32 v75, v60, v61
	global_store_dwordx4 v[68:69], v[72:75], off
	s_and_b64 vcc, exec, s[10:11]
	s_nop 1
	v_mov_b32_e32 v72, v196
	v_mov_b32_e32 v73, v197
	v_mov_b32_e32 v74, v198
	v_mov_b32_e32 v75, v199
	v_lshlrev_b32_e32 v76, 16, v72
	v_and_b32_e32 v77, 0xffff0000, v72
	v_lshlrev_b32_e32 v72, 16, v73
	v_and_b32_e32 v73, 0xffff0000, v73
	v_pk_add_f32 v[56:57], v[56:57], v[72:73]
	v_lshlrev_b32_e32 v72, 16, v74
	v_and_b32_e32 v73, 0xffff0000, v74
	v_pk_add_f32 v[50:51], v[50:51], v[72:73]
	v_lshlrev_b32_e32 v72, 16, v75
	v_and_b32_e32 v73, 0xffff0000, v75
	v_pk_add_f32 v[54:55], v[54:55], v[76:77]
	v_pk_add_f32 v[52:53], v[52:53], v[72:73]
	s_cbranch_vccnz .LBB0_870
	global_store_dwordx4 v[70:71], v[54:57], off offset:512
	global_store_dwordx4 v[70:71], v[50:53], off offset:528

; #define GAS __attribute__((address_space(1)))
; __device__ __forceinline__ unsigned cvt_pk_bf16(float lo, float hi) { f32x2 v = {lo, hi}; bf16x2_t b = __builtin_convertvector(v, bf16x2_t); return __builtin_bit_cast(unsigned, b); }
; __device__ __forceinline__ float bf_lo(unsigned u) { return __uint_as_float(u << 16); }
; __device__ __forceinline__ float bf_hi(unsigned u) { return __uint_as_float(u & 0xffff0000u); }
;     __device__ __forceinline__ void operator()(const f32x4 (&acc)[2][2][4][2], const Unit& u, int wr, int wc, int fr, int fq) const {
;     ...
;             for (int m = 0; m < 4; ++m) { const int row = row0 + ai * HALF + m * 16; const size_t off = (size_t)row * 1024 + col0; float q = 0.f;
; #pragma unroll
;                 for (int bj = 0; bj < 2; ++bj) { const u32x4 xo = *(const GAS u32x4*)(xb + off + bj * HALF);
;                     f32x4 v0 = acc[ai][bj][m][0], v1 = acc[ai][bj][m][1];
;                     v0[0] += bf_lo(xo.x); v0[1] += bf_hi(xo.x); v0[2] += bf_lo(xo.y); v0[3] += bf_hi(xo.y); v1[0] += bf_lo(xo.z); v1[1] += bf_hi(xo.z); v1[2] += bf_lo(xo.w); v1[3] += bf_hi(xo.w);
;                     if (out) { *(GAS f32x4*)(out + off + bj * HALF) = v0; *(GAS f32x4*)(out + off + bj * HALF + 4) = v1; }
;                     u32x4 w; w.x = cvt_pk_bf16(v0[0], v0[1]); w.y = cvt_pk_bf16(v0[2], v0[3]); w.z = cvt_pk_bf16(v1[0], v1[1]); w.w = cvt_pk_bf16(v1[2], v1[3]);
;                     *(GAS u32x4*)(xb + off + bj * HALF) = w;
;                     q += ((v0[0] * v0[0] + v0[1] * v0[1]) + (v0[2] * v0[2] + v0[3] * v0[3])) + ((v1[0] * v1[0] + v1[1] * v1[1]) + (v1[2] * v1[2] + v1[3] * v1[3])); }
;                 q += __shfl_xor(q, 16); q += __shfl_xor(q, 32);
;                 if (fq == 0) rowss[(size_t)row * 16 + u.pn * 4 + wc] = q; }
.LBB0_872:
	s_or_b64 exec, exec, s[24:25]
	v_add_u32_e32 v50, 0x90, v142
	s_waitcnt lgkmcnt(0)
	v_ashrrev_i32_e32 v51, 31, v50
	v_lshlrev_b64 v[52:53], 10, v[50:51]
	v_lshl_add_u64 v[58:59], v[52:53], 0, v[140:141]
	v_lshl_add_u64 v[52:53], v[58:59], 1, s[12:13]
	s_and_b64 vcc, exec, s[10:11]
	s_nop 1
	v_mov_b32_e32 v54, v200
	v_mov_b32_e32 v55, v201
	v_mov_b32_e32 v56, v202
	v_mov_b32_e32 v57, v203
	v_lshlrev_b32_e32 v60, 16, v54
	v_and_b32_e32 v61, 0xffff0000, v54
	v_lshlrev_b32_e32 v54, 16, v55
	v_and_b32_e32 v55, 0xffff0000, v55
	v_pk_add_f32 v[48:49], v[48:49], v[54:55]
	v_lshlrev_b32_e32 v54, 16, v56
	v_and_b32_e32 v55, 0xffff0000, v56
	v_pk_add_f32 v[42:43], v[42:43], v[54:55]
	v_lshlrev_b32_e32 v54, 16, v57
	v_and_b32_e32 v55, 0xffff0000, v57
	v_pk_add_f32 v[46:47], v[46:47], v[60:61]
	v_pk_add_f32 v[44:45], v[44:45], v[54:55]
	v_lshl_add_u64 v[54:55], v[58:59], 2, s[2:3]
	s_cbranch_vccnz .LBB0_874
	global_store_dwordx4 v[54:55], v[46:49], off
	global_store_dwordx4 v[54:55], v[42:45], off offset:16
.LBB0_874:
	v_cvt_pk_bf16_f32 v56, v46, v47
	v_cvt_pk_bf16_f32 v57, v48, v49
	v_cvt_pk_bf16_f32 v58, v42, v43
	v_cvt_pk_bf16_f32 v59, v44, v45
	global_store_dwordx4 v[52:53], v[56:59], off
	s_and_b64 vcc, exec, s[10:11]
	s_nop 1
	v_mov_b32_e32 v56, v204
	v_mov_b32_e32 v57, v205
	v_mov_b32_e32 v58, v206
	v_mov_b32_e32 v59, v207
	v_lshlrev_b32_e32 v60, 16, v56
	v_and_b32_e32 v61, 0xffff0000, v56
	v_lshlrev_b32_e32 v56, 16, v57
	v_and_b32_e32 v57, 0xffff0000, v57
	v_pk_add_f32 v[40:41], v[40:41], v[56:57]
	v_lshlrev_b32_e32 v56, 16, v58
	v_and_b32_e32 v57, 0xffff0000, v58
	v_pk_add_f32 v[34:35], v[34:35], v[56:57]
	v_lshlrev_b32_e32 v56, 16, v59
	v_and_b32_e32 v57, 0xffff0000, v59
	v_pk_add_f32 v[38:39], v[38:39], v[60:61]
	v_pk_add_f32 v[36:37], v[36:37], v[56:57]
	s_cbranch_vccnz .LBB0_876
	global_store_dwordx4 v[54:55], v[38:41], off offset:512
	global_store_dwordx4 v[54:55], v[34:37], off offset:528

; #define GAS __attribute__((address_space(1)))
; __device__ __forceinline__ unsigned cvt_pk_bf16(float lo, float hi) { f32x2 v = {lo, hi}; bf16x2_t b = __builtin_convertvector(v, bf16x2_t); return __builtin_bit_cast(unsigned, b); }
; __device__ __forceinline__ float bf_lo(unsigned u) { return __uint_as_float(u << 16); }
; __device__ __forceinline__ float bf_hi(unsigned u) { return __uint_as_float(u & 0xffff0000u); }
;     __device__ __forceinline__ void operator()(const f32x4 (&acc)[2][2][4][2], const Unit& u, int wr, int wc, int fr, int fq) const {
;     ...
;             for (int m = 0; m < 4; ++m) { const int row = row0 + ai * HALF + m * 16; const size_t off = (size_t)row * 1024 + col0; float q = 0.f;
; #pragma unroll
;                 for (int bj = 0; bj < 2; ++bj) { const u32x4 xo = *(const GAS u32x4*)(xb + off + bj * HALF);
;                     f32x4 v0 = acc[ai][bj][m][0], v1 = acc[ai][bj][m][1];
;                     v0[0] += bf_lo(xo.x); v0[1] += bf_hi(xo.x); v0[2] += bf_lo(xo.y); v0[3] += bf_hi(xo.y); v1[0] += bf_lo(xo.z); v1[1] += bf_hi(xo.z); v1[2] += bf_lo(xo.w); v1[3] += bf_hi(xo.w);
;                     if (out) { *(GAS f32x4*)(out + off + bj * HALF) = v0; *(GAS f32x4*)(out + off + bj * HALF + 4) = v1; }
;                     u32x4 w; w.x = cvt_pk_bf16(v0[0], v0[1]); w.y = cvt_pk_bf16(v0[2], v0[3]); w.z = cvt_pk_bf16(v1[0], v1[1]); w.w = cvt_pk_bf16(v1[2], v1[3]);
;                     *(GAS u32x4*)(xb + off + bj * HALF) = w;
;                     q += ((v0[0] * v0[0] + v0[1] * v0[1]) + (v0[2] * v0[2] + v0[3] * v0[3])) + ((v1[0] * v1[0] + v1[1] * v1[1]) + (v1[2] * v1[2] + v1[3] * v1[3])); }
;                 q += __shfl_xor(q, 16); q += __shfl_xor(q, 32);
;                 if (fq == 0) rowss[(size_t)row * 16 + u.pn * 4 + wc] = q; }
.LBB0_878:
	s_or_b64 exec, exec, s[24:25]
	v_add_u32_e32 v34, 0xa0, v142
	s_waitcnt lgkmcnt(0)
	v_ashrrev_i32_e32 v35, 31, v34
	v_lshlrev_b64 v[36:37], 10, v[34:35]
	v_lshl_add_u64 v[42:43], v[36:37], 0, v[140:141]
	v_lshl_add_u64 v[36:37], v[42:43], 1, s[12:13]
	s_and_b64 vcc, exec, s[10:11]
	s_nop 1
	v_mov_b32_e32 v38, v208
	v_mov_b32_e32 v39, v209
	v_mov_b32_e32 v40, v210
	v_mov_b32_e32 v41, v211
	v_lshlrev_b32_e32 v44, 16, v38
	v_and_b32_e32 v45, 0xffff0000, v38
	v_lshlrev_b32_e32 v38, 16, v39
	v_and_b32_e32 v39, 0xffff0000, v39
	v_pk_add_f32 v[32:33], v[32:33], v[38:39]
	v_lshlrev_b32_e32 v38, 16, v40
	v_and_b32_e32 v39, 0xffff0000, v40
	v_pk_add_f32 v[26:27], v[26:27], v[38:39]
	v_lshlrev_b32_e32 v38, 16, v41
	v_and_b32_e32 v39, 0xffff0000, v41
	v_pk_add_f32 v[30:31], v[30:31], v[44:45]
	v_pk_add_f32 v[28:29], v[28:29], v[38:39]
	v_lshl_add_u64 v[38:39], v[42:43], 2, s[2:3]
	s_cbranch_vccnz .LBB0_880
	global_store_dwordx4 v[38:39], v[30:33], off
	global_store_dwordx4 v[38:39], v[26:29], off offset:16
.LBB0_880:
	v_cvt_pk_bf16_f32 v40, v30, v31
	v_cvt_pk_bf16_f32 v41, v32, v33
	v_cvt_pk_bf16_f32 v42, v26, v27
	v_cvt_pk_bf16_f32 v43, v28, v29
	global_store_dwordx4 v[36:37], v[40:43], off
	s_and_b64 vcc, exec, s[10:11]
	s_nop 1
	v_mov_b32_e32 v40, v212
	v_mov_b32_e32 v41, v213
	v_mov_b32_e32 v42, v214
	v_mov_b32_e32 v43, v215
	v_lshlrev_b32_e32 v44, 16, v40
	v_and_b32_e32 v45, 0xffff0000, v40
	v_lshlrev_b32_e32 v40, 16, v41
	v_and_b32_e32 v41, 0xffff0000, v41
	v_pk_add_f32 v[24:25], v[24:25], v[40:41]
	v_lshlrev_b32_e32 v40, 16, v42
	v_and_b32_e32 v41, 0xffff0000, v42
	v_pk_add_f32 v[18:19], v[18:19], v[40:41]
	v_lshlrev_b32_e32 v40, 16, v43
	v_and_b32_e32 v41, 0xffff0000, v43
	v_pk_add_f32 v[22:23], v[22:23], v[44:45]
	v_pk_add_f32 v[20:21], v[20:21], v[40:41]
	s_cbranch_vccnz .LBB0_882
	global_store_dwordx4 v[38:39], v[22:25], off offset:512
	global_store_dwordx4 v[38:39], v[18:21], off offset:528

; #define GAS __attribute__((address_space(1)))
; __device__ __forceinline__ unsigned cvt_pk_bf16(float lo, float hi) { f32x2 v = {lo, hi}; bf16x2_t b = __builtin_convertvector(v, bf16x2_t); return __builtin_bit_cast(unsigned, b); }
; __device__ __forceinline__ float bf_lo(unsigned u) { return __uint_as_float(u << 16); }
; __device__ __forceinline__ float bf_hi(unsigned u) { return __uint_as_float(u & 0xffff0000u); }
;     __device__ __forceinline__ void operator()(const f32x4 (&acc)[2][2][4][2], const Unit& u, int wr, int wc, int fr, int fq) const {
;     ...
;             for (int m = 0; m < 4; ++m) { const int row = row0 + ai * HALF + m * 16; const size_t off = (size_t)row * 1024 + col0; float q = 0.f;
; #pragma unroll
;                 for (int bj = 0; bj < 2; ++bj) { const u32x4 xo = *(const GAS u32x4*)(xb + off + bj * HALF);
;                     f32x4 v0 = acc[ai][bj][m][0], v1 = acc[ai][bj][m][1];
;                     v0[0] += bf_lo(xo.x); v0[1] += bf_hi(xo.x); v0[2] += bf_lo(xo.y); v0[3] += bf_hi(xo.y); v1[0] += bf_lo(xo.z); v1[1] += bf_hi(xo.z); v1[2] += bf_lo(xo.w); v1[3] += bf_hi(xo.w);
;                     if (out) { *(GAS f32x4*)(out + off + bj * HALF) = v0; *(GAS f32x4*)(out + off + bj * HALF + 4) = v1; }
;                     u32x4 w; w.x = cvt_pk_bf16(v0[0], v0[1]); w.y = cvt_pk_bf16(v0[2], v0[3]); w.z = cvt_pk_bf16(v1[0], v1[1]); w.w = cvt_pk_bf16(v1[2], v1[3]);
;                     *(GAS u32x4*)(xb + off + bj * HALF) = w;
;                     q += ((v0[0] * v0[0] + v0[1] * v0[1]) + (v0[2] * v0[2] + v0[3] * v0[3])) + ((v1[0] * v1[0] + v1[1] * v1[1]) + (v1[2] * v1[2] + v1[3] * v1[3])); }
;                 q += __shfl_xor(q, 16); q += __shfl_xor(q, 32);
;                 if (fq == 0) rowss[(size_t)row * 16 + u.pn * 4 + wc] = q; }
.LBB0_884:
	s_or_b64 exec, exec, s[24:25]
	v_add_u32_e32 v18, 0xb0, v142
	s_waitcnt lgkmcnt(0)
	v_ashrrev_i32_e32 v19, 31, v18
	v_lshlrev_b64 v[20:21], 10, v[18:19]
	v_lshl_add_u64 v[26:27], v[20:21], 0, v[140:141]
	v_lshl_add_u64 v[20:21], v[26:27], 1, s[12:13]
	s_and_b64 vcc, exec, s[10:11]
	s_nop 1
	v_mov_b32_e32 v22, v216
	v_mov_b32_e32 v23, v217
	v_mov_b32_e32 v24, v218
	v_mov_b32_e32 v25, v219
	v_lshlrev_b32_e32 v28, 16, v22
	v_and_b32_e32 v29, 0xffff0000, v22
	v_lshlrev_b32_e32 v22, 16, v23
	v_and_b32_e32 v23, 0xffff0000, v23
	v_pk_add_f32 v[16:17], v[16:17], v[22:23]
	v_lshlrev_b32_e32 v22, 16, v24
	v_and_b32_e32 v23, 0xffff0000, v24
	v_pk_add_f32 v[10:11], v[10:11], v[22:23]
	v_lshlrev_b32_e32 v22, 16, v25
	v_and_b32_e32 v23, 0xffff0000, v25
	v_pk_add_f32 v[14:15], v[14:15], v[28:29]
	v_pk_add_f32 v[12:13], v[12:13], v[22:23]
	v_lshl_add_u64 v[22:23], v[26:27], 2, s[2:3]
	s_cbranch_vccnz .LBB0_886
	global_store_dwordx4 v[22:23], v[14:17], off
	global_store_dwordx4 v[22:23], v[10:13], off offset:16
.LBB0_886:
	v_cvt_pk_bf16_f32 v24, v14, v15
	v_cvt_pk_bf16_f32 v25, v16, v17
	v_cvt_pk_bf16_f32 v26, v10, v11
	v_cvt_pk_bf16_f32 v27, v12, v13
	global_store_dwordx4 v[20:21], v[24:27], off
	s_and_b64 vcc, exec, s[10:11]
	s_nop 1
	v_mov_b32_e32 v24, v220
	v_mov_b32_e32 v25, v221
	v_mov_b32_e32 v26, v222
	v_mov_b32_e32 v27, v223
	v_lshlrev_b32_e32 v28, 16, v24
	v_and_b32_e32 v29, 0xffff0000, v24
	v_lshlrev_b32_e32 v24, 16, v25
	v_and_b32_e32 v25, 0xffff0000, v25
	v_pk_add_f32 v[8:9], v[8:9], v[24:25]
	v_lshlrev_b32_e32 v24, 16, v26
	v_and_b32_e32 v25, 0xffff0000, v26
	v_pk_add_f32 v[2:3], v[2:3], v[24:25]
	v_lshlrev_b32_e32 v24, 16, v27
	v_and_b32_e32 v25, 0xffff0000, v27
	v_pk_add_f32 v[6:7], v[6:7], v[28:29]
	v_pk_add_f32 v[4:5], v[4:5], v[24:25]
	s_cbranch_vccnz .LBB0_888
	global_store_dwordx4 v[22:23], v[6:9], off offset:512
	global_store_dwordx4 v[22:23], v[2:5], off offset:528
